# v15 + nontemporal f32 residual-stream stores in the residual epilogues
# speedup vs baseline: 1.0021x; 1.0004x over previous
;     static __device__ __forceinline__ void run(const f32x4 (&acc)[2][2][4][2], const Unit& u, int wr, int wc, int fr, int fq, const float* xin, float* xout, const float* gate, float gs, const float* lazy_ssq, const float* lazy_g, ...
;     ...
;             for (int m = 0; m < 4; ++m) { rl[ai][m] = LAZY ? __builtin_amdgcn_rsqf(lazy_ssq[row0 + ai * HALF + m * 16] * (1.0f / 1024.0f) + 1e-6f) : 1.0f; sq[ai][m] = 0.f; sqb[ai][m] = 0.f; }
; #pragma unroll
;         for (int bj = 0; bj < 2; ++bj) {
;             const unsigned col = col0 + bj * HALF;
;             f32x4 gv[2], lg[2], wv[2], w2[2];
; #pragma unroll
;             for (int n = 0; n < 2; ++n) {
;                 gv[n] = *(const f32x4*)(gate + (b * 9216u + col + 4 * n)) * gs;
;                 lg[n] = (f32x4){1.f, 1.f, 1.f, 1.f}; if (LAZY) lg[n] = *(const f32x4*)(lazy_g + col + 4 * n);
;                 wv[n] = (f32x4){0.f, 0.f, 0.f, 0.f}; w2[n] = (f32x4){1.f, 1.f, 1.f, 1.f};
;                 if (aout) { wv[n] = *(const f32x4*)(wg + col + 4 * n) * (*(const f32x4*)(wsc + (b * 9216u + col + 4 * n)) + 1.0f); if (WG2) { w2[n] = *(const f32x4*)(wg2 + col + 4 * n); wv[n] = wv[n] * w2[n]; } }
;             }
;             f32x4 xq[2][2][2];
;     ...
;             constexpr bool DEEP = !LAZY && !WG2;
;             if (DEEP) RES_LD(0, 0);
; #pragma unroll
;             for (int pp = 0; pp < 4; ++pp) {
;                 if (DEEP) { if (pp < 3) RES_LD((pp + 1) & 1, pp + 1); } else RES_LD(pp & 1, pp);
; #pragma unroll
;                 for (int j = 0; j < 2; ++j) { const int i_ = 2 * pp + j, ai = i_ >> 2, m = i_ & 3; const unsigned off = (row0 + ai * HALF + m * 16) * 1024u + col;
;                     const f32x4 xi0 = xq[pp & 1][j][0], xi1 = xq[pp & 1][j][1];
;                     f32x4 xo0 = gv[0] * acc[ai][bj][m][0], xo1 = gv[1] * acc[ai][bj][m][1];
;                     if (LAZY) { xo0 = xo0 + xi0 * lg[0] * rl[ai][m]; xo1 = xo1 + xi1 * lg[1] * rl[ai][m]; } else { xo0 = xo0 + xi0; xo1 = xo1 + xi1; }
;                     *(f32x4*)(xout + off) = xo0; *(f32x4*)(xout + off + 4) = xo1;
;                     if (aout) { const f32x4 a0 = xo0 * wv[0], a1 = xo1 * wv[1]; u32x4 w; w.x = cvt_pk_bf16(a0[0], a0[1]); w.y = cvt_pk_bf16(a0[2], a0[3]); w.z = cvt_pk_bf16(a1[0], a1[1]); w.w = cvt_pk_bf16(a1[2], a1[3]);
;                         *(u32x4*)(aout + off) = w;
.LBB0_319:
	v_lshlrev_b32_e32 v175, 10, v172
	v_add_u32_e32 v176, v184, v175
	v_lshlrev_b64 v[208:209], 2, v[176:177]
	s_waitcnt vmcnt(0)
	v_pk_mul_f32 v[204:205], s[36:37], v[136:137] op_sel_hi:[0,1]
	v_lshl_add_u64 v[136:137], s[34:35], 0, v[208:209]
	v_pk_mul_f32 v[200:201], s[36:37], v[140:141] op_sel_hi:[0,1]
	v_fmamk_f32 v140, v146, 0x3a800000, v222
	global_load_dwordx4 v[148:151], v[136:137], off offset:16
	global_load_dwordx4 v[144:147], v[136:137], off
	v_add_u32_e32 v190, 0x4000, v176
	v_mov_b32_e32 v191, v177
	v_rsq_f32_e32 v174, v140
	v_lshl_add_u64 v[140:141], v[190:191], 2, s[34:35]
	v_pk_mul_f32 v[198:199], s[36:37], v[142:143] op_sel_hi:[0,1]
	v_pk_mul_f32 v[202:203], s[36:37], v[138:139] op_sel_hi:[0,1]
	global_load_dwordx4 v[136:139], v[140:141], off offset:16
	s_nop 0
	global_load_dwordx4 v[140:143], v[140:141], off
	v_lshl_add_u64 v[208:209], s[30:31], 0, v[208:209]
	v_mov_b32_e32 v231, 0
	s_and_b64 vcc, exec, s[8:9]
	v_mov_b32_e32 v232, 0
	s_waitcnt vmcnt(3)
	v_pk_mul_f32 v[150:151], v[134:135], v[150:151]
	s_waitcnt vmcnt(2)
	v_pk_mul_f32 v[146:147], v[130:131], v[146:147]
	v_pk_mul_f32 v[144:145], v[128:129], v[144:145]
	v_pk_mul_f32 v[148:149], v[132:133], v[148:149]
	v_pk_mul_f32 v[146:147], v[174:175], v[146:147] op_sel_hi:[0,1]
	v_pk_mul_f32 v[144:145], v[174:175], v[144:145] op_sel_hi:[0,1]
	v_pk_mul_f32 v[150:151], v[174:175], v[150:151] op_sel_hi:[0,1]
	v_pk_mul_f32 v[148:149], v[174:175], v[148:149] op_sel_hi:[0,1]
	v_pk_fma_f32 v[144:145], v[124:125], v[204:205], v[144:145]
	v_pk_fma_f32 v[146:147], v[126:127], v[202:203], v[146:147]
	v_pk_fma_f32 v[148:149], v[120:121], v[200:201], v[148:149]
	v_pk_fma_f32 v[150:151], v[122:123], v[198:199], v[150:151]
	global_store_dwordx4 v[208:209], v[144:147], off nt
	global_store_dwordx4 v[208:209], v[148:151], off offset:16 nt
	s_cbranch_vccnz .LBB0_321
	v_pk_mul_f32 v[208:209], v[188:189], v[146:147]
	v_pk_mul_f32 v[214:215], v[186:187], v[144:145]
	v_pk_mul_f32 v[234:235], v[192:193], v[148:149]
	v_cvt_pk_bf16_f32 v232, v214, v215
	v_cvt_pk_bf16_f32 v233, v208, v209
	v_lshl_add_u64 v[208:209], v[176:177], 1, s[28:29]
	v_pk_mul_f32 v[236:237], v[194:195], v[150:151]
	v_cvt_pk_bf16_f32 v234, v234, v235
	s_nop 0
	v_cvt_pk_bf16_f32 v235, v236, v237
	global_store_dwordx4 v[208:209], v[232:235], off
	v_mov_b32_e32 v209, v148
	v_mov_b32_e32 v148, v145
	v_mov_b32_e32 v208, v144
	v_pk_mul_f32 v[144:145], v[148:149], v[148:149]
	v_mov_b32_e32 v149, v150
	v_mov_b32_e32 v150, v147
	v_mov_b32_e32 v148, v146
	v_pk_mul_f32 v[146:147], v[150:151], v[150:151]
	v_pk_fma_f32 v[144:145], v[208:209], v[208:209], v[144:145]
	v_pk_fma_f32 v[146:147], v[148:149], v[148:149], v[146:147]
	s_nop 0
	v_pk_add_f32 v[144:145], v[144:145], v[146:147]
	s_nop 0
	v_add_f32_e32 v232, v144, v145
.LBB0_321:
	v_fmamk_f32 v144, v196, 0x3a800000, v222
	v_rsq_f32_e32 v196, v144
	s_waitcnt vmcnt(2)
	v_pk_mul_f32 v[142:143], v[130:131], v[142:143]
	v_pk_mul_f32 v[140:141], v[128:129], v[140:141]
	v_pk_mul_f32 v[138:139], v[134:135], v[138:139]
	v_pk_mul_f32 v[136:137], v[132:133], v[136:137]
	v_pk_mul_f32 v[142:143], v[196:197], v[142:143] op_sel_hi:[0,1]
	v_pk_mul_f32 v[140:141], v[196:197], v[140:141] op_sel_hi:[0,1]
	v_pk_mul_f32 v[138:139], v[196:197], v[138:139] op_sel_hi:[0,1]
	v_pk_mul_f32 v[136:137], v[196:197], v[136:137] op_sel_hi:[0,1]
	v_pk_fma_f32 v[142:143], v[110:111], v[202:203], v[142:143]
	v_pk_fma_f32 v[140:141], v[108:109], v[204:205], v[140:141]
	v_pk_fma_f32 v[138:139], v[106:107], v[198:199], v[138:139]
	v_pk_fma_f32 v[136:137], v[104:105], v[200:201], v[136:137]
	v_lshl_add_u64 v[144:145], v[190:191], 2, s[30:31]
	s_and_b64 vcc, exec, s[8:9]
	global_store_dwordx4 v[144:145], v[140:143], off nt
	global_store_dwordx4 v[144:145], v[136:139], off offset:16 nt
	s_cbranch_vccnz .LBB0_323
	v_pk_mul_f32 v[146:147], v[188:189], v[142:143]
	v_pk_mul_f32 v[144:145], v[186:187], v[140:141]
	v_pk_mul_f32 v[148:149], v[194:195], v[138:139]
	v_pk_mul_f32 v[150:151], v[192:193], v[136:137]
	v_cvt_pk_bf16_f32 v144, v144, v145
	v_cvt_pk_bf16_f32 v145, v146, v147
	s_nop 0
	v_cvt_pk_bf16_f32 v146, v150, v151
	v_cvt_pk_bf16_f32 v147, v148, v149
	v_lshl_add_u64 v[148:149], v[190:191], 1, s[28:29]
	global_store_dwordx4 v[148:149], v[144:147], off
	s_nop 1
	v_mov_b32_e32 v145, v136
	v_mov_b32_e32 v136, v141
	v_mov_b32_e32 v141, v138
	v_mov_b32_e32 v138, v143
	v_mov_b32_e32 v144, v140
	v_pk_mul_f32 v[136:137], v[136:137], v[136:137]
	v_mov_b32_e32 v140, v142
	v_pk_mul_f32 v[138:139], v[138:139], v[138:139]
	v_pk_fma_f32 v[136:137], v[144:145], v[144:145], v[136:137]
	v_pk_fma_f32 v[138:139], v[140:141], v[140:141], v[138:139]
	s_nop 0
	v_pk_add_f32 v[136:137], v[136:137], v[138:139]
	s_nop 0
	v_add_f32_e32 v231, v136, v137
;     static __device__ __forceinline__ void run(const f32x4 (&acc)[2][2][4][2], const Unit& u, int wr, int wc, int fr, int fq, const float* xin, float* xout, const float* gate, float gs, const float* lazy_ssq, const float* lazy_g, ...
;     ...
;             for (int m = 0; m < 4; ++m) { rl[ai][m] = LAZY ? __builtin_amdgcn_rsqf(lazy_ssq[row0 + ai * HALF + m * 16] * (1.0f / 1024.0f) + 1e-6f) : 1.0f; sq[ai][m] = 0.f; sqb[ai][m] = 0.f; }
; #pragma unroll
;         for (int bj = 0; bj < 2; ++bj) {
;             const unsigned col = col0 + bj * HALF;
;             f32x4 gv[2], lg[2], wv[2], w2[2];
; #pragma unroll
;             for (int n = 0; n < 2; ++n) {
;                 gv[n] = *(const f32x4*)(gate + (b * 9216u + col + 4 * n)) * gs;
;                 lg[n] = (f32x4){1.f, 1.f, 1.f, 1.f}; if (LAZY) lg[n] = *(const f32x4*)(lazy_g + col + 4 * n);
;                 wv[n] = (f32x4){0.f, 0.f, 0.f, 0.f}; w2[n] = (f32x4){1.f, 1.f, 1.f, 1.f};
;                 if (aout) { wv[n] = *(const f32x4*)(wg + col + 4 * n) * (*(const f32x4*)(wsc + (b * 9216u + col + 4 * n)) + 1.0f); if (WG2) { w2[n] = *(const f32x4*)(wg2 + col + 4 * n); wv[n] = wv[n] * w2[n]; } }
;             }
;             f32x4 xq[2][2][2];
;     ...
;             constexpr bool DEEP = !LAZY && !WG2;
;             if (DEEP) RES_LD(0, 0);
; #pragma unroll
;             for (int pp = 0; pp < 4; ++pp) {
;                 if (DEEP) { if (pp < 3) RES_LD((pp + 1) & 1, pp + 1); } else RES_LD(pp & 1, pp);
; #pragma unroll
;                 for (int j = 0; j < 2; ++j) { const int i_ = 2 * pp + j, ai = i_ >> 2, m = i_ & 3; const unsigned off = (row0 + ai * HALF + m * 16) * 1024u + col;
;                     const f32x4 xi0 = xq[pp & 1][j][0], xi1 = xq[pp & 1][j][1];
;                     f32x4 xo0 = gv[0] * acc[ai][bj][m][0], xo1 = gv[1] * acc[ai][bj][m][1];
;                     if (LAZY) { xo0 = xo0 + xi0 * lg[0] * rl[ai][m]; xo1 = xo1 + xi1 * lg[1] * rl[ai][m]; } else { xo0 = xo0 + xi0; xo1 = xo1 + xi1; }
;                     *(f32x4*)(xout + off) = xo0; *(f32x4*)(xout + off + 4) = xo1;
;                     if (aout) { const f32x4 a0 = xo0 * wv[0], a1 = xo1 * wv[1]; u32x4 w; w.x = cvt_pk_bf16(a0[0], a0[1]); w.y = cvt_pk_bf16(a0[2], a0[3]); w.z = cvt_pk_bf16(a1[0], a1[1]); w.w = cvt_pk_bf16(a1[2], a1[3]);
;                         *(u32x4*)(aout + off) = w;
.LBB0_323:
	v_add_u32_e32 v208, 0x8000, v176
	v_mov_b32_e32 v209, v177
	v_fmamk_f32 v136, v206, 0x3a800000, v222
	v_lshlrev_b64 v[214:215], 2, v[208:209]
	v_rsq_f32_e32 v190, v136
	v_lshl_add_u64 v[136:137], s[34:35], 0, v[214:215]
	global_load_dwordx4 v[148:151], v[136:137], off offset:16
	global_load_dwordx4 v[144:147], v[136:137], off
	v_add_u32_e32 v206, 0xc000, v176
	v_mov_b32_e32 v207, v177
	v_lshl_add_u64 v[140:141], v[206:207], 2, s[34:35]
	global_load_dwordx4 v[136:139], v[140:141], off offset:16
	s_nop 0
	global_load_dwordx4 v[140:143], v[140:141], off
	v_lshl_add_u64 v[214:215], s[30:31], 0, v[214:215]
	v_mov_b32_e32 v233, 0
	s_and_b64 vcc, exec, s[8:9]
	v_mov_b32_e32 v234, 0
	s_waitcnt vmcnt(3)
	v_pk_mul_f32 v[150:151], v[134:135], v[150:151]
	s_waitcnt vmcnt(2)
	v_pk_mul_f32 v[146:147], v[130:131], v[146:147]
	v_pk_mul_f32 v[144:145], v[128:129], v[144:145]
	v_pk_mul_f32 v[148:149], v[132:133], v[148:149]
	v_pk_mul_f32 v[146:147], v[190:191], v[146:147] op_sel_hi:[0,1]
	v_pk_mul_f32 v[144:145], v[190:191], v[144:145] op_sel_hi:[0,1]
	v_pk_mul_f32 v[150:151], v[190:191], v[150:151] op_sel_hi:[0,1]
	v_pk_mul_f32 v[148:149], v[190:191], v[148:149] op_sel_hi:[0,1]
	v_pk_fma_f32 v[146:147], v[94:95], v[202:203], v[146:147]
	v_pk_fma_f32 v[144:145], v[92:93], v[204:205], v[144:145]
	v_pk_fma_f32 v[150:151], v[90:91], v[198:199], v[150:151]
	v_pk_fma_f32 v[148:149], v[88:89], v[200:201], v[148:149]
	global_store_dwordx4 v[214:215], v[144:147], off nt
	global_store_dwordx4 v[214:215], v[148:151], off offset:16 nt
	s_cbranch_vccnz .LBB0_325
	v_pk_mul_f32 v[234:235], v[186:187], v[144:145]
	v_pk_mul_f32 v[236:237], v[192:193], v[148:149]
	v_lshl_add_u64 v[208:209], v[208:209], 1, s[28:29]
	v_pk_mul_f32 v[214:215], v[188:189], v[146:147]
	v_pk_mul_f32 v[238:239], v[194:195], v[150:151]
	v_cvt_pk_bf16_f32 v234, v234, v235
	v_cvt_pk_bf16_f32 v235, v214, v215
	v_cvt_pk_bf16_f32 v236, v236, v237
	s_nop 0
	v_cvt_pk_bf16_f32 v237, v238, v239
	global_store_dwordx4 v[208:209], v[234:237], off
	v_mov_b32_e32 v209, v148
	v_mov_b32_e32 v148, v145
	v_mov_b32_e32 v208, v144
	v_pk_mul_f32 v[144:145], v[148:149], v[148:149]
	v_mov_b32_e32 v149, v150
	v_mov_b32_e32 v150, v147
	v_mov_b32_e32 v148, v146
	v_pk_mul_f32 v[146:147], v[150:151], v[150:151]
	v_pk_fma_f32 v[144:145], v[208:209], v[208:209], v[144:145]
	v_pk_fma_f32 v[146:147], v[148:149], v[148:149], v[146:147]
	s_nop 0
	v_pk_add_f32 v[144:145], v[144:145], v[146:147]
	s_nop 0
	v_add_f32_e32 v234, v144, v145
.LBB0_325:
	v_fmamk_f32 v144, v210, 0x3a800000, v222
	v_rsq_f32_e32 v210, v144
	s_waitcnt vmcnt(2)
	v_pk_mul_f32 v[142:143], v[130:131], v[142:143]
	v_pk_mul_f32 v[140:141], v[128:129], v[140:141]
	v_pk_mul_f32 v[138:139], v[134:135], v[138:139]
	v_pk_mul_f32 v[136:137], v[132:133], v[136:137]
	v_pk_mul_f32 v[142:143], v[210:211], v[142:143] op_sel_hi:[0,1]
	v_pk_mul_f32 v[140:141], v[210:211], v[140:141] op_sel_hi:[0,1]
	v_pk_mul_f32 v[138:139], v[210:211], v[138:139] op_sel_hi:[0,1]
	v_pk_mul_f32 v[136:137], v[210:211], v[136:137] op_sel_hi:[0,1]
	v_pk_fma_f32 v[142:143], v[78:79], v[202:203], v[142:143]
	v_pk_fma_f32 v[140:141], v[76:77], v[204:205], v[140:141]
	v_pk_fma_f32 v[138:139], v[74:75], v[198:199], v[138:139]
	v_pk_fma_f32 v[136:137], v[72:73], v[200:201], v[136:137]
	v_lshl_add_u64 v[144:145], v[206:207], 2, s[30:31]
	s_and_b64 vcc, exec, s[8:9]
	global_store_dwordx4 v[144:145], v[140:143], off nt
	global_store_dwordx4 v[144:145], v[136:139], off offset:16 nt
	s_cbranch_vccnz .LBB0_327
	v_pk_mul_f32 v[146:147], v[188:189], v[142:143]
	v_pk_mul_f32 v[144:145], v[186:187], v[140:141]
	v_pk_mul_f32 v[148:149], v[194:195], v[138:139]
	v_pk_mul_f32 v[150:151], v[192:193], v[136:137]
	v_cvt_pk_bf16_f32 v144, v144, v145
	v_cvt_pk_bf16_f32 v145, v146, v147
	s_nop 0
	v_cvt_pk_bf16_f32 v146, v150, v151
	v_cvt_pk_bf16_f32 v147, v148, v149
	v_lshl_add_u64 v[148:149], v[206:207], 1, s[28:29]
	global_store_dwordx4 v[148:149], v[144:147], off
	s_nop 1
	v_mov_b32_e32 v145, v136
	v_mov_b32_e32 v136, v141
	v_mov_b32_e32 v141, v138
	v_mov_b32_e32 v138, v143
	v_mov_b32_e32 v144, v140
	v_pk_mul_f32 v[136:137], v[136:137], v[136:137]
	v_mov_b32_e32 v140, v142
	v_pk_mul_f32 v[138:139], v[138:139], v[138:139]
	v_pk_fma_f32 v[136:137], v[144:145], v[144:145], v[136:137]
	v_pk_fma_f32 v[138:139], v[140:141], v[140:141], v[138:139]
	s_nop 0
	v_pk_add_f32 v[136:137], v[136:137], v[138:139]
	s_nop 0
	v_add_f32_e32 v233, v136, v137
;     static __device__ __forceinline__ void run(const f32x4 (&acc)[2][2][4][2], const Unit& u, int wr, int wc, int fr, int fq, const float* xin, float* xout, const float* gate, float gs, const float* lazy_ssq, const float* lazy_g, ...
;     ...
;             for (int m = 0; m < 4; ++m) { rl[ai][m] = LAZY ? __builtin_amdgcn_rsqf(lazy_ssq[row0 + ai * HALF + m * 16] * (1.0f / 1024.0f) + 1e-6f) : 1.0f; sq[ai][m] = 0.f; sqb[ai][m] = 0.f; }
; #pragma unroll
;         for (int bj = 0; bj < 2; ++bj) {
;             const unsigned col = col0 + bj * HALF;
;             f32x4 gv[2], lg[2], wv[2], w2[2];
; #pragma unroll
;             for (int n = 0; n < 2; ++n) {
;                 gv[n] = *(const f32x4*)(gate + (b * 9216u + col + 4 * n)) * gs;
;                 lg[n] = (f32x4){1.f, 1.f, 1.f, 1.f}; if (LAZY) lg[n] = *(const f32x4*)(lazy_g + col + 4 * n);
;                 wv[n] = (f32x4){0.f, 0.f, 0.f, 0.f}; w2[n] = (f32x4){1.f, 1.f, 1.f, 1.f};
;                 if (aout) { wv[n] = *(const f32x4*)(wg + col + 4 * n) * (*(const f32x4*)(wsc + (b * 9216u + col + 4 * n)) + 1.0f); if (WG2) { w2[n] = *(const f32x4*)(wg2 + col + 4 * n); wv[n] = wv[n] * w2[n]; } }
;             }
;             f32x4 xq[2][2][2];
;     ...
;             constexpr bool DEEP = !LAZY && !WG2;
;             if (DEEP) RES_LD(0, 0);
; #pragma unroll
;             for (int pp = 0; pp < 4; ++pp) {
;                 if (DEEP) { if (pp < 3) RES_LD((pp + 1) & 1, pp + 1); } else RES_LD(pp & 1, pp);
; #pragma unroll
;                 for (int j = 0; j < 2; ++j) { const int i_ = 2 * pp + j, ai = i_ >> 2, m = i_ & 3; const unsigned off = (row0 + ai * HALF + m * 16) * 1024u + col;
;                     const f32x4 xi0 = xq[pp & 1][j][0], xi1 = xq[pp & 1][j][1];
;                     f32x4 xo0 = gv[0] * acc[ai][bj][m][0], xo1 = gv[1] * acc[ai][bj][m][1];
;                     if (LAZY) { xo0 = xo0 + xi0 * lg[0] * rl[ai][m]; xo1 = xo1 + xi1 * lg[1] * rl[ai][m]; } else { xo0 = xo0 + xi0; xo1 = xo1 + xi1; }
;                     *(f32x4*)(xout + off) = xo0; *(f32x4*)(xout + off + 4) = xo1;
;                     if (aout) { const f32x4 a0 = xo0 * wv[0], a1 = xo1 * wv[1]; u32x4 w; w.x = cvt_pk_bf16(a0[0], a0[1]); w.y = cvt_pk_bf16(a0[2], a0[3]); w.z = cvt_pk_bf16(a1[0], a1[1]); w.w = cvt_pk_bf16(a1[2], a1[3]);
;                         *(u32x4*)(aout + off) = w;
.LBB0_327:
	s_nop 0
	v_fmamk_f32 v136, v213, 0x3a800000, v222
	v_lshlrev_b32_e32 v213, 10, v158
	v_add_u32_e32 v214, v213, v184
	v_mov_b32_e32 v215, v177
	v_rsq_f32_e32 v206, v136
	v_lshl_add_u64 v[136:137], v[214:215], 2, s[34:35]
	global_load_dwordx4 v[148:151], v[136:137], off offset:16
	global_load_dwordx4 v[144:147], v[136:137], off
	v_add_u32_e32 v136, 0x4000, v214
	v_mov_b32_e32 v137, v177
	v_lshl_add_u64 v[140:141], v[136:137], 2, s[34:35]
	global_load_dwordx4 v[136:139], v[140:141], off offset:16
	s_nop 0
	global_load_dwordx4 v[140:143], v[140:141], off
	v_add_u32_e32 v208, 0x20000, v176
	v_mov_b32_e32 v209, v177
	v_lshl_add_u64 v[236:237], v[208:209], 2, s[30:31]
	v_mov_b32_e32 v235, 0
	s_and_b64 vcc, exec, s[8:9]
	s_waitcnt vmcnt(3)
	v_pk_mul_f32 v[150:151], v[134:135], v[150:151]
	s_waitcnt vmcnt(2)
	v_pk_mul_f32 v[146:147], v[130:131], v[146:147]
	v_pk_mul_f32 v[144:145], v[128:129], v[144:145]
	v_pk_mul_f32 v[146:147], v[206:207], v[146:147] op_sel_hi:[0,1]
	v_pk_mul_f32 v[144:145], v[206:207], v[144:145] op_sel_hi:[0,1]
	v_pk_mul_f32 v[148:149], v[132:133], v[148:149]
	v_pk_fma_f32 v[146:147], v[62:63], v[202:203], v[146:147]
	v_pk_fma_f32 v[144:145], v[60:61], v[204:205], v[144:145]
	v_pk_mul_f32 v[150:151], v[206:207], v[150:151] op_sel_hi:[0,1]
	v_pk_mul_f32 v[148:149], v[206:207], v[148:149] op_sel_hi:[0,1]
	v_pk_fma_f32 v[150:151], v[58:59], v[198:199], v[150:151]
	v_pk_fma_f32 v[148:149], v[56:57], v[200:201], v[148:149]
	global_store_dwordx4 v[236:237], v[144:147], off nt
	global_store_dwordx4 v[236:237], v[148:151], off offset:16 nt
	v_mov_b32_e32 v236, 0
	s_cbranch_vccnz .LBB0_329
	v_pk_mul_f32 v[238:239], v[188:189], v[146:147]
	v_pk_mul_f32 v[236:237], v[186:187], v[144:145]
	v_lshl_add_u64 v[208:209], v[208:209], 1, s[28:29]
	v_pk_mul_f32 v[240:241], v[194:195], v[150:151]
	v_pk_mul_f32 v[242:243], v[192:193], v[148:149]
	v_cvt_pk_bf16_f32 v236, v236, v237
	v_cvt_pk_bf16_f32 v237, v238, v239
	s_nop 0
	v_cvt_pk_bf16_f32 v238, v242, v243
	v_cvt_pk_bf16_f32 v239, v240, v241
	global_store_dwordx4 v[208:209], v[236:239], off
	v_mov_b32_e32 v209, v148
	v_mov_b32_e32 v148, v145
	v_mov_b32_e32 v208, v144
	v_pk_mul_f32 v[144:145], v[148:149], v[148:149]
	v_mov_b32_e32 v149, v150
	v_mov_b32_e32 v150, v147
	v_mov_b32_e32 v148, v146
	v_pk_mul_f32 v[146:147], v[150:151], v[150:151]
	v_pk_fma_f32 v[144:145], v[208:209], v[208:209], v[144:145]
	v_pk_fma_f32 v[146:147], v[148:149], v[148:149], v[146:147]
	s_nop 0
	v_pk_add_f32 v[144:145], v[144:145], v[146:147]
	s_nop 0
	v_add_f32_e32 v236, v144, v145
.LBB0_329:
	v_fmamk_f32 v144, v212, 0x3a800000, v222
	v_rsq_f32_e32 v212, v144
	s_waitcnt vmcnt(2)
	v_pk_mul_f32 v[142:143], v[130:131], v[142:143]
	v_pk_mul_f32 v[140:141], v[128:129], v[140:141]
	v_pk_mul_f32 v[138:139], v[134:135], v[138:139]
	v_pk_mul_f32 v[136:137], v[132:133], v[136:137]
	v_add_u32_e32 v144, 0x24000, v176
	v_pk_mul_f32 v[142:143], v[212:213], v[142:143] op_sel_hi:[0,1]
	v_pk_mul_f32 v[140:141], v[212:213], v[140:141] op_sel_hi:[0,1]
	v_pk_mul_f32 v[138:139], v[212:213], v[138:139] op_sel_hi:[0,1]
	v_pk_mul_f32 v[136:137], v[212:213], v[136:137] op_sel_hi:[0,1]
	v_mov_b32_e32 v145, v177
	v_pk_fma_f32 v[142:143], v[46:47], v[202:203], v[142:143]
	v_pk_fma_f32 v[140:141], v[44:45], v[204:205], v[140:141]
	v_pk_fma_f32 v[138:139], v[42:43], v[198:199], v[138:139]
	v_pk_fma_f32 v[136:137], v[40:41], v[200:201], v[136:137]
	v_lshl_add_u64 v[146:147], v[144:145], 2, s[30:31]
	s_and_b64 vcc, exec, s[8:9]
	global_store_dwordx4 v[146:147], v[140:143], off nt
	global_store_dwordx4 v[146:147], v[136:139], off offset:16 nt
	s_cbranch_vccnz .LBB0_331
	v_pk_mul_f32 v[148:149], v[188:189], v[142:143]
	v_pk_mul_f32 v[146:147], v[186:187], v[140:141]
	v_lshl_add_u64 v[144:145], v[144:145], 1, s[28:29]
	v_pk_mul_f32 v[150:151], v[194:195], v[138:139]
	v_pk_mul_f32 v[208:209], v[192:193], v[136:137]
	v_cvt_pk_bf16_f32 v146, v146, v147
	v_cvt_pk_bf16_f32 v147, v148, v149
	s_nop 0
	v_cvt_pk_bf16_f32 v148, v208, v209
	v_cvt_pk_bf16_f32 v149, v150, v151
	global_store_dwordx4 v[144:145], v[146:149], off
	v_mov_b32_e32 v145, v136
	v_mov_b32_e32 v136, v141
	v_mov_b32_e32 v141, v138
	v_mov_b32_e32 v138, v143
	v_mov_b32_e32 v144, v140
	v_pk_mul_f32 v[136:137], v[136:137], v[136:137]
	v_mov_b32_e32 v140, v142
	v_pk_mul_f32 v[138:139], v[138:139], v[138:139]
	v_pk_fma_f32 v[136:137], v[144:145], v[144:145], v[136:137]
	v_pk_fma_f32 v[138:139], v[140:141], v[140:141], v[138:139]
	s_nop 0
	v_pk_add_f32 v[136:137], v[136:137], v[138:139]
	s_nop 0
	v_add_f32_e32 v235, v136, v137
;     static __device__ __forceinline__ void run(const f32x4 (&acc)[2][2][4][2], const Unit& u, int wr, int wc, int fr, int fq, const float* xin, float* xout, const float* gate, float gs, const float* lazy_ssq, const float* lazy_g, ...
;     ...
;             for (int m = 0; m < 4; ++m) { rl[ai][m] = LAZY ? __builtin_amdgcn_rsqf(lazy_ssq[row0 + ai * HALF + m * 16] * (1.0f / 1024.0f) + 1e-6f) : 1.0f; sq[ai][m] = 0.f; sqb[ai][m] = 0.f; }
; #pragma unroll
;         for (int bj = 0; bj < 2; ++bj) {
;             const unsigned col = col0 + bj * HALF;
;             f32x4 gv[2], lg[2], wv[2], w2[2];
; #pragma unroll
;             for (int n = 0; n < 2; ++n) {
;                 gv[n] = *(const f32x4*)(gate + (b * 9216u + col + 4 * n)) * gs;
;                 lg[n] = (f32x4){1.f, 1.f, 1.f, 1.f}; if (LAZY) lg[n] = *(const f32x4*)(lazy_g + col + 4 * n);
;                 wv[n] = (f32x4){0.f, 0.f, 0.f, 0.f}; w2[n] = (f32x4){1.f, 1.f, 1.f, 1.f};
;                 if (aout) { wv[n] = *(const f32x4*)(wg + col + 4 * n) * (*(const f32x4*)(wsc + (b * 9216u + col + 4 * n)) + 1.0f); if (WG2) { w2[n] = *(const f32x4*)(wg2 + col + 4 * n); wv[n] = wv[n] * w2[n]; } }
;             }
;             f32x4 xq[2][2][2];
;     ...
;             constexpr bool DEEP = !LAZY && !WG2;
;             if (DEEP) RES_LD(0, 0);
; #pragma unroll
;             for (int pp = 0; pp < 4; ++pp) {
;                 if (DEEP) { if (pp < 3) RES_LD((pp + 1) & 1, pp + 1); } else RES_LD(pp & 1, pp);
; #pragma unroll
;                 for (int j = 0; j < 2; ++j) { const int i_ = 2 * pp + j, ai = i_ >> 2, m = i_ & 3; const unsigned off = (row0 + ai * HALF + m * 16) * 1024u + col;
;                     const f32x4 xi0 = xq[pp & 1][j][0], xi1 = xq[pp & 1][j][1];
;                     f32x4 xo0 = gv[0] * acc[ai][bj][m][0], xo1 = gv[1] * acc[ai][bj][m][1];
;                     if (LAZY) { xo0 = xo0 + xi0 * lg[0] * rl[ai][m]; xo1 = xo1 + xi1 * lg[1] * rl[ai][m]; } else { xo0 = xo0 + xi0; xo1 = xo1 + xi1; }
;                     *(f32x4*)(xout + off) = xo0; *(f32x4*)(xout + off + 4) = xo1;
;                     if (aout) { const f32x4 a0 = xo0 * wv[0], a1 = xo1 * wv[1]; u32x4 w; w.x = cvt_pk_bf16(a0[0], a0[1]); w.y = cvt_pk_bf16(a0[2], a0[3]); w.z = cvt_pk_bf16(a1[0], a1[1]); w.w = cvt_pk_bf16(a1[2], a1[3]);
;                         *(u32x4*)(aout + off) = w;
.LBB0_331:
	s_nop 0
	v_fmamk_f32 v136, v211, 0x3a800000, v222
	v_rsq_f32_e32 v208, v136
	v_add_u32_e32 v136, 0x8000, v214
	v_mov_b32_e32 v137, v177
	v_lshl_add_u64 v[136:137], v[136:137], 2, s[34:35]
	global_load_dwordx4 v[148:151], v[136:137], off offset:16
	global_load_dwordx4 v[144:147], v[136:137], off
	v_add_u32_e32 v136, 0xc000, v214
	v_mov_b32_e32 v137, v177
	v_lshl_add_u64 v[140:141], v[136:137], 2, s[34:35]
	global_load_dwordx4 v[136:139], v[140:141], off offset:16
	s_nop 0
	global_load_dwordx4 v[140:143], v[140:141], off
	v_add_u32_e32 v214, 0x28000, v176
	v_mov_b32_e32 v215, v177
	v_lshl_add_u64 v[238:239], v[214:215], 2, s[30:31]
	v_mov_b32_e32 v237, 0
	s_and_b64 vcc, exec, s[8:9]
	s_waitcnt vmcnt(3)
	v_pk_mul_f32 v[150:151], v[134:135], v[150:151]
	s_waitcnt vmcnt(2)
	v_pk_mul_f32 v[146:147], v[130:131], v[146:147]
	v_pk_mul_f32 v[144:145], v[128:129], v[144:145]
	v_pk_mul_f32 v[146:147], v[208:209], v[146:147] op_sel_hi:[0,1]
	v_pk_mul_f32 v[144:145], v[208:209], v[144:145] op_sel_hi:[0,1]
	v_pk_mul_f32 v[148:149], v[132:133], v[148:149]
	v_pk_fma_f32 v[146:147], v[30:31], v[202:203], v[146:147]
	v_pk_fma_f32 v[144:145], v[28:29], v[204:205], v[144:145]
	v_pk_mul_f32 v[150:151], v[208:209], v[150:151] op_sel_hi:[0,1]
	v_pk_mul_f32 v[148:149], v[208:209], v[148:149] op_sel_hi:[0,1]
	v_pk_fma_f32 v[150:151], v[26:27], v[198:199], v[150:151]
	v_pk_fma_f32 v[148:149], v[24:25], v[200:201], v[148:149]
	global_store_dwordx4 v[238:239], v[144:147], off nt
	global_store_dwordx4 v[238:239], v[148:151], off offset:16 nt
	v_mov_b32_e32 v238, 0
	s_cbranch_vccnz .LBB0_333
	v_pk_mul_f32 v[240:241], v[188:189], v[146:147]
	v_pk_mul_f32 v[238:239], v[186:187], v[144:145]
	v_lshl_add_u64 v[214:215], v[214:215], 1, s[28:29]
	v_pk_mul_f32 v[242:243], v[194:195], v[150:151]
	v_pk_mul_f32 v[244:245], v[192:193], v[148:149]
	v_cvt_pk_bf16_f32 v238, v238, v239
	v_cvt_pk_bf16_f32 v239, v240, v241
	s_nop 0
	v_cvt_pk_bf16_f32 v240, v244, v245
	v_cvt_pk_bf16_f32 v241, v242, v243
	global_store_dwordx4 v[214:215], v[238:241], off
	v_mov_b32_e32 v215, v148
	v_mov_b32_e32 v148, v145
	v_mov_b32_e32 v214, v144
	v_pk_mul_f32 v[144:145], v[148:149], v[148:149]
	v_mov_b32_e32 v149, v150
	v_mov_b32_e32 v150, v147
	v_mov_b32_e32 v148, v146
	v_pk_mul_f32 v[146:147], v[150:151], v[150:151]
	v_pk_fma_f32 v[144:145], v[214:215], v[214:215], v[144:145]
	v_pk_fma_f32 v[146:147], v[148:149], v[148:149], v[146:147]
	s_nop 0
	v_pk_add_f32 v[144:145], v[144:145], v[146:147]
	s_nop 0
	v_add_f32_e32 v238, v144, v145
.LBB0_333:
	v_fmamk_f32 v144, v197, 0x3a800000, v222
	v_rsq_f32_e32 v214, v144
	s_waitcnt vmcnt(2)
	v_pk_mul_f32 v[130:131], v[130:131], v[142:143]
	v_pk_mul_f32 v[128:129], v[128:129], v[140:141]
	v_pk_mul_f32 v[134:135], v[134:135], v[138:139]
	v_pk_mul_f32 v[132:133], v[132:133], v[136:137]
	v_add_u32_e32 v176, 0x2c000, v176
	v_pk_mul_f32 v[130:131], v[214:215], v[130:131] op_sel_hi:[0,1]
	v_pk_mul_f32 v[128:129], v[214:215], v[128:129] op_sel_hi:[0,1]
	v_pk_mul_f32 v[134:135], v[214:215], v[134:135] op_sel_hi:[0,1]
	v_pk_mul_f32 v[132:133], v[214:215], v[132:133] op_sel_hi:[0,1]
	v_pk_fma_f32 v[130:131], v[14:15], v[202:203], v[130:131]
	v_pk_fma_f32 v[128:129], v[12:13], v[204:205], v[128:129]
	v_pk_fma_f32 v[134:135], v[10:11], v[198:199], v[134:135]
	v_pk_fma_f32 v[132:133], v[8:9], v[200:201], v[132:133]
	v_lshl_add_u64 v[136:137], v[176:177], 2, s[30:31]
	s_and_b64 vcc, exec, s[8:9]
	global_store_dwordx4 v[136:137], v[128:131], off nt
	global_store_dwordx4 v[136:137], v[132:135], off offset:16 nt
	s_cbranch_vccnz .LBB0_335
	v_pk_mul_f32 v[138:139], v[188:189], v[130:131]
	v_pk_mul_f32 v[136:137], v[186:187], v[128:129]
	v_pk_mul_f32 v[140:141], v[194:195], v[134:135]
	v_pk_mul_f32 v[142:143], v[192:193], v[132:133]
	v_cvt_pk_bf16_f32 v136, v136, v137
	v_cvt_pk_bf16_f32 v137, v138, v139
	s_nop 0
	v_cvt_pk_bf16_f32 v138, v142, v143
	v_cvt_pk_bf16_f32 v139, v140, v141
	v_lshl_add_u64 v[140:141], v[176:177], 1, s[28:29]
	global_store_dwordx4 v[140:141], v[136:139], off
	s_nop 1
	v_mov_b32_e32 v137, v132
	v_mov_b32_e32 v132, v129
	v_mov_b32_e32 v136, v128
	v_pk_mul_f32 v[128:129], v[132:133], v[132:133]
	v_mov_b32_e32 v133, v134
	v_mov_b32_e32 v134, v131
	v_mov_b32_e32 v132, v130
	v_pk_mul_f32 v[130:131], v[134:135], v[134:135]
	v_pk_fma_f32 v[128:129], v[136:137], v[136:137], v[128:129]
	v_pk_fma_f32 v[130:131], v[132:133], v[132:133], v[130:131]
	s_nop 0
	v_pk_add_f32 v[128:129], v[128:129], v[130:131]
	s_nop 0
	v_add_f32_e32 v237, v128, v129

;     static __device__ __forceinline__ void run(const f32x4 (&acc)[2][2][4][2], const Unit& u, int wr, int wc, int fr, int fq, const float* xin, float* xout, const float* gate, float gs, const float* lazy_ssq, const float* lazy_g, ...
;     ...
;         for (int bj = 0; bj < 2; ++bj) {
;             const unsigned col = col0 + bj * HALF;
;             f32x4 gv[2], lg[2], wv[2], w2[2];
; #pragma unroll
;             for (int n = 0; n < 2; ++n) {
;                 gv[n] = *(const f32x4*)(gate + (b * 9216u + col + 4 * n)) * gs;
;                 lg[n] = (f32x4){1.f, 1.f, 1.f, 1.f}; if (LAZY) lg[n] = *(const f32x4*)(lazy_g + col + 4 * n);
;                 wv[n] = (f32x4){0.f, 0.f, 0.f, 0.f}; w2[n] = (f32x4){1.f, 1.f, 1.f, 1.f};
;                 if (aout) { wv[n] = *(const f32x4*)(wg + col + 4 * n) * (*(const f32x4*)(wsc + (b * 9216u + col + 4 * n)) + 1.0f); if (WG2) { w2[n] = *(const f32x4*)(wg2 + col + 4 * n); wv[n] = wv[n] * w2[n]; } }
;             }
;             f32x4 xq[2][2][2];
;     ...
;             constexpr bool DEEP = !LAZY && !WG2;
;             if (DEEP) RES_LD(0, 0);
; #pragma unroll
;             for (int pp = 0; pp < 4; ++pp) {
;                 if (DEEP) { if (pp < 3) RES_LD((pp + 1) & 1, pp + 1); } else RES_LD(pp & 1, pp);
; #pragma unroll
;                 for (int j = 0; j < 2; ++j) { const int i_ = 2 * pp + j, ai = i_ >> 2, m = i_ & 3; const unsigned off = (row0 + ai * HALF + m * 16) * 1024u + col;
;                     const f32x4 xi0 = xq[pp & 1][j][0], xi1 = xq[pp & 1][j][1];
;                     f32x4 xo0 = gv[0] * acc[ai][bj][m][0], xo1 = gv[1] * acc[ai][bj][m][1];
;                     if (LAZY) { xo0 = xo0 + xi0 * lg[0] * rl[ai][m]; xo1 = xo1 + xi1 * lg[1] * rl[ai][m]; } else { xo0 = xo0 + xi0; xo1 = xo1 + xi1; }
;                     *(f32x4*)(xout + off) = xo0; *(f32x4*)(xout + off + 4) = xo1;
;                     if (aout) { const f32x4 a0 = xo0 * wv[0], a1 = xo1 * wv[1]; u32x4 w; w.x = cvt_pk_bf16(a0[0], a0[1]); w.y = cvt_pk_bf16(a0[2], a0[3]); w.z = cvt_pk_bf16(a1[0], a1[1]); w.w = cvt_pk_bf16(a1[2], a1[3]);
;                         *(u32x4*)(aout + off) = w;
;                         sq[ai][m] += ((xo0[0] * xo0[0] + xo0[1] * xo0[1]) + (xo0[2] * xo0[2] + xo0[3] * xo0[3])) + ((xo1[0] * xo1[0] + xo1[1] * xo1[1]) + (xo1[2] * xo1[2] + xo1[3] * xo1[3]));
.LBB0_339:
	v_add_u32_e32 v176, v202, v175
	v_lshlrev_b64 v[204:205], 2, v[176:177]
	v_lshl_add_u64 v[136:137], s[34:35], 0, v[204:205]
	global_load_dwordx4 v[240:243], v[136:137], off
	global_load_dwordx4 v[244:247], v[136:137], off offset:16
	v_mov_b32_e32 v201, v177
	v_add_u32_e32 v200, 0x4000, v176
	v_lshl_add_u64 v[144:145], v[200:201], 2, s[34:35]
	global_load_dwordx4 v[136:139], v[144:145], off offset:16
	s_nop 0
	global_load_dwordx4 v[144:147], v[144:145], off
	s_mov_b32 s37, s36
	s_mov_b32 s38, s36
	s_mov_b32 s39, s36
	v_mov_b32_e32 v175, v174
	v_mov_b32_e32 v248, v174
	v_mov_b32_e32 v249, v174
	s_waitcnt vmcnt(5)
	v_pk_mul_f32 v[182:183], s[38:39], v[150:151]
	v_pk_mul_f32 v[192:193], s[36:37], v[148:149]
	v_pk_mul_f32 v[194:195], s[38:39], v[142:143]
	v_pk_mul_f32 v[198:199], s[36:37], v[140:141]
	s_and_b64 vcc, exec, s[8:9]
	v_lshl_add_u64 v[204:205], s[30:31], 0, v[204:205]
	s_waitcnt vmcnt(3)
	v_pk_mul_f32 v[140:141], v[130:131], v[242:243]
	v_pk_mul_f32 v[142:143], v[128:129], v[240:241]
	s_waitcnt vmcnt(2)
	v_pk_mul_f32 v[148:149], v[134:135], v[246:247]
	v_pk_mul_f32 v[150:151], v[132:133], v[244:245]
	v_pk_mul_f32 v[140:141], v[248:249], v[140:141]
	v_pk_mul_f32 v[142:143], v[174:175], v[142:143]
	v_pk_mul_f32 v[240:241], v[248:249], v[148:149]
	v_pk_mul_f32 v[174:175], v[174:175], v[150:151]
	v_pk_fma_f32 v[150:151], v[118:119], v[194:195], v[140:141]
	v_pk_fma_f32 v[148:149], v[116:117], v[198:199], v[142:143]
	v_pk_fma_f32 v[142:143], v[114:115], v[182:183], v[240:241]
	v_pk_fma_f32 v[140:141], v[112:113], v[192:193], v[174:175]
	global_store_dwordx4 v[204:205], v[148:151], off nt
	global_store_dwordx4 v[204:205], v[140:143], off offset:16 nt
	s_cbranch_vccnz .LBB0_341
	v_pk_mul_f32 v[174:175], v[188:189], v[150:151]
	v_pk_mul_f32 v[204:205], v[186:187], v[148:149]
	v_pk_mul_f32 v[242:243], v[184:185], v[140:141]
	v_cvt_pk_bf16_f32 v240, v204, v205
	v_cvt_pk_bf16_f32 v241, v174, v175
	v_lshl_add_u64 v[174:175], v[176:177], 1, s[28:29]
	v_pk_mul_f32 v[244:245], v[180:181], v[142:143]
	v_cvt_pk_bf16_f32 v242, v242, v243
	s_nop 0
	v_cvt_pk_bf16_f32 v243, v244, v245
	global_store_dwordx4 v[174:175], v[240:243], off
	v_mov_b32_e32 v175, v140
	v_mov_b32_e32 v140, v149
	v_mov_b32_e32 v149, v142
	v_mov_b32_e32 v142, v151
	v_mov_b32_e32 v174, v148
	v_pk_mul_f32 v[140:141], v[140:141], v[140:141]
	v_mov_b32_e32 v148, v150
	v_pk_mul_f32 v[142:143], v[142:143], v[142:143]
	v_pk_fma_f32 v[140:141], v[174:175], v[174:175], v[140:141]
	v_pk_fma_f32 v[142:143], v[148:149], v[148:149], v[142:143]
	s_nop 0
	v_pk_add_f32 v[140:141], v[140:141], v[142:143]
	s_nop 0
	v_add_f32_e32 v140, v140, v141
	v_add_f32_e32 v232, v232, v140
.LBB0_341:
	v_mov_b32_e32 v197, v196
	s_waitcnt vmcnt(2)
	v_pk_mul_f32 v[140:141], v[130:131], v[146:147]
	v_pk_mul_f32 v[142:143], v[128:129], v[144:145]
	v_mov_b32_e32 v144, v196
	v_mov_b32_e32 v145, v196
	v_pk_mul_f32 v[138:139], v[134:135], v[138:139]
	v_pk_mul_f32 v[136:137], v[132:133], v[136:137]
	v_pk_mul_f32 v[140:141], v[144:145], v[140:141]
	v_pk_mul_f32 v[146:147], v[196:197], v[142:143]
	v_pk_mul_f32 v[138:139], v[144:145], v[138:139]
	v_pk_mul_f32 v[136:137], v[196:197], v[136:137]
	v_pk_fma_f32 v[142:143], v[102:103], v[194:195], v[140:141]
	v_pk_fma_f32 v[140:141], v[100:101], v[198:199], v[146:147]
	v_pk_fma_f32 v[138:139], v[98:99], v[182:183], v[138:139]
	v_pk_fma_f32 v[136:137], v[96:97], v[192:193], v[136:137]
	v_lshl_add_u64 v[144:145], v[200:201], 2, s[30:31]
	s_and_b64 vcc, exec, s[8:9]
	global_store_dwordx4 v[144:145], v[140:143], off nt
	global_store_dwordx4 v[144:145], v[136:139], off offset:16 nt
	s_cbranch_vccnz .LBB0_343
	v_pk_mul_f32 v[146:147], v[188:189], v[142:143]
	v_pk_mul_f32 v[144:145], v[186:187], v[140:141]
	v_pk_mul_f32 v[148:149], v[180:181], v[138:139]
	v_pk_mul_f32 v[150:151], v[184:185], v[136:137]
	v_cvt_pk_bf16_f32 v144, v144, v145
	v_cvt_pk_bf16_f32 v145, v146, v147
	s_nop 0
	v_cvt_pk_bf16_f32 v146, v150, v151
	v_cvt_pk_bf16_f32 v147, v148, v149
	v_lshl_add_u64 v[148:149], v[200:201], 1, s[28:29]
	global_store_dwordx4 v[148:149], v[144:147], off
	s_nop 1
	v_mov_b32_e32 v145, v136
	v_mov_b32_e32 v136, v141
	v_mov_b32_e32 v141, v138
	v_mov_b32_e32 v138, v143
	v_mov_b32_e32 v144, v140
	v_pk_mul_f32 v[136:137], v[136:137], v[136:137]
	v_mov_b32_e32 v140, v142
	v_pk_mul_f32 v[138:139], v[138:139], v[138:139]
	v_pk_fma_f32 v[136:137], v[144:145], v[144:145], v[136:137]
	v_pk_fma_f32 v[138:139], v[140:141], v[140:141], v[138:139]
	s_nop 0
	v_pk_add_f32 v[136:137], v[136:137], v[138:139]
	s_nop 0
	v_add_f32_e32 v136, v136, v137
	v_add_f32_e32 v231, v231, v136
; __device__ __forceinline__ unsigned cvt_pk_bf16(float lo, float hi) { unsigned r; asm volatile("v_cvt_pk_bf16_f32 %0, %1, %2" : "=v"(r) : "v"(lo), "v"(hi)); return r; }
; #define RES_LD(buf, pp) do { _Pragma("unroll") for (int j = 0; j < 2; ++j) { const int i_ = 2 * (pp) + j; const unsigned off_ = (row0 + (i_ >> 2) * HALF + (i_ & 3) * 16) * 1024u + col; \
;                 xq[buf][j][0] = *(const f32x4*)(xin + off_); xq[buf][j][1] = *(const f32x4*)(xin + off_ + 4); } } while (0)
;     static __device__ __forceinline__ void run(const f32x4 (&acc)[2][2][4][2], const Unit& u, int wr, int wc, int fr, int fq, const float* xin, float* xout, const float* gate, float gs, const float* lazy_ssq, const float* lazy_g, ...
;     ...
;             constexpr bool DEEP = !LAZY && !WG2;
;             if (DEEP) RES_LD(0, 0);
; #pragma unroll
;             for (int pp = 0; pp < 4; ++pp) {
;                 if (DEEP) { if (pp < 3) RES_LD((pp + 1) & 1, pp + 1); } else RES_LD(pp & 1, pp);
; #pragma unroll
;                 for (int j = 0; j < 2; ++j) { const int i_ = 2 * pp + j, ai = i_ >> 2, m = i_ & 3; const unsigned off = (row0 + ai * HALF + m * 16) * 1024u + col;
;                     const f32x4 xi0 = xq[pp & 1][j][0], xi1 = xq[pp & 1][j][1];
;                     f32x4 xo0 = gv[0] * acc[ai][bj][m][0], xo1 = gv[1] * acc[ai][bj][m][1];
;                     if (LAZY) { xo0 = xo0 + xi0 * lg[0] * rl[ai][m]; xo1 = xo1 + xi1 * lg[1] * rl[ai][m]; } else { xo0 = xo0 + xi0; xo1 = xo1 + xi1; }
;                     *(f32x4*)(xout + off) = xo0; *(f32x4*)(xout + off + 4) = xo1;
;                     if (aout) { const f32x4 a0 = xo0 * wv[0], a1 = xo1 * wv[1]; u32x4 w; w.x = cvt_pk_bf16(a0[0], a0[1]); w.y = cvt_pk_bf16(a0[2], a0[3]); w.z = cvt_pk_bf16(a1[0], a1[1]); w.w = cvt_pk_bf16(a1[2], a1[3]);
;                         *(u32x4*)(aout + off) = w;
;                         sq[ai][m] += ((xo0[0] * xo0[0] + xo0[1] * xo0[1]) + (xo0[2] * xo0[2] + xo0[3] * xo0[3])) + ((xo1[0] * xo1[0] + xo1[1] * xo1[1]) + (xo1[2] * xo1[2] + xo1[3] * xo1[3]));
;                         if (WG2) { const f32x4 b0 = xo0 * w2[0], b1 = xo1 * w2[1]; sqb[ai][m] += ((b0[0] * b0[0] + b0[1] * b0[1]) + (b0[2] * b0[2] + b0[3] * b0[3])) + ((b1[0] * b1[0] + b1[1] * b1[1]) + (b1[2] * b1[2] + b1[3] * b1[3])); } } }
.LBB0_343:
	v_add_u32_e32 v196, 0x8000, v176
	v_mov_b32_e32 v197, v177
	v_lshlrev_b64 v[200:201], 2, v[196:197]
	v_lshl_add_u64 v[136:137], s[34:35], 0, v[200:201]
	global_load_dwordx4 v[144:147], v[136:137], off
	global_load_dwordx4 v[148:151], v[136:137], off offset:16
	v_add_u32_e32 v174, 0xc000, v176
	v_mov_b32_e32 v175, v177
	v_lshl_add_u64 v[140:141], v[174:175], 2, s[34:35]
	global_load_dwordx4 v[136:139], v[140:141], off offset:16
	s_nop 0
	global_load_dwordx4 v[140:143], v[140:141], off
	v_mov_b32_e32 v191, v190
	v_mov_b32_e32 v204, v190
	v_mov_b32_e32 v205, v190
	s_and_b64 vcc, exec, s[8:9]
	v_lshl_add_u64 v[200:201], s[30:31], 0, v[200:201]
	s_waitcnt vmcnt(3)
	v_pk_mul_f32 v[146:147], v[130:131], v[146:147]
	v_pk_mul_f32 v[144:145], v[128:129], v[144:145]
	s_waitcnt vmcnt(2)
	v_pk_mul_f32 v[150:151], v[134:135], v[150:151]
	v_pk_mul_f32 v[148:149], v[132:133], v[148:149]
	v_pk_mul_f32 v[146:147], v[204:205], v[146:147]
	v_pk_mul_f32 v[144:145], v[190:191], v[144:145]
	v_pk_mul_f32 v[204:205], v[204:205], v[150:151]
	v_pk_mul_f32 v[190:191], v[190:191], v[148:149]
	v_pk_fma_f32 v[150:151], v[86:87], v[194:195], v[146:147]
	v_pk_fma_f32 v[148:149], v[84:85], v[198:199], v[144:145]
	v_pk_fma_f32 v[146:147], v[82:83], v[182:183], v[204:205]
	v_pk_fma_f32 v[144:145], v[80:81], v[192:193], v[190:191]
	global_store_dwordx4 v[200:201], v[148:151], off nt
	global_store_dwordx4 v[200:201], v[144:147], off offset:16 nt
	s_cbranch_vccnz .LBB0_345
	v_pk_mul_f32 v[190:191], v[188:189], v[150:151]
	v_pk_mul_f32 v[200:201], v[186:187], v[148:149]
	v_pk_mul_f32 v[242:243], v[184:185], v[144:145]
	v_cvt_pk_bf16_f32 v240, v200, v201
	v_cvt_pk_bf16_f32 v241, v190, v191
	v_lshl_add_u64 v[190:191], v[196:197], 1, s[28:29]
	v_pk_mul_f32 v[204:205], v[180:181], v[146:147]
	v_cvt_pk_bf16_f32 v242, v242, v243
	s_nop 0
	v_cvt_pk_bf16_f32 v243, v204, v205
	global_store_dwordx4 v[190:191], v[240:243], off
	v_mov_b32_e32 v191, v144
	v_mov_b32_e32 v144, v149
	v_mov_b32_e32 v149, v146
	v_mov_b32_e32 v146, v151
	v_mov_b32_e32 v190, v148
	v_pk_mul_f32 v[144:145], v[144:145], v[144:145]
	v_mov_b32_e32 v148, v150
	v_pk_mul_f32 v[146:147], v[146:147], v[146:147]
	v_pk_fma_f32 v[144:145], v[190:191], v[190:191], v[144:145]
	v_pk_fma_f32 v[146:147], v[148:149], v[148:149], v[146:147]
	s_nop 0
	v_pk_add_f32 v[144:145], v[144:145], v[146:147]
	s_nop 0
	v_add_f32_e32 v144, v144, v145
	v_add_f32_e32 v234, v234, v144
.LBB0_345:
	v_mov_b32_e32 v211, v210
	s_waitcnt vmcnt(2)
	v_pk_mul_f32 v[142:143], v[130:131], v[142:143]
	v_pk_mul_f32 v[140:141], v[128:129], v[140:141]
	v_mov_b32_e32 v144, v210
	v_mov_b32_e32 v145, v210
	v_pk_mul_f32 v[138:139], v[134:135], v[138:139]
	v_pk_mul_f32 v[136:137], v[132:133], v[136:137]
	v_pk_mul_f32 v[142:143], v[144:145], v[142:143]
	v_pk_mul_f32 v[140:141], v[210:211], v[140:141]
	v_pk_mul_f32 v[138:139], v[144:145], v[138:139]
	v_pk_mul_f32 v[136:137], v[210:211], v[136:137]
	v_pk_fma_f32 v[142:143], v[70:71], v[194:195], v[142:143]
	v_pk_fma_f32 v[140:141], v[68:69], v[198:199], v[140:141]
	v_pk_fma_f32 v[138:139], v[66:67], v[182:183], v[138:139]
	v_pk_fma_f32 v[136:137], v[64:65], v[192:193], v[136:137]
	v_lshl_add_u64 v[144:145], v[174:175], 2, s[30:31]
	s_and_b64 vcc, exec, s[8:9]
	global_store_dwordx4 v[144:145], v[140:143], off nt
	global_store_dwordx4 v[144:145], v[136:139], off offset:16 nt
	s_cbranch_vccnz .LBB0_347
	v_pk_mul_f32 v[146:147], v[188:189], v[142:143]
	v_pk_mul_f32 v[144:145], v[186:187], v[140:141]
	v_pk_mul_f32 v[148:149], v[180:181], v[138:139]
	v_pk_mul_f32 v[150:151], v[184:185], v[136:137]
	v_cvt_pk_bf16_f32 v144, v144, v145
	v_cvt_pk_bf16_f32 v145, v146, v147
	s_nop 0
	v_cvt_pk_bf16_f32 v146, v150, v151
	v_cvt_pk_bf16_f32 v147, v148, v149
	v_lshl_add_u64 v[148:149], v[174:175], 1, s[28:29]
	global_store_dwordx4 v[148:149], v[144:147], off
	s_nop 1
	v_mov_b32_e32 v145, v136
	v_mov_b32_e32 v136, v141
	v_mov_b32_e32 v141, v138
	v_mov_b32_e32 v138, v143
	v_mov_b32_e32 v144, v140
	v_pk_mul_f32 v[136:137], v[136:137], v[136:137]
	v_mov_b32_e32 v140, v142
	v_pk_mul_f32 v[138:139], v[138:139], v[138:139]
	v_pk_fma_f32 v[136:137], v[144:145], v[144:145], v[136:137]
	v_pk_fma_f32 v[138:139], v[140:141], v[140:141], v[138:139]
	s_nop 0
	v_pk_add_f32 v[136:137], v[136:137], v[138:139]
	s_nop 0
	v_add_f32_e32 v136, v136, v137
	v_add_f32_e32 v233, v233, v136
.LBB0_347:
	v_add_u32_e32 v174, v213, v202
	v_mov_b32_e32 v175, v177
	v_lshl_add_u64 v[136:137], v[174:175], 2, s[34:35]
	global_load_dwordx4 v[148:151], v[136:137], off offset:16
	global_load_dwordx4 v[144:147], v[136:137], off
	v_add_u32_e32 v136, 0x4000, v174
	v_mov_b32_e32 v137, v177
	v_lshl_add_u64 v[140:141], v[136:137], 2, s[34:35]
	global_load_dwordx4 v[136:139], v[140:141], off offset:16
	s_nop 0
	global_load_dwordx4 v[140:143], v[140:141], off
	v_mov_b32_e32 v207, v206
	v_mov_b32_e32 v196, v206
	v_mov_b32_e32 v197, v206
	v_add_u32_e32 v190, 0x20000, v176
	v_mov_b32_e32 v191, v177
	s_and_b64 vcc, exec, s[8:9]
	s_waitcnt vmcnt(3)
	v_pk_mul_f32 v[150:151], v[134:135], v[150:151]
	s_waitcnt vmcnt(2)
	v_pk_mul_f32 v[146:147], v[130:131], v[146:147]
	v_pk_mul_f32 v[144:145], v[128:129], v[144:145]
	v_pk_mul_f32 v[148:149], v[132:133], v[148:149]
	v_pk_mul_f32 v[146:147], v[196:197], v[146:147]
	v_pk_mul_f32 v[144:145], v[206:207], v[144:145]
	v_pk_mul_f32 v[150:151], v[196:197], v[150:151]
	v_pk_mul_f32 v[148:149], v[206:207], v[148:149]
	v_pk_fma_f32 v[146:147], v[54:55], v[194:195], v[146:147]
	v_pk_fma_f32 v[144:145], v[52:53], v[198:199], v[144:145]
	v_pk_fma_f32 v[150:151], v[50:51], v[182:183], v[150:151]
	v_pk_fma_f32 v[148:149], v[48:49], v[192:193], v[148:149]
	v_lshl_add_u64 v[196:197], v[190:191], 2, s[30:31]
	global_store_dwordx4 v[196:197], v[144:147], off nt
	global_store_dwordx4 v[196:197], v[148:151], off offset:16 nt
	s_cbranch_vccnz .LBB0_349
	v_pk_mul_f32 v[200:201], v[186:187], v[144:145]
	v_pk_mul_f32 v[202:203], v[184:185], v[148:149]
	v_lshl_add_u64 v[190:191], v[190:191], 1, s[28:29]
	v_pk_mul_f32 v[196:197], v[188:189], v[146:147]
	v_pk_mul_f32 v[204:205], v[180:181], v[150:151]
	v_cvt_pk_bf16_f32 v200, v200, v201
	v_cvt_pk_bf16_f32 v201, v196, v197
	v_cvt_pk_bf16_f32 v202, v202, v203
	s_nop 0
	v_cvt_pk_bf16_f32 v203, v204, v205
	global_store_dwordx4 v[190:191], v[200:203], off
	v_mov_b32_e32 v191, v148
	v_mov_b32_e32 v148, v145
	v_mov_b32_e32 v190, v144
	v_pk_mul_f32 v[144:145], v[148:149], v[148:149]
	v_mov_b32_e32 v149, v150
	v_mov_b32_e32 v150, v147
	v_mov_b32_e32 v148, v146
	v_pk_mul_f32 v[146:147], v[150:151], v[150:151]
	v_pk_fma_f32 v[144:145], v[190:191], v[190:191], v[144:145]
	v_pk_fma_f32 v[146:147], v[148:149], v[148:149], v[146:147]
	s_nop 0
	v_pk_add_f32 v[144:145], v[144:145], v[146:147]
	s_nop 0
	v_add_f32_e32 v144, v144, v145
	v_add_f32_e32 v236, v236, v144
; __device__ __forceinline__ unsigned cvt_pk_bf16(float lo, float hi) { unsigned r; asm volatile("v_cvt_pk_bf16_f32 %0, %1, %2" : "=v"(r) : "v"(lo), "v"(hi)); return r; }
; #define RES_LD(buf, pp) do { _Pragma("unroll") for (int j = 0; j < 2; ++j) { const int i_ = 2 * (pp) + j; const unsigned off_ = (row0 + (i_ >> 2) * HALF + (i_ & 3) * 16) * 1024u + col; \
;                 xq[buf][j][0] = *(const f32x4*)(xin + off_); xq[buf][j][1] = *(const f32x4*)(xin + off_ + 4); } } while (0)
;     static __device__ __forceinline__ void run(const f32x4 (&acc)[2][2][4][2], const Unit& u, int wr, int wc, int fr, int fq, const float* xin, float* xout, const float* gate, float gs, const float* lazy_ssq, const float* lazy_g, ...
;     ...
;             constexpr bool DEEP = !LAZY && !WG2;
;             if (DEEP) RES_LD(0, 0);
; #pragma unroll
;             for (int pp = 0; pp < 4; ++pp) {
;                 if (DEEP) { if (pp < 3) RES_LD((pp + 1) & 1, pp + 1); } else RES_LD(pp & 1, pp);
; #pragma unroll
;                 for (int j = 0; j < 2; ++j) { const int i_ = 2 * pp + j, ai = i_ >> 2, m = i_ & 3; const unsigned off = (row0 + ai * HALF + m * 16) * 1024u + col;
;                     const f32x4 xi0 = xq[pp & 1][j][0], xi1 = xq[pp & 1][j][1];
;                     f32x4 xo0 = gv[0] * acc[ai][bj][m][0], xo1 = gv[1] * acc[ai][bj][m][1];
;                     if (LAZY) { xo0 = xo0 + xi0 * lg[0] * rl[ai][m]; xo1 = xo1 + xi1 * lg[1] * rl[ai][m]; } else { xo0 = xo0 + xi0; xo1 = xo1 + xi1; }
;                     *(f32x4*)(xout + off) = xo0; *(f32x4*)(xout + off + 4) = xo1;
;                     if (aout) { const f32x4 a0 = xo0 * wv[0], a1 = xo1 * wv[1]; u32x4 w; w.x = cvt_pk_bf16(a0[0], a0[1]); w.y = cvt_pk_bf16(a0[2], a0[3]); w.z = cvt_pk_bf16(a1[0], a1[1]); w.w = cvt_pk_bf16(a1[2], a1[3]);
;                         *(u32x4*)(aout + off) = w;
;                         sq[ai][m] += ((xo0[0] * xo0[0] + xo0[1] * xo0[1]) + (xo0[2] * xo0[2] + xo0[3] * xo0[3])) + ((xo1[0] * xo1[0] + xo1[1] * xo1[1]) + (xo1[2] * xo1[2] + xo1[3] * xo1[3]));
;                         if (WG2) { const f32x4 b0 = xo0 * w2[0], b1 = xo1 * w2[1]; sqb[ai][m] += ((b0[0] * b0[0] + b0[1] * b0[1]) + (b0[2] * b0[2] + b0[3] * b0[3])) + ((b1[0] * b1[0] + b1[1] * b1[1]) + (b1[2] * b1[2] + b1[3] * b1[3])); } } }
.LBB0_349:
	v_mov_b32_e32 v213, v212
	s_waitcnt vmcnt(2)
	v_pk_mul_f32 v[142:143], v[130:131], v[142:143]
	v_pk_mul_f32 v[140:141], v[128:129], v[140:141]
	v_mov_b32_e32 v146, v212
	v_mov_b32_e32 v147, v212
	v_pk_mul_f32 v[138:139], v[134:135], v[138:139]
	v_pk_mul_f32 v[136:137], v[132:133], v[136:137]
	v_add_u32_e32 v144, 0x24000, v176
	v_pk_mul_f32 v[142:143], v[146:147], v[142:143]
	v_pk_mul_f32 v[140:141], v[212:213], v[140:141]
	v_pk_mul_f32 v[138:139], v[146:147], v[138:139]
	v_pk_mul_f32 v[136:137], v[212:213], v[136:137]
	v_mov_b32_e32 v145, v177
	v_pk_fma_f32 v[142:143], v[38:39], v[194:195], v[142:143]
	v_pk_fma_f32 v[140:141], v[36:37], v[198:199], v[140:141]
	v_pk_fma_f32 v[138:139], v[34:35], v[182:183], v[138:139]
	v_pk_fma_f32 v[136:137], v[32:33], v[192:193], v[136:137]
	v_lshl_add_u64 v[146:147], v[144:145], 2, s[30:31]
	s_and_b64 vcc, exec, s[8:9]
	global_store_dwordx4 v[146:147], v[140:143], off nt
	global_store_dwordx4 v[146:147], v[136:139], off offset:16 nt
	s_cbranch_vccnz .LBB0_351
	v_pk_mul_f32 v[148:149], v[188:189], v[142:143]
	v_pk_mul_f32 v[146:147], v[186:187], v[140:141]
	v_lshl_add_u64 v[144:145], v[144:145], 1, s[28:29]
	v_pk_mul_f32 v[150:151], v[180:181], v[138:139]
	v_pk_mul_f32 v[190:191], v[184:185], v[136:137]
	v_cvt_pk_bf16_f32 v146, v146, v147
	v_cvt_pk_bf16_f32 v147, v148, v149
	s_nop 0
	v_cvt_pk_bf16_f32 v148, v190, v191
	v_cvt_pk_bf16_f32 v149, v150, v151
	global_store_dwordx4 v[144:145], v[146:149], off
	v_mov_b32_e32 v145, v136
	v_mov_b32_e32 v136, v141
	v_mov_b32_e32 v141, v138
	v_mov_b32_e32 v138, v143
	v_mov_b32_e32 v144, v140
	v_pk_mul_f32 v[136:137], v[136:137], v[136:137]
	v_mov_b32_e32 v140, v142
	v_pk_mul_f32 v[138:139], v[138:139], v[138:139]
	v_pk_fma_f32 v[136:137], v[144:145], v[144:145], v[136:137]
	v_pk_fma_f32 v[138:139], v[140:141], v[140:141], v[138:139]
	s_nop 0
	v_pk_add_f32 v[136:137], v[136:137], v[138:139]
	s_nop 0
	v_add_f32_e32 v136, v136, v137
	v_add_f32_e32 v235, v235, v136
.LBB0_351:
	s_nop 0
	v_add_u32_e32 v136, 0x8000, v174
	v_mov_b32_e32 v137, v177
	v_lshl_add_u64 v[136:137], v[136:137], 2, s[34:35]
	global_load_dwordx4 v[148:151], v[136:137], off offset:16
	global_load_dwordx4 v[144:147], v[136:137], off
	v_add_u32_e32 v136, 0xc000, v174
	v_mov_b32_e32 v137, v177
	v_lshl_add_u64 v[140:141], v[136:137], 2, s[34:35]
	global_load_dwordx4 v[136:139], v[140:141], off offset:16
	s_nop 0
	global_load_dwordx4 v[140:143], v[140:141], off
	v_mov_b32_e32 v209, v208
	v_mov_b32_e32 v190, v208
	v_mov_b32_e32 v191, v208
	v_add_u32_e32 v174, 0x28000, v176
	v_mov_b32_e32 v175, v177
	s_and_b64 vcc, exec, s[8:9]
	s_waitcnt vmcnt(3)
	v_pk_mul_f32 v[150:151], v[134:135], v[150:151]
	s_waitcnt vmcnt(2)
	v_pk_mul_f32 v[146:147], v[130:131], v[146:147]
	v_pk_mul_f32 v[144:145], v[128:129], v[144:145]
	v_pk_mul_f32 v[148:149], v[132:133], v[148:149]
	v_pk_mul_f32 v[146:147], v[190:191], v[146:147]
	v_pk_mul_f32 v[144:145], v[208:209], v[144:145]
	v_pk_mul_f32 v[150:151], v[190:191], v[150:151]
	v_pk_mul_f32 v[148:149], v[208:209], v[148:149]
	v_pk_fma_f32 v[146:147], v[22:23], v[194:195], v[146:147]
	v_pk_fma_f32 v[144:145], v[20:21], v[198:199], v[144:145]
	v_pk_fma_f32 v[150:151], v[18:19], v[182:183], v[150:151]
	v_pk_fma_f32 v[148:149], v[16:17], v[192:193], v[148:149]
	v_lshl_add_u64 v[190:191], v[174:175], 2, s[30:31]
	global_store_dwordx4 v[190:191], v[144:147], off nt
	global_store_dwordx4 v[190:191], v[148:151], off offset:16 nt
	s_cbranch_vccnz .LBB0_353
	v_pk_mul_f32 v[202:203], v[184:185], v[148:149]
	v_lshl_add_u64 v[174:175], v[174:175], 1, s[28:29]
	v_pk_mul_f32 v[190:191], v[188:189], v[146:147]
	v_pk_mul_f32 v[196:197], v[186:187], v[144:145]
	v_pk_mul_f32 v[204:205], v[180:181], v[150:151]
	v_cvt_pk_bf16_f32 v200, v196, v197
	v_cvt_pk_bf16_f32 v201, v190, v191
	v_cvt_pk_bf16_f32 v202, v202, v203
	s_nop 0
	v_cvt_pk_bf16_f32 v203, v204, v205
	global_store_dwordx4 v[174:175], v[200:203], off
	v_mov_b32_e32 v175, v148
	v_mov_b32_e32 v148, v145
	v_mov_b32_e32 v174, v144
	v_pk_mul_f32 v[144:145], v[148:149], v[148:149]
	v_mov_b32_e32 v149, v150
	v_mov_b32_e32 v150, v147
	v_mov_b32_e32 v148, v146
	v_pk_mul_f32 v[146:147], v[150:151], v[150:151]
	v_pk_fma_f32 v[144:145], v[174:175], v[174:175], v[144:145]
	v_pk_fma_f32 v[146:147], v[148:149], v[148:149], v[146:147]
	s_nop 0
	v_pk_add_f32 v[144:145], v[144:145], v[146:147]
	s_nop 0
	v_add_f32_e32 v144, v144, v145
	v_add_f32_e32 v238, v238, v144
.LBB0_353:
	v_mov_b32_e32 v215, v214
	s_waitcnt vmcnt(2)
	v_pk_mul_f32 v[130:131], v[130:131], v[142:143]
	v_pk_mul_f32 v[128:129], v[128:129], v[140:141]
	v_mov_b32_e32 v140, v214
	v_mov_b32_e32 v141, v214
	v_pk_mul_f32 v[134:135], v[134:135], v[138:139]
	v_pk_mul_f32 v[132:133], v[132:133], v[136:137]
	v_add_u32_e32 v176, 0x2c000, v176
	v_pk_mul_f32 v[130:131], v[140:141], v[130:131]
	v_pk_mul_f32 v[128:129], v[214:215], v[128:129]
	v_pk_mul_f32 v[134:135], v[140:141], v[134:135]
	v_pk_mul_f32 v[132:133], v[214:215], v[132:133]
	v_pk_fma_f32 v[130:131], v[6:7], v[194:195], v[130:131]
	v_pk_fma_f32 v[128:129], v[4:5], v[198:199], v[128:129]
	v_pk_fma_f32 v[134:135], v[2:3], v[182:183], v[134:135]
	v_pk_fma_f32 v[132:133], v[0:1], v[192:193], v[132:133]
	v_lshl_add_u64 v[136:137], v[176:177], 2, s[30:31]
	s_and_b64 vcc, exec, s[8:9]
	global_store_dwordx4 v[136:137], v[128:131], off nt
	global_store_dwordx4 v[136:137], v[132:135], off offset:16 nt
	s_cbranch_vccnz .LBB0_355
	v_pk_mul_f32 v[138:139], v[188:189], v[130:131]
	v_pk_mul_f32 v[136:137], v[186:187], v[128:129]
	v_pk_mul_f32 v[140:141], v[180:181], v[134:135]
	v_pk_mul_f32 v[142:143], v[184:185], v[132:133]
	v_cvt_pk_bf16_f32 v136, v136, v137
	v_cvt_pk_bf16_f32 v137, v138, v139
	s_nop 0
	v_cvt_pk_bf16_f32 v138, v142, v143
	v_cvt_pk_bf16_f32 v139, v140, v141
	v_lshl_add_u64 v[140:141], v[176:177], 1, s[28:29]
	global_store_dwordx4 v[140:141], v[136:139], off
	s_nop 1
	v_mov_b32_e32 v137, v132
	v_mov_b32_e32 v132, v129
	v_mov_b32_e32 v136, v128
	v_pk_mul_f32 v[128:129], v[132:133], v[132:133]
	v_mov_b32_e32 v133, v134
	v_mov_b32_e32 v134, v131
	v_mov_b32_e32 v132, v130
	v_pk_mul_f32 v[130:131], v[134:135], v[134:135]
	v_pk_fma_f32 v[128:129], v[136:137], v[136:137], v[128:129]
	v_pk_fma_f32 v[130:131], v[132:133], v[132:133], v[130:131]
	s_nop 0
	v_pk_add_f32 v[128:129], v[128:129], v[130:131]
	s_nop 0
	v_add_f32_e32 v128, v128, v129
	v_add_f32_e32 v237, v237, v128

;     static __device__ __forceinline__ void run(const f32x4 (&acc)[2][2][4][2], const Unit& u, int wr, int wc, int fr, int fq, const float* xin, float* xout, const float* gate, float gs, const float* lazy_ssq, const float* lazy_g, ...
;     ...
;                 gv[n] = *(const f32x4*)(gate + (b * 9216u + col + 4 * n)) * gs;
;                 lg[n] = (f32x4){1.f, 1.f, 1.f, 1.f}; if (LAZY) lg[n] = *(const f32x4*)(lazy_g + col + 4 * n);
;                 wv[n] = (f32x4){0.f, 0.f, 0.f, 0.f}; w2[n] = (f32x4){1.f, 1.f, 1.f, 1.f};
;                 if (aout) { wv[n] = *(const f32x4*)(wg + col + 4 * n) * (*(const f32x4*)(wsc + (b * 9216u + col + 4 * n)) + 1.0f); if (WG2) { w2[n] = *(const f32x4*)(wg2 + col + 4 * n); wv[n] = wv[n] * w2[n]; } }
;             }
;             f32x4 xq[2][2][2];
;     ...
;             constexpr bool DEEP = !LAZY && !WG2;
;             if (DEEP) RES_LD(0, 0);
; #pragma unroll
;             for (int pp = 0; pp < 4; ++pp) {
;                 if (DEEP) { if (pp < 3) RES_LD((pp + 1) & 1, pp + 1); } else RES_LD(pp & 1, pp);
; #pragma unroll
;                 for (int j = 0; j < 2; ++j) { const int i_ = 2 * pp + j, ai = i_ >> 2, m = i_ & 3; const unsigned off = (row0 + ai * HALF + m * 16) * 1024u + col;
;                     const f32x4 xi0 = xq[pp & 1][j][0], xi1 = xq[pp & 1][j][1];
;                     f32x4 xo0 = gv[0] * acc[ai][bj][m][0], xo1 = gv[1] * acc[ai][bj][m][1];
;                     if (LAZY) { xo0 = xo0 + xi0 * lg[0] * rl[ai][m]; xo1 = xo1 + xi1 * lg[1] * rl[ai][m]; } else { xo0 = xo0 + xi0; xo1 = xo1 + xi1; }
;                     *(f32x4*)(xout + off) = xo0; *(f32x4*)(xout + off + 4) = xo1;
;                     if (aout) { const f32x4 a0 = xo0 * wv[0], a1 = xo1 * wv[1]; u32x4 w; w.x = cvt_pk_bf16(a0[0], a0[1]); w.y = cvt_pk_bf16(a0[2], a0[3]); w.z = cvt_pk_bf16(a1[0], a1[1]); w.w = cvt_pk_bf16(a1[2], a1[3]);
;                         *(u32x4*)(aout + off) = w;
;                         sq[ai][m] += ((xo0[0] * xo0[0] + xo0[1] * xo0[1]) + (xo0[2] * xo0[2] + xo0[3] * xo0[3])) + ((xo1[0] * xo1[0] + xo1[1] * xo1[1]) + (xo1[2] * xo1[2] + xo1[3] * xo1[3]));
;                         if (WG2) { const f32x4 b0 = xo0 * w2[0], b1 = xo1 * w2[1]; sqb[ai][m] += ((b0[0] * b0[0] + b0[1] * b0[1]) + (b0[2] * b0[2] + b0[3] * b0[3])) + ((b1[0] * b1[0] + b1[1] * b1[1]) + (b1[2] * b1[2] + b1[3] * b1[3])); } } }
.LBB0_381:
	s_lshl_b32 s67, s63, 8
	s_lshl_b32 s68, s65, 6
	s_add_i32 s68, s68, s67
	v_or_b32_e32 v152, s68, v230
	v_lshlrev_b32_e32 v153, 10, v152
	v_add_u32_e32 v176, v192, v153
	v_lshlrev_b64 v[154:155], 2, v[176:177]
	v_lshl_add_u64 v[140:141], s[38:39], 0, v[154:155]
	v_add_u32_e32 v156, 0x4000, v176
	v_mov_b32_e32 v157, v177
	global_load_dwordx4 v[172:175], v[140:141], off
	global_load_dwordx4 v[180:183], v[140:141], off offset:16
	v_lshl_add_u64 v[148:149], v[156:157], 2, s[38:39]
	global_load_dwordx4 v[140:143], v[148:149], off offset:16
	s_nop 0
	global_load_dwordx4 v[148:151], v[148:149], off
	s_waitcnt vmcnt(0)
	v_pk_mul_f32 v[202:203], s[40:41], v[146:147] op_sel_hi:[0,1]
	v_pk_mul_f32 v[200:201], s[40:41], v[144:145] op_sel_hi:[0,1]
	v_pk_mul_f32 v[204:205], s[40:41], v[138:139] op_sel_hi:[0,1]
	v_pk_mul_f32 v[206:207], s[40:41], v[136:137] op_sel_hi:[0,1]
	s_and_b64 vcc, exec, s[8:9]
	v_lshl_add_u64 v[154:155], s[36:37], 0, v[154:155]
	v_pk_fma_f32 v[146:147], v[126:127], v[204:205], v[174:175]
	v_pk_fma_f32 v[144:145], v[124:125], v[206:207], v[172:173]
	v_pk_fma_f32 v[138:139], v[122:123], v[202:203], v[182:183]
	v_pk_fma_f32 v[136:137], v[120:121], v[200:201], v[180:181]
	global_store_dwordx4 v[154:155], v[144:147], off nt
	global_store_dwordx4 v[154:155], v[136:139], off offset:16 nt
	s_cbranch_vccnz .LBB0_383
	v_pk_mul_f32 v[154:155], v[194:195], v[146:147]
	v_pk_mul_f32 v[158:159], v[186:187], v[144:145]
	v_pk_mul_f32 v[180:181], v[198:199], v[138:139]
	v_pk_mul_f32 v[174:175], v[196:197], v[136:137]
	v_cvt_pk_bf16_f32 v172, v158, v159
	v_cvt_pk_bf16_f32 v173, v154, v155
	v_lshl_add_u64 v[154:155], v[176:177], 1, s[34:35]
	v_pk_mul_f32 v[158:159], v[132:133], v[144:145]
	v_cvt_pk_bf16_f32 v174, v174, v175
	v_cvt_pk_bf16_f32 v175, v180, v181
	global_store_dwordx4 v[154:155], v[172:175], off
	v_pk_mul_f32 v[154:155], v[134:135], v[146:147]
	v_mov_b32_e32 v181, v158
	v_mov_b32_e32 v158, v145
	v_mov_b32_e32 v180, v144
	v_pk_mul_f32 v[144:145], v[158:159], v[158:159]
	v_mov_b32_e32 v159, v154
	v_mov_b32_e32 v154, v147
	v_mov_b32_e32 v158, v146
	v_pk_mul_f32 v[146:147], v[154:155], v[154:155]
	v_pk_mul_f32 v[174:175], v[128:129], v[136:137]
	v_pk_fma_f32 v[144:145], v[180:181], v[180:181], v[144:145]
	v_pk_fma_f32 v[146:147], v[158:159], v[158:159], v[146:147]
	v_pk_mul_f32 v[172:173], v[130:131], v[138:139]
	v_pk_add_f32 v[144:145], v[144:145], v[146:147]
	v_mov_b32_e32 v147, v174
	v_mov_b32_e32 v174, v137
	v_mov_b32_e32 v146, v136
	v_pk_mul_f32 v[136:137], v[174:175], v[174:175]
	s_nop 0
	v_pk_fma_f32 v[136:137], v[146:147], v[146:147], v[136:137]
	v_mov_b32_e32 v147, v172
	v_mov_b32_e32 v172, v139
	v_mov_b32_e32 v146, v138
	v_pk_mul_f32 v[138:139], v[172:173], v[172:173]
	s_nop 0
	v_pk_fma_f32 v[138:139], v[146:147], v[146:147], v[138:139]
	s_nop 0
	v_pk_add_f32 v[136:137], v[136:137], v[138:139]
	s_nop 0
	v_pk_add_f32 v[154:155], v[144:145], v[136:137]
	s_branch .LBB0_384

; __device__ __forceinline__ unsigned cvt_pk_bf16(float lo, float hi) { unsigned r; asm volatile("v_cvt_pk_bf16_f32 %0, %1, %2" : "=v"(r) : "v"(lo), "v"(hi)); return r; }
;     static __device__ __forceinline__ void run(const f32x4 (&acc)[2][2][4][2], const Unit& u, int wr, int wc, int fr, int fq, const float* xin, float* xout, const float* gate, float gs, const float* lazy_ssq, const float* lazy_g, ...
;     ...
;                 for (int j = 0; j < 2; ++j) { const int i_ = 2 * pp + j, ai = i_ >> 2, m = i_ & 3; const unsigned off = (row0 + ai * HALF + m * 16) * 1024u + col;
;                     const f32x4 xi0 = xq[pp & 1][j][0], xi1 = xq[pp & 1][j][1];
;                     f32x4 xo0 = gv[0] * acc[ai][bj][m][0], xo1 = gv[1] * acc[ai][bj][m][1];
;                     if (LAZY) { xo0 = xo0 + xi0 * lg[0] * rl[ai][m]; xo1 = xo1 + xi1 * lg[1] * rl[ai][m]; } else { xo0 = xo0 + xi0; xo1 = xo1 + xi1; }
;                     *(f32x4*)(xout + off) = xo0; *(f32x4*)(xout + off + 4) = xo1;
;                     if (aout) { const f32x4 a0 = xo0 * wv[0], a1 = xo1 * wv[1]; u32x4 w; w.x = cvt_pk_bf16(a0[0], a0[1]); w.y = cvt_pk_bf16(a0[2], a0[3]); w.z = cvt_pk_bf16(a1[0], a1[1]); w.w = cvt_pk_bf16(a1[2], a1[3]);
;                         *(u32x4*)(aout + off) = w;
;                         sq[ai][m] += ((xo0[0] * xo0[0] + xo0[1] * xo0[1]) + (xo0[2] * xo0[2] + xo0[3] * xo0[3])) + ((xo1[0] * xo1[0] + xo1[1] * xo1[1]) + (xo1[2] * xo1[2] + xo1[3] * xo1[3]));
;                         if (WG2) { const f32x4 b0 = xo0 * w2[0], b1 = xo1 * w2[1]; sqb[ai][m] += ((b0[0] * b0[0] + b0[1] * b0[1]) + (b0[2] * b0[2] + b0[3] * b0[3])) + ((b1[0] * b1[0] + b1[1] * b1[1]) + (b1[2] * b1[2] + b1[3] * b1[3])); } } }
.LBB0_384:
	v_pk_fma_f32 v[146:147], v[110:111], v[204:205], v[150:151]
	v_pk_fma_f32 v[144:145], v[108:109], v[206:207], v[148:149]
	v_pk_fma_f32 v[138:139], v[106:107], v[202:203], v[142:143]
	v_pk_fma_f32 v[136:137], v[104:105], v[200:201], v[140:141]
	v_lshl_add_u64 v[140:141], v[156:157], 2, s[36:37]
	s_and_b64 vcc, exec, s[8:9]
	global_store_dwordx4 v[140:141], v[144:147], off nt
	global_store_dwordx4 v[140:141], v[136:139], off offset:16 nt
	s_cbranch_vccnz .LBB0_386
	v_pk_mul_f32 v[142:143], v[194:195], v[146:147]
	v_pk_mul_f32 v[140:141], v[186:187], v[144:145]
	v_pk_mul_f32 v[148:149], v[198:199], v[138:139]
	v_pk_mul_f32 v[150:151], v[196:197], v[136:137]
	v_cvt_pk_bf16_f32 v140, v140, v141
	v_cvt_pk_bf16_f32 v141, v142, v143
	s_nop 0
	v_cvt_pk_bf16_f32 v142, v150, v151
	v_cvt_pk_bf16_f32 v143, v148, v149
	v_lshl_add_u64 v[148:149], v[156:157], 1, s[34:35]
	global_store_dwordx4 v[148:149], v[140:143], off
	v_mov_b32_e32 v156, v144
	v_pk_mul_f32 v[150:151], v[128:129], v[136:137]
	v_pk_mul_f32 v[140:141], v[134:135], v[146:147]
	v_pk_mul_f32 v[142:143], v[132:133], v[144:145]
	v_mov_b32_e32 v144, v146
	v_mov_b32_e32 v157, v142
	v_mov_b32_e32 v142, v145
	v_mov_b32_e32 v145, v140
	v_mov_b32_e32 v140, v147
	v_pk_mul_f32 v[142:143], v[142:143], v[142:143]
	v_pk_mul_f32 v[140:141], v[140:141], v[140:141]
	v_pk_fma_f32 v[142:143], v[156:157], v[156:157], v[142:143]
	v_pk_fma_f32 v[140:141], v[144:145], v[144:145], v[140:141]
	v_pk_mul_f32 v[148:149], v[130:131], v[138:139]
	v_pk_add_f32 v[140:141], v[142:143], v[140:141]
	v_mov_b32_e32 v143, v150
	v_mov_b32_e32 v150, v137
	v_mov_b32_e32 v142, v136
	v_pk_mul_f32 v[136:137], v[150:151], v[150:151]
	s_nop 0
	v_pk_fma_f32 v[136:137], v[142:143], v[142:143], v[136:137]
	v_mov_b32_e32 v143, v148
	v_mov_b32_e32 v148, v139
	v_mov_b32_e32 v142, v138
	v_pk_mul_f32 v[138:139], v[148:149], v[148:149]
	s_nop 0
	v_pk_fma_f32 v[138:139], v[142:143], v[142:143], v[138:139]
	s_nop 0
	v_pk_add_f32 v[136:137], v[136:137], v[138:139]
	s_nop 0
	v_pk_add_f32 v[156:157], v[140:141], v[136:137]
	s_branch .LBB0_387

; __device__ __forceinline__ unsigned cvt_pk_bf16(float lo, float hi) { unsigned r; asm volatile("v_cvt_pk_bf16_f32 %0, %1, %2" : "=v"(r) : "v"(lo), "v"(hi)); return r; }
; #define RES_LD(buf, pp) do { _Pragma("unroll") for (int j = 0; j < 2; ++j) { const int i_ = 2 * (pp) + j; const unsigned off_ = (row0 + (i_ >> 2) * HALF + (i_ & 3) * 16) * 1024u + col; \
;                 xq[buf][j][0] = *(const f32x4*)(xin + off_); xq[buf][j][1] = *(const f32x4*)(xin + off_ + 4); } } while (0)
;     static __device__ __forceinline__ void run(const f32x4 (&acc)[2][2][4][2], const Unit& u, int wr, int wc, int fr, int fq, const float* xin, float* xout, const float* gate, float gs, const float* lazy_ssq, const float* lazy_g, ...
;     ...
;             constexpr bool DEEP = !LAZY && !WG2;
;             if (DEEP) RES_LD(0, 0);
; #pragma unroll
;             for (int pp = 0; pp < 4; ++pp) {
;                 if (DEEP) { if (pp < 3) RES_LD((pp + 1) & 1, pp + 1); } else RES_LD(pp & 1, pp);
; #pragma unroll
;                 for (int j = 0; j < 2; ++j) { const int i_ = 2 * pp + j, ai = i_ >> 2, m = i_ & 3; const unsigned off = (row0 + ai * HALF + m * 16) * 1024u + col;
;                     const f32x4 xi0 = xq[pp & 1][j][0], xi1 = xq[pp & 1][j][1];
;                     f32x4 xo0 = gv[0] * acc[ai][bj][m][0], xo1 = gv[1] * acc[ai][bj][m][1];
;                     if (LAZY) { xo0 = xo0 + xi0 * lg[0] * rl[ai][m]; xo1 = xo1 + xi1 * lg[1] * rl[ai][m]; } else { xo0 = xo0 + xi0; xo1 = xo1 + xi1; }
;                     *(f32x4*)(xout + off) = xo0; *(f32x4*)(xout + off + 4) = xo1;
;                     if (aout) { const f32x4 a0 = xo0 * wv[0], a1 = xo1 * wv[1]; u32x4 w; w.x = cvt_pk_bf16(a0[0], a0[1]); w.y = cvt_pk_bf16(a0[2], a0[3]); w.z = cvt_pk_bf16(a1[0], a1[1]); w.w = cvt_pk_bf16(a1[2], a1[3]);
;                         *(u32x4*)(aout + off) = w;
;                         sq[ai][m] += ((xo0[0] * xo0[0] + xo0[1] * xo0[1]) + (xo0[2] * xo0[2] + xo0[3] * xo0[3])) + ((xo1[0] * xo1[0] + xo1[1] * xo1[1]) + (xo1[2] * xo1[2] + xo1[3] * xo1[3]));
;                         if (WG2) { const f32x4 b0 = xo0 * w2[0], b1 = xo1 * w2[1]; sqb[ai][m] += ((b0[0] * b0[0] + b0[1] * b0[1]) + (b0[2] * b0[2] + b0[3] * b0[3])) + ((b1[0] * b1[0] + b1[1] * b1[1]) + (b1[2] * b1[2] + b1[3] * b1[3])); } } }
.LBB0_387:
	v_add_u32_e32 v158, 0x8000, v176
	v_mov_b32_e32 v159, v177
	v_lshlrev_b64 v[148:149], 2, v[158:159]
	v_lshl_add_u64 v[136:137], s[38:39], 0, v[148:149]
	v_add_u32_e32 v172, 0xc000, v176
	v_mov_b32_e32 v173, v177
	global_load_dwordx4 v[144:147], v[136:137], off
	global_load_dwordx4 v[180:183], v[136:137], off offset:16
	v_lshl_add_u64 v[140:141], v[172:173], 2, s[38:39]
	global_load_dwordx4 v[136:139], v[140:141], off offset:16
	s_nop 0
	global_load_dwordx4 v[140:143], v[140:141], off
	s_and_b64 vcc, exec, s[8:9]
	v_lshl_add_u64 v[174:175], s[36:37], 0, v[148:149]
	s_waitcnt vmcnt(3)
	v_pk_fma_f32 v[150:151], v[94:95], v[204:205], v[146:147]
	v_pk_fma_f32 v[148:149], v[92:93], v[206:207], v[144:145]
	s_waitcnt vmcnt(2)
	v_pk_fma_f32 v[146:147], v[90:91], v[202:203], v[182:183]
	v_pk_fma_f32 v[144:145], v[88:89], v[200:201], v[180:181]
	global_store_dwordx4 v[174:175], v[148:151], off nt
	global_store_dwordx4 v[174:175], v[144:147], off offset:16 nt
	s_cbranch_vccnz .LBB0_389
	v_pk_mul_f32 v[174:175], v[194:195], v[150:151]
	v_pk_mul_f32 v[180:181], v[186:187], v[148:149]
	v_pk_mul_f32 v[184:185], v[198:199], v[146:147]
	v_pk_mul_f32 v[182:183], v[196:197], v[144:145]
	v_cvt_pk_bf16_f32 v180, v180, v181
	v_cvt_pk_bf16_f32 v181, v174, v175
	v_lshl_add_u64 v[158:159], v[158:159], 1, s[34:35]
	v_pk_mul_f32 v[174:175], v[132:133], v[148:149]
	v_cvt_pk_bf16_f32 v182, v182, v183
	v_cvt_pk_bf16_f32 v183, v184, v185
	global_store_dwordx4 v[158:159], v[180:183], off
	v_pk_mul_f32 v[158:159], v[134:135], v[150:151]
	v_mov_b32_e32 v185, v174
	v_mov_b32_e32 v174, v149
	v_mov_b32_e32 v184, v148
	v_pk_mul_f32 v[148:149], v[174:175], v[174:175]
	v_mov_b32_e32 v175, v158
	v_mov_b32_e32 v158, v151
	v_mov_b32_e32 v174, v150
	v_pk_mul_f32 v[150:151], v[158:159], v[158:159]
	v_pk_mul_f32 v[182:183], v[128:129], v[144:145]
	v_pk_fma_f32 v[148:149], v[184:185], v[184:185], v[148:149]
	v_pk_fma_f32 v[150:151], v[174:175], v[174:175], v[150:151]
	v_pk_mul_f32 v[180:181], v[130:131], v[146:147]
	v_pk_add_f32 v[148:149], v[148:149], v[150:151]
	v_mov_b32_e32 v151, v182
	v_mov_b32_e32 v182, v145
	v_mov_b32_e32 v150, v144
	v_pk_mul_f32 v[144:145], v[182:183], v[182:183]
	s_nop 0
	v_pk_fma_f32 v[144:145], v[150:151], v[150:151], v[144:145]
	v_mov_b32_e32 v151, v180
	v_mov_b32_e32 v180, v147
	v_mov_b32_e32 v150, v146
	v_pk_mul_f32 v[146:147], v[180:181], v[180:181]
	s_nop 0
	v_pk_fma_f32 v[146:147], v[150:151], v[150:151], v[146:147]
	s_nop 0
	v_pk_add_f32 v[144:145], v[144:145], v[146:147]
	s_nop 0
	v_pk_add_f32 v[158:159], v[148:149], v[144:145]
	s_branch .LBB0_390

; __device__ __forceinline__ unsigned cvt_pk_bf16(float lo, float hi) { unsigned r; asm volatile("v_cvt_pk_bf16_f32 %0, %1, %2" : "=v"(r) : "v"(lo), "v"(hi)); return r; }
;     static __device__ __forceinline__ void run(const f32x4 (&acc)[2][2][4][2], const Unit& u, int wr, int wc, int fr, int fq, const float* xin, float* xout, const float* gate, float gs, const float* lazy_ssq, const float* lazy_g, ...
;     ...
;                 for (int j = 0; j < 2; ++j) { const int i_ = 2 * pp + j, ai = i_ >> 2, m = i_ & 3; const unsigned off = (row0 + ai * HALF + m * 16) * 1024u + col;
;                     const f32x4 xi0 = xq[pp & 1][j][0], xi1 = xq[pp & 1][j][1];
;                     f32x4 xo0 = gv[0] * acc[ai][bj][m][0], xo1 = gv[1] * acc[ai][bj][m][1];
;                     if (LAZY) { xo0 = xo0 + xi0 * lg[0] * rl[ai][m]; xo1 = xo1 + xi1 * lg[1] * rl[ai][m]; } else { xo0 = xo0 + xi0; xo1 = xo1 + xi1; }
;                     *(f32x4*)(xout + off) = xo0; *(f32x4*)(xout + off + 4) = xo1;
;                     if (aout) { const f32x4 a0 = xo0 * wv[0], a1 = xo1 * wv[1]; u32x4 w; w.x = cvt_pk_bf16(a0[0], a0[1]); w.y = cvt_pk_bf16(a0[2], a0[3]); w.z = cvt_pk_bf16(a1[0], a1[1]); w.w = cvt_pk_bf16(a1[2], a1[3]);
;                         *(u32x4*)(aout + off) = w;
;                         sq[ai][m] += ((xo0[0] * xo0[0] + xo0[1] * xo0[1]) + (xo0[2] * xo0[2] + xo0[3] * xo0[3])) + ((xo1[0] * xo1[0] + xo1[1] * xo1[1]) + (xo1[2] * xo1[2] + xo1[3] * xo1[3]));
;                         if (WG2) { const f32x4 b0 = xo0 * w2[0], b1 = xo1 * w2[1]; sqb[ai][m] += ((b0[0] * b0[0] + b0[1] * b0[1]) + (b0[2] * b0[2] + b0[3] * b0[3])) + ((b1[0] * b1[0] + b1[1] * b1[1]) + (b1[2] * b1[2] + b1[3] * b1[3])); } } }
.LBB0_390:
	s_waitcnt vmcnt(2)
	v_pk_fma_f32 v[142:143], v[78:79], v[204:205], v[142:143]
	v_pk_fma_f32 v[140:141], v[76:77], v[206:207], v[140:141]
	v_pk_fma_f32 v[138:139], v[74:75], v[202:203], v[138:139]
	v_pk_fma_f32 v[136:137], v[72:73], v[200:201], v[136:137]
	v_lshl_add_u64 v[144:145], v[172:173], 2, s[36:37]
	s_and_b64 vcc, exec, s[8:9]
	global_store_dwordx4 v[144:145], v[140:143], off nt
	global_store_dwordx4 v[144:145], v[136:139], off offset:16 nt
	s_cbranch_vccnz .LBB0_392
	v_pk_mul_f32 v[146:147], v[194:195], v[142:143]
	v_pk_mul_f32 v[144:145], v[186:187], v[140:141]
	v_pk_mul_f32 v[148:149], v[198:199], v[138:139]
	v_pk_mul_f32 v[150:151], v[196:197], v[136:137]
	v_cvt_pk_bf16_f32 v144, v144, v145
	v_cvt_pk_bf16_f32 v145, v146, v147
	s_nop 0
	v_cvt_pk_bf16_f32 v146, v150, v151
	v_cvt_pk_bf16_f32 v147, v148, v149
	v_lshl_add_u64 v[148:149], v[172:173], 1, s[34:35]
	global_store_dwordx4 v[148:149], v[144:147], off
	v_mov_b32_e32 v172, v140
	v_pk_mul_f32 v[150:151], v[128:129], v[136:137]
	v_pk_mul_f32 v[146:147], v[132:133], v[140:141]
	v_pk_mul_f32 v[144:145], v[134:135], v[142:143]
	v_mov_b32_e32 v173, v146
	v_mov_b32_e32 v146, v141
	v_pk_mul_f32 v[140:141], v[146:147], v[146:147]
	v_mov_b32_e32 v147, v144
	v_mov_b32_e32 v144, v143
	v_mov_b32_e32 v146, v142
	v_pk_mul_f32 v[142:143], v[144:145], v[144:145]
	v_pk_fma_f32 v[140:141], v[172:173], v[172:173], v[140:141]
	v_pk_fma_f32 v[142:143], v[146:147], v[146:147], v[142:143]
	v_pk_mul_f32 v[148:149], v[130:131], v[138:139]
	v_pk_add_f32 v[140:141], v[140:141], v[142:143]
	v_mov_b32_e32 v143, v150
	v_mov_b32_e32 v150, v137
	v_mov_b32_e32 v142, v136
	v_pk_mul_f32 v[136:137], v[150:151], v[150:151]
	s_nop 0
	v_pk_fma_f32 v[136:137], v[142:143], v[142:143], v[136:137]
	v_mov_b32_e32 v143, v148
	v_mov_b32_e32 v148, v139
	v_mov_b32_e32 v142, v138
	v_pk_mul_f32 v[138:139], v[148:149], v[148:149]
	s_nop 0
	v_pk_fma_f32 v[138:139], v[142:143], v[142:143], v[138:139]
	s_nop 0
	v_pk_add_f32 v[136:137], v[136:137], v[138:139]
	s_nop 0
	v_pk_add_f32 v[174:175], v[140:141], v[136:137]
	s_branch .LBB0_393

; __device__ __forceinline__ unsigned cvt_pk_bf16(float lo, float hi) { unsigned r; asm volatile("v_cvt_pk_bf16_f32 %0, %1, %2" : "=v"(r) : "v"(lo), "v"(hi)); return r; }
; #define RES_LD(buf, pp) do { _Pragma("unroll") for (int j = 0; j < 2; ++j) { const int i_ = 2 * (pp) + j; const unsigned off_ = (row0 + (i_ >> 2) * HALF + (i_ & 3) * 16) * 1024u + col; \
;                 xq[buf][j][0] = *(const f32x4*)(xin + off_); xq[buf][j][1] = *(const f32x4*)(xin + off_ + 4); } } while (0)
;     static __device__ __forceinline__ void run(const f32x4 (&acc)[2][2][4][2], const Unit& u, int wr, int wc, int fr, int fq, const float* xin, float* xout, const float* gate, float gs, const float* lazy_ssq, const float* lazy_g, ...
;     ...
;             constexpr bool DEEP = !LAZY && !WG2;
;             if (DEEP) RES_LD(0, 0);
; #pragma unroll
;             for (int pp = 0; pp < 4; ++pp) {
;                 if (DEEP) { if (pp < 3) RES_LD((pp + 1) & 1, pp + 1); } else RES_LD(pp & 1, pp);
; #pragma unroll
;                 for (int j = 0; j < 2; ++j) { const int i_ = 2 * pp + j, ai = i_ >> 2, m = i_ & 3; const unsigned off = (row0 + ai * HALF + m * 16) * 1024u + col;
;                     const f32x4 xi0 = xq[pp & 1][j][0], xi1 = xq[pp & 1][j][1];
;                     f32x4 xo0 = gv[0] * acc[ai][bj][m][0], xo1 = gv[1] * acc[ai][bj][m][1];
;                     if (LAZY) { xo0 = xo0 + xi0 * lg[0] * rl[ai][m]; xo1 = xo1 + xi1 * lg[1] * rl[ai][m]; } else { xo0 = xo0 + xi0; xo1 = xo1 + xi1; }
;                     *(f32x4*)(xout + off) = xo0; *(f32x4*)(xout + off + 4) = xo1;
;                     if (aout) { const f32x4 a0 = xo0 * wv[0], a1 = xo1 * wv[1]; u32x4 w; w.x = cvt_pk_bf16(a0[0], a0[1]); w.y = cvt_pk_bf16(a0[2], a0[3]); w.z = cvt_pk_bf16(a1[0], a1[1]); w.w = cvt_pk_bf16(a1[2], a1[3]);
;                         *(u32x4*)(aout + off) = w;
;                         sq[ai][m] += ((xo0[0] * xo0[0] + xo0[1] * xo0[1]) + (xo0[2] * xo0[2] + xo0[3] * xo0[3])) + ((xo1[0] * xo1[0] + xo1[1] * xo1[1]) + (xo1[2] * xo1[2] + xo1[3] * xo1[3]));
;                         if (WG2) { const f32x4 b0 = xo0 * w2[0], b1 = xo1 * w2[1]; sqb[ai][m] += ((b0[0] * b0[0] + b0[1] * b0[1]) + (b0[2] * b0[2] + b0[3] * b0[3])) + ((b1[0] * b1[0] + b1[1] * b1[1]) + (b1[2] * b1[2] + b1[3] * b1[3])); } } }
.LBB0_393:
	v_add_u32_e32 v172, 0x80, v152
	v_lshlrev_b32_e32 v173, 10, v172
	v_add_u32_e32 v184, v173, v192
	v_mov_b32_e32 v185, v177
	v_lshl_add_u64 v[136:137], v[184:185], 2, s[38:39]
	global_load_dwordx4 v[144:147], v[136:137], off offset:16
	global_load_dwordx4 v[148:151], v[136:137], off
	v_add_u32_e32 v136, 0x4000, v184
	v_mov_b32_e32 v137, v177
	v_lshl_add_u64 v[140:141], v[136:137], 2, s[38:39]
	global_load_dwordx4 v[136:139], v[140:141], off offset:16
	s_nop 0
	global_load_dwordx4 v[140:143], v[140:141], off
	v_add_u32_e32 v180, 0x20000, v176
	v_mov_b32_e32 v181, v177
	v_lshl_add_u64 v[182:183], v[180:181], 2, s[36:37]
	s_and_b64 vcc, exec, s[8:9]
	s_waitcnt vmcnt(3)
	v_pk_fma_f32 v[146:147], v[58:59], v[202:203], v[146:147]
	s_waitcnt vmcnt(2)
	v_pk_fma_f32 v[150:151], v[62:63], v[204:205], v[150:151]
	v_pk_fma_f32 v[148:149], v[60:61], v[206:207], v[148:149]
	v_pk_fma_f32 v[144:145], v[56:57], v[200:201], v[144:145]
	global_store_dwordx4 v[182:183], v[148:151], off nt
	global_store_dwordx4 v[182:183], v[144:147], off offset:16 nt
	s_cbranch_vccnz .LBB0_395
	v_pk_mul_f32 v[182:183], v[194:195], v[150:151]
	v_pk_mul_f32 v[208:209], v[186:187], v[148:149]
	v_pk_mul_f32 v[212:213], v[198:199], v[146:147]
	v_pk_mul_f32 v[210:211], v[196:197], v[144:145]
	v_cvt_pk_bf16_f32 v208, v208, v209
	v_cvt_pk_bf16_f32 v209, v182, v183
	v_lshl_add_u64 v[180:181], v[180:181], 1, s[34:35]
	v_pk_mul_f32 v[182:183], v[132:133], v[148:149]
	v_cvt_pk_bf16_f32 v210, v210, v211
	v_cvt_pk_bf16_f32 v211, v212, v213
	global_store_dwordx4 v[180:181], v[208:211], off
	v_pk_mul_f32 v[180:181], v[134:135], v[150:151]
	v_mov_b32_e32 v213, v182
	v_mov_b32_e32 v182, v149
	v_mov_b32_e32 v212, v148
	v_pk_mul_f32 v[148:149], v[182:183], v[182:183]
	v_mov_b32_e32 v183, v180
	v_mov_b32_e32 v180, v151
	v_mov_b32_e32 v182, v150
	v_pk_mul_f32 v[150:151], v[180:181], v[180:181]
	v_pk_mul_f32 v[210:211], v[128:129], v[144:145]
	v_pk_fma_f32 v[148:149], v[212:213], v[212:213], v[148:149]
	v_pk_fma_f32 v[150:151], v[182:183], v[182:183], v[150:151]
	v_pk_mul_f32 v[208:209], v[130:131], v[146:147]
	v_pk_add_f32 v[148:149], v[148:149], v[150:151]
	v_mov_b32_e32 v151, v210
	v_mov_b32_e32 v210, v145
	v_mov_b32_e32 v150, v144
	v_pk_mul_f32 v[144:145], v[210:211], v[210:211]
	s_nop 0
	v_pk_fma_f32 v[144:145], v[150:151], v[150:151], v[144:145]
	v_mov_b32_e32 v151, v208
	v_mov_b32_e32 v208, v147
	v_mov_b32_e32 v150, v146
	v_pk_mul_f32 v[146:147], v[208:209], v[208:209]
	s_nop 0
	v_pk_fma_f32 v[146:147], v[150:151], v[150:151], v[146:147]
	s_nop 0
	v_pk_add_f32 v[144:145], v[144:145], v[146:147]
	s_nop 0
	v_pk_add_f32 v[180:181], v[148:149], v[144:145]
	s_branch .LBB0_396

; __device__ __forceinline__ unsigned cvt_pk_bf16(float lo, float hi) { unsigned r; asm volatile("v_cvt_pk_bf16_f32 %0, %1, %2" : "=v"(r) : "v"(lo), "v"(hi)); return r; }
;     static __device__ __forceinline__ void run(const f32x4 (&acc)[2][2][4][2], const Unit& u, int wr, int wc, int fr, int fq, const float* xin, float* xout, const float* gate, float gs, const float* lazy_ssq, const float* lazy_g, ...
;     ...
;                 for (int j = 0; j < 2; ++j) { const int i_ = 2 * pp + j, ai = i_ >> 2, m = i_ & 3; const unsigned off = (row0 + ai * HALF + m * 16) * 1024u + col;
;                     const f32x4 xi0 = xq[pp & 1][j][0], xi1 = xq[pp & 1][j][1];
;                     f32x4 xo0 = gv[0] * acc[ai][bj][m][0], xo1 = gv[1] * acc[ai][bj][m][1];
;                     if (LAZY) { xo0 = xo0 + xi0 * lg[0] * rl[ai][m]; xo1 = xo1 + xi1 * lg[1] * rl[ai][m]; } else { xo0 = xo0 + xi0; xo1 = xo1 + xi1; }
;                     *(f32x4*)(xout + off) = xo0; *(f32x4*)(xout + off + 4) = xo1;
;                     if (aout) { const f32x4 a0 = xo0 * wv[0], a1 = xo1 * wv[1]; u32x4 w; w.x = cvt_pk_bf16(a0[0], a0[1]); w.y = cvt_pk_bf16(a0[2], a0[3]); w.z = cvt_pk_bf16(a1[0], a1[1]); w.w = cvt_pk_bf16(a1[2], a1[3]);
;                         *(u32x4*)(aout + off) = w;
;                         sq[ai][m] += ((xo0[0] * xo0[0] + xo0[1] * xo0[1]) + (xo0[2] * xo0[2] + xo0[3] * xo0[3])) + ((xo1[0] * xo1[0] + xo1[1] * xo1[1]) + (xo1[2] * xo1[2] + xo1[3] * xo1[3]));
;                         if (WG2) { const f32x4 b0 = xo0 * w2[0], b1 = xo1 * w2[1]; sqb[ai][m] += ((b0[0] * b0[0] + b0[1] * b0[1]) + (b0[2] * b0[2] + b0[3] * b0[3])) + ((b1[0] * b1[0] + b1[1] * b1[1]) + (b1[2] * b1[2] + b1[3] * b1[3])); } } }
.LBB0_396:
	v_add_u32_e32 v144, 0x24000, v176
	v_mov_b32_e32 v145, v177
	s_waitcnt vmcnt(2)
	v_pk_fma_f32 v[142:143], v[46:47], v[204:205], v[142:143]
	v_pk_fma_f32 v[140:141], v[44:45], v[206:207], v[140:141]
	v_pk_fma_f32 v[138:139], v[42:43], v[202:203], v[138:139]
	v_pk_fma_f32 v[136:137], v[40:41], v[200:201], v[136:137]
	v_lshl_add_u64 v[146:147], v[144:145], 2, s[36:37]
	s_and_b64 vcc, exec, s[8:9]
	global_store_dwordx4 v[146:147], v[140:143], off nt
	global_store_dwordx4 v[146:147], v[136:139], off offset:16 nt
	s_cbranch_vccnz .LBB0_398
	v_pk_mul_f32 v[146:147], v[186:187], v[140:141]
	v_pk_mul_f32 v[148:149], v[194:195], v[142:143]
	v_cvt_pk_bf16_f32 v146, v146, v147
	v_lshl_add_u64 v[144:145], v[144:145], 1, s[34:35]
	v_cvt_pk_bf16_f32 v147, v148, v149
	v_pk_mul_f32 v[150:151], v[198:199], v[138:139]
	v_pk_mul_f32 v[182:183], v[196:197], v[136:137]
	s_nop 0
	v_cvt_pk_bf16_f32 v148, v182, v183
	v_cvt_pk_bf16_f32 v149, v150, v151
	global_store_dwordx4 v[144:145], v[146:149], off
	v_pk_mul_f32 v[144:145], v[134:135], v[142:143]
	v_mov_b32_e32 v182, v140
	v_pk_mul_f32 v[146:147], v[132:133], v[140:141]
	v_pk_mul_f32 v[150:151], v[128:129], v[136:137]
	v_mov_b32_e32 v183, v146
	v_mov_b32_e32 v146, v141
	v_pk_mul_f32 v[140:141], v[146:147], v[146:147]
	v_mov_b32_e32 v147, v144
	v_mov_b32_e32 v144, v143
	v_mov_b32_e32 v146, v142
	v_pk_mul_f32 v[142:143], v[144:145], v[144:145]
	v_pk_fma_f32 v[140:141], v[182:183], v[182:183], v[140:141]
	v_pk_fma_f32 v[142:143], v[146:147], v[146:147], v[142:143]
	v_pk_mul_f32 v[148:149], v[130:131], v[138:139]
	v_pk_add_f32 v[140:141], v[140:141], v[142:143]
	v_mov_b32_e32 v143, v150
	v_mov_b32_e32 v150, v137
	v_mov_b32_e32 v142, v136
	v_pk_mul_f32 v[136:137], v[150:151], v[150:151]
	s_nop 0
	v_pk_fma_f32 v[136:137], v[142:143], v[142:143], v[136:137]
	v_mov_b32_e32 v143, v148
	v_mov_b32_e32 v148, v139
	v_mov_b32_e32 v142, v138
	v_pk_mul_f32 v[138:139], v[148:149], v[148:149]
	s_nop 0
	v_pk_fma_f32 v[138:139], v[142:143], v[142:143], v[138:139]
	s_nop 0
	v_pk_add_f32 v[136:137], v[136:137], v[138:139]
	s_nop 0
	v_pk_add_f32 v[182:183], v[140:141], v[136:137]
	s_branch .LBB0_399

; __device__ __forceinline__ unsigned cvt_pk_bf16(float lo, float hi) { unsigned r; asm volatile("v_cvt_pk_bf16_f32 %0, %1, %2" : "=v"(r) : "v"(lo), "v"(hi)); return r; }
; #define RES_LD(buf, pp) do { _Pragma("unroll") for (int j = 0; j < 2; ++j) { const int i_ = 2 * (pp) + j; const unsigned off_ = (row0 + (i_ >> 2) * HALF + (i_ & 3) * 16) * 1024u + col; \
;                 xq[buf][j][0] = *(const f32x4*)(xin + off_); xq[buf][j][1] = *(const f32x4*)(xin + off_ + 4); } } while (0)
;     static __device__ __forceinline__ void run(const f32x4 (&acc)[2][2][4][2], const Unit& u, int wr, int wc, int fr, int fq, const float* xin, float* xout, const float* gate, float gs, const float* lazy_ssq, const float* lazy_g, ...
;     ...
;             constexpr bool DEEP = !LAZY && !WG2;
;             if (DEEP) RES_LD(0, 0);
; #pragma unroll
;             for (int pp = 0; pp < 4; ++pp) {
;                 if (DEEP) { if (pp < 3) RES_LD((pp + 1) & 1, pp + 1); } else RES_LD(pp & 1, pp);
; #pragma unroll
;                 for (int j = 0; j < 2; ++j) { const int i_ = 2 * pp + j, ai = i_ >> 2, m = i_ & 3; const unsigned off = (row0 + ai * HALF + m * 16) * 1024u + col;
;                     const f32x4 xi0 = xq[pp & 1][j][0], xi1 = xq[pp & 1][j][1];
;                     f32x4 xo0 = gv[0] * acc[ai][bj][m][0], xo1 = gv[1] * acc[ai][bj][m][1];
;                     if (LAZY) { xo0 = xo0 + xi0 * lg[0] * rl[ai][m]; xo1 = xo1 + xi1 * lg[1] * rl[ai][m]; } else { xo0 = xo0 + xi0; xo1 = xo1 + xi1; }
;                     *(f32x4*)(xout + off) = xo0; *(f32x4*)(xout + off + 4) = xo1;
;                     if (aout) { const f32x4 a0 = xo0 * wv[0], a1 = xo1 * wv[1]; u32x4 w; w.x = cvt_pk_bf16(a0[0], a0[1]); w.y = cvt_pk_bf16(a0[2], a0[3]); w.z = cvt_pk_bf16(a1[0], a1[1]); w.w = cvt_pk_bf16(a1[2], a1[3]);
;                         *(u32x4*)(aout + off) = w;
;                         sq[ai][m] += ((xo0[0] * xo0[0] + xo0[1] * xo0[1]) + (xo0[2] * xo0[2] + xo0[3] * xo0[3])) + ((xo1[0] * xo1[0] + xo1[1] * xo1[1]) + (xo1[2] * xo1[2] + xo1[3] * xo1[3]));
;                         if (WG2) { const f32x4 b0 = xo0 * w2[0], b1 = xo1 * w2[1]; sqb[ai][m] += ((b0[0] * b0[0] + b0[1] * b0[1]) + (b0[2] * b0[2] + b0[3] * b0[3])) + ((b1[0] * b1[0] + b1[1] * b1[1]) + (b1[2] * b1[2] + b1[3] * b1[3])); } } }
.LBB0_399:
	v_add_u32_e32 v136, 0x8000, v184
	v_mov_b32_e32 v137, v177
	v_lshl_add_u64 v[136:137], v[136:137], 2, s[38:39]
	global_load_dwordx4 v[144:147], v[136:137], off offset:16
	global_load_dwordx4 v[148:151], v[136:137], off
	v_add_u32_e32 v136, 0xc000, v184
	v_mov_b32_e32 v137, v177
	v_lshl_add_u64 v[140:141], v[136:137], 2, s[38:39]
	global_load_dwordx4 v[136:139], v[140:141], off offset:16
	s_nop 0
	global_load_dwordx4 v[140:143], v[140:141], off
	v_add_u32_e32 v184, 0x28000, v176
	v_mov_b32_e32 v185, v177
	v_lshl_add_u64 v[208:209], v[184:185], 2, s[36:37]
	s_and_b64 vcc, exec, s[8:9]
	s_waitcnt vmcnt(3)
	v_pk_fma_f32 v[146:147], v[26:27], v[202:203], v[146:147]
	s_waitcnt vmcnt(2)
	v_pk_fma_f32 v[150:151], v[30:31], v[204:205], v[150:151]
	v_pk_fma_f32 v[148:149], v[28:29], v[206:207], v[148:149]
	v_pk_fma_f32 v[144:145], v[24:25], v[200:201], v[144:145]
	global_store_dwordx4 v[208:209], v[148:151], off nt
	global_store_dwordx4 v[208:209], v[144:147], off offset:16 nt
	s_cbranch_vccnz .LBB0_401
	v_pk_mul_f32 v[208:209], v[186:187], v[148:149]
	v_pk_mul_f32 v[210:211], v[194:195], v[150:151]
	v_cvt_pk_bf16_f32 v208, v208, v209
	v_lshl_add_u64 v[184:185], v[184:185], 1, s[34:35]
	v_cvt_pk_bf16_f32 v209, v210, v211
	v_pk_mul_f32 v[212:213], v[198:199], v[146:147]
	v_pk_mul_f32 v[214:215], v[196:197], v[144:145]
	s_nop 0
	v_cvt_pk_bf16_f32 v210, v214, v215
	v_cvt_pk_bf16_f32 v211, v212, v213
	global_store_dwordx4 v[184:185], v[208:211], off
	v_pk_mul_f32 v[184:185], v[134:135], v[150:151]
	v_mov_b32_e32 v214, v148
	v_pk_mul_f32 v[208:209], v[132:133], v[148:149]
	v_pk_mul_f32 v[212:213], v[128:129], v[144:145]
	v_mov_b32_e32 v215, v208
	v_mov_b32_e32 v208, v149
	v_pk_mul_f32 v[148:149], v[208:209], v[208:209]
	v_mov_b32_e32 v209, v184
	v_mov_b32_e32 v184, v151
	v_mov_b32_e32 v208, v150
	v_pk_mul_f32 v[150:151], v[184:185], v[184:185]
	v_pk_fma_f32 v[148:149], v[214:215], v[214:215], v[148:149]
	v_pk_fma_f32 v[150:151], v[208:209], v[208:209], v[150:151]
	v_pk_mul_f32 v[210:211], v[130:131], v[146:147]
	v_pk_add_f32 v[148:149], v[148:149], v[150:151]
	v_mov_b32_e32 v151, v212
	v_mov_b32_e32 v212, v145
	v_mov_b32_e32 v150, v144
	v_pk_mul_f32 v[144:145], v[212:213], v[212:213]
	s_nop 0
	v_pk_fma_f32 v[144:145], v[150:151], v[150:151], v[144:145]
	v_mov_b32_e32 v151, v210
	v_mov_b32_e32 v210, v147
	v_mov_b32_e32 v150, v146
	v_pk_mul_f32 v[146:147], v[210:211], v[210:211]
	s_nop 0
	v_pk_fma_f32 v[146:147], v[150:151], v[150:151], v[146:147]
	s_nop 0
	v_pk_add_f32 v[144:145], v[144:145], v[146:147]
	s_nop 0
	v_pk_add_f32 v[184:185], v[148:149], v[144:145]
	s_branch .LBB0_402

; __device__ __forceinline__ unsigned cvt_pk_bf16(float lo, float hi) { unsigned r; asm volatile("v_cvt_pk_bf16_f32 %0, %1, %2" : "=v"(r) : "v"(lo), "v"(hi)); return r; }
;     static __device__ __forceinline__ void run(const f32x4 (&acc)[2][2][4][2], const Unit& u, int wr, int wc, int fr, int fq, const float* xin, float* xout, const float* gate, float gs, const float* lazy_ssq, const float* lazy_g, ...
;     ...
;                 for (int j = 0; j < 2; ++j) { const int i_ = 2 * pp + j, ai = i_ >> 2, m = i_ & 3; const unsigned off = (row0 + ai * HALF + m * 16) * 1024u + col;
;                     const f32x4 xi0 = xq[pp & 1][j][0], xi1 = xq[pp & 1][j][1];
;                     f32x4 xo0 = gv[0] * acc[ai][bj][m][0], xo1 = gv[1] * acc[ai][bj][m][1];
;                     if (LAZY) { xo0 = xo0 + xi0 * lg[0] * rl[ai][m]; xo1 = xo1 + xi1 * lg[1] * rl[ai][m]; } else { xo0 = xo0 + xi0; xo1 = xo1 + xi1; }
;                     *(f32x4*)(xout + off) = xo0; *(f32x4*)(xout + off + 4) = xo1;
;                     if (aout) { const f32x4 a0 = xo0 * wv[0], a1 = xo1 * wv[1]; u32x4 w; w.x = cvt_pk_bf16(a0[0], a0[1]); w.y = cvt_pk_bf16(a0[2], a0[3]); w.z = cvt_pk_bf16(a1[0], a1[1]); w.w = cvt_pk_bf16(a1[2], a1[3]);
;                         *(u32x4*)(aout + off) = w;
;                         sq[ai][m] += ((xo0[0] * xo0[0] + xo0[1] * xo0[1]) + (xo0[2] * xo0[2] + xo0[3] * xo0[3])) + ((xo1[0] * xo1[0] + xo1[1] * xo1[1]) + (xo1[2] * xo1[2] + xo1[3] * xo1[3]));
;                         if (WG2) { const f32x4 b0 = xo0 * w2[0], b1 = xo1 * w2[1]; sqb[ai][m] += ((b0[0] * b0[0] + b0[1] * b0[1]) + (b0[2] * b0[2] + b0[3] * b0[3])) + ((b1[0] * b1[0] + b1[1] * b1[1]) + (b1[2] * b1[2] + b1[3] * b1[3])); } } }
.LBB0_402:
	v_add_u32_e32 v176, 0x2c000, v176
	s_waitcnt vmcnt(2)
	v_pk_fma_f32 v[142:143], v[14:15], v[204:205], v[142:143]
	v_pk_fma_f32 v[140:141], v[12:13], v[206:207], v[140:141]
	v_pk_fma_f32 v[138:139], v[10:11], v[202:203], v[138:139]
	v_pk_fma_f32 v[136:137], v[8:9], v[200:201], v[136:137]
	v_lshl_add_u64 v[144:145], v[176:177], 2, s[36:37]
	s_and_b64 vcc, exec, s[8:9]
	global_store_dwordx4 v[144:145], v[140:143], off nt
	global_store_dwordx4 v[144:145], v[136:139], off offset:16 nt
	s_cbranch_vccnz .LBB0_404
	v_pk_mul_f32 v[146:147], v[194:195], v[142:143]
	v_pk_mul_f32 v[144:145], v[186:187], v[140:141]
	v_pk_mul_f32 v[148:149], v[198:199], v[138:139]
	v_pk_mul_f32 v[150:151], v[196:197], v[136:137]
	v_cvt_pk_bf16_f32 v144, v144, v145
	v_cvt_pk_bf16_f32 v145, v146, v147
	v_pk_mul_f32 v[134:135], v[134:135], v[142:143]
	v_cvt_pk_bf16_f32 v146, v150, v151
	v_cvt_pk_bf16_f32 v147, v148, v149
	v_lshl_add_u64 v[148:149], v[176:177], 1, s[34:35]
	v_pk_mul_f32 v[132:133], v[132:133], v[140:141]
	global_store_dwordx4 v[148:149], v[144:147], off
	v_pk_mul_f32 v[128:129], v[128:129], v[136:137]
	v_pk_mul_f32 v[130:131], v[130:131], v[138:139]
	v_mov_b32_e32 v145, v132
	v_mov_b32_e32 v132, v141
	v_mov_b32_e32 v141, v134
	v_mov_b32_e32 v134, v143
	v_mov_b32_e32 v144, v140
	v_pk_mul_f32 v[132:133], v[132:133], v[132:133]
	v_mov_b32_e32 v140, v142
	v_pk_mul_f32 v[134:135], v[134:135], v[134:135]
	v_pk_fma_f32 v[132:133], v[144:145], v[144:145], v[132:133]
	v_pk_fma_f32 v[134:135], v[140:141], v[140:141], v[134:135]
	s_nop 0
	v_pk_add_f32 v[132:133], v[132:133], v[134:135]
	v_mov_b32_e32 v135, v128
	v_mov_b32_e32 v128, v137
	v_mov_b32_e32 v134, v136
	v_pk_mul_f32 v[128:129], v[128:129], v[128:129]
	s_nop 0
	v_pk_fma_f32 v[128:129], v[134:135], v[134:135], v[128:129]
	v_mov_b32_e32 v135, v130
	v_mov_b32_e32 v130, v139
	v_mov_b32_e32 v134, v138
	v_pk_mul_f32 v[130:131], v[130:131], v[130:131]
	s_nop 0
	v_pk_fma_f32 v[130:131], v[134:135], v[134:135], v[130:131]
	s_nop 0
	v_pk_add_f32 v[128:129], v[128:129], v[130:131]
	s_nop 0
	v_pk_add_f32 v[186:187], v[132:133], v[128:129]
	s_branch .LBB0_405

;     static __device__ __forceinline__ void run(const f32x4 (&acc)[2][2][4][2], const Unit& u, int wr, int wc, int fr, int fq, const float* xin, float* xout, const float* gate, float gs, const float* lazy_ssq, const float* lazy_g, ...
;     ...
;                 gv[n] = *(const f32x4*)(gate + (b * 9216u + col + 4 * n)) * gs;
;                 lg[n] = (f32x4){1.f, 1.f, 1.f, 1.f}; if (LAZY) lg[n] = *(const f32x4*)(lazy_g + col + 4 * n);
;                 wv[n] = (f32x4){0.f, 0.f, 0.f, 0.f}; w2[n] = (f32x4){1.f, 1.f, 1.f, 1.f};
;                 if (aout) { wv[n] = *(const f32x4*)(wg + col + 4 * n) * (*(const f32x4*)(wsc + (b * 9216u + col + 4 * n)) + 1.0f); if (WG2) { w2[n] = *(const f32x4*)(wg2 + col + 4 * n); wv[n] = wv[n] * w2[n]; } }
;             }
;             f32x4 xq[2][2][2];
;     ...
;             constexpr bool DEEP = !LAZY && !WG2;
;             if (DEEP) RES_LD(0, 0);
; #pragma unroll
;             for (int pp = 0; pp < 4; ++pp) {
;                 if (DEEP) { if (pp < 3) RES_LD((pp + 1) & 1, pp + 1); } else RES_LD(pp & 1, pp);
; #pragma unroll
;                 for (int j = 0; j < 2; ++j) { const int i_ = 2 * pp + j, ai = i_ >> 2, m = i_ & 3; const unsigned off = (row0 + ai * HALF + m * 16) * 1024u + col;
;                     const f32x4 xi0 = xq[pp & 1][j][0], xi1 = xq[pp & 1][j][1];
;                     f32x4 xo0 = gv[0] * acc[ai][bj][m][0], xo1 = gv[1] * acc[ai][bj][m][1];
;                     if (LAZY) { xo0 = xo0 + xi0 * lg[0] * rl[ai][m]; xo1 = xo1 + xi1 * lg[1] * rl[ai][m]; } else { xo0 = xo0 + xi0; xo1 = xo1 + xi1; }
;                     *(f32x4*)(xout + off) = xo0; *(f32x4*)(xout + off + 4) = xo1;
;                     if (aout) { const f32x4 a0 = xo0 * wv[0], a1 = xo1 * wv[1]; u32x4 w; w.x = cvt_pk_bf16(a0[0], a0[1]); w.y = cvt_pk_bf16(a0[2], a0[3]); w.z = cvt_pk_bf16(a1[0], a1[1]); w.w = cvt_pk_bf16(a1[2], a1[3]);
;                         *(u32x4*)(aout + off) = w;
;                         sq[ai][m] += ((xo0[0] * xo0[0] + xo0[1] * xo0[1]) + (xo0[2] * xo0[2] + xo0[3] * xo0[3])) + ((xo1[0] * xo1[0] + xo1[1] * xo1[1]) + (xo1[2] * xo1[2] + xo1[3] * xo1[3]));
;                         if (WG2) { const f32x4 b0 = xo0 * w2[0], b1 = xo1 * w2[1]; sqb[ai][m] += ((b0[0] * b0[0] + b0[1] * b0[1]) + (b0[2] * b0[2] + b0[3] * b0[3])) + ((b1[0] * b1[0] + b1[1] * b1[1]) + (b1[2] * b1[2] + b1[3] * b1[3])); } } }
.LBB0_409:
	v_add_u32_e32 v176, v208, v153
	v_lshlrev_b64 v[206:207], 2, v[176:177]
	v_lshl_add_u64 v[144:145], s[38:39], 0, v[206:207]
	v_mov_b32_e32 v205, v177
	v_add_u32_e32 v204, 0x4000, v176
	global_load_dwordx4 v[210:213], v[144:145], off
	global_load_dwordx4 v[232:235], v[144:145], off offset:16
	v_lshl_add_u64 v[148:149], v[204:205], 2, s[38:39]
	global_load_dwordx4 v[144:147], v[148:149], off offset:16
	s_nop 0
	global_load_dwordx4 v[148:151], v[148:149], off
	s_mov_b32 s41, s40
	s_mov_b32 s42, s40
	s_mov_b32 s43, s40
	s_waitcnt vmcnt(4)
	v_pk_mul_f32 v[190:191], s[42:43], v[142:143]
	v_pk_mul_f32 v[188:189], s[40:41], v[140:141]
	v_pk_mul_f32 v[200:201], s[42:43], v[138:139]
	v_pk_mul_f32 v[202:203], s[40:41], v[136:137]
	s_and_b64 vcc, exec, s[8:9]
	v_lshl_add_u64 v[206:207], s[36:37], 0, v[206:207]
	s_waitcnt vmcnt(3)
	v_pk_fma_f32 v[142:143], v[118:119], v[200:201], v[212:213]
	v_pk_fma_f32 v[140:141], v[116:117], v[202:203], v[210:211]
	s_waitcnt vmcnt(2)
	v_pk_fma_f32 v[138:139], v[114:115], v[190:191], v[234:235]
	v_pk_fma_f32 v[136:137], v[112:113], v[188:189], v[232:233]
	global_store_dwordx4 v[206:207], v[140:143], off nt
	global_store_dwordx4 v[206:207], v[136:139], off offset:16 nt
	s_cbranch_vccnz .LBB0_411
	v_pk_mul_f32 v[206:207], v[196:197], v[142:143]
	v_pk_mul_f32 v[210:211], v[194:195], v[140:141]
	v_pk_mul_f32 v[212:213], v[192:193], v[136:137]
	v_cvt_pk_bf16_f32 v210, v210, v211
	v_cvt_pk_bf16_f32 v211, v206, v207
	v_lshl_add_u64 v[206:207], v[176:177], 1, s[34:35]
	v_pk_mul_f32 v[214:215], v[198:199], v[138:139]
	v_cvt_pk_bf16_f32 v212, v212, v213
	v_mov_b32_e32 v232, v140
	v_cvt_pk_bf16_f32 v213, v214, v215
	global_store_dwordx4 v[206:207], v[210:213], off
	v_pk_mul_f32 v[206:207], v[134:135], v[142:143]
	v_pk_mul_f32 v[214:215], v[128:129], v[136:137]
	v_pk_mul_f32 v[210:211], v[132:133], v[140:141]
	v_pk_mul_f32 v[212:213], v[130:131], v[138:139]
	v_mov_b32_e32 v233, v210
	v_mov_b32_e32 v210, v141
	v_pk_mul_f32 v[140:141], v[210:211], v[210:211]
	v_mov_b32_e32 v211, v206
	v_mov_b32_e32 v206, v143
	v_mov_b32_e32 v210, v142
	v_pk_mul_f32 v[142:143], v[206:207], v[206:207]
	v_pk_fma_f32 v[140:141], v[232:233], v[232:233], v[140:141]
	v_pk_fma_f32 v[142:143], v[210:211], v[210:211], v[142:143]
	s_nop 0
	v_pk_add_f32 v[140:141], v[140:141], v[142:143]
	v_mov_b32_e32 v143, v214
	v_mov_b32_e32 v214, v137
	v_mov_b32_e32 v142, v136
	v_pk_mul_f32 v[136:137], v[214:215], v[214:215]
	s_nop 0
	v_pk_fma_f32 v[136:137], v[142:143], v[142:143], v[136:137]
	v_mov_b32_e32 v143, v212
	v_mov_b32_e32 v212, v139
	v_mov_b32_e32 v142, v138
	v_pk_mul_f32 v[138:139], v[212:213], v[212:213]
	s_nop 0
	v_pk_fma_f32 v[138:139], v[142:143], v[142:143], v[138:139]
	s_nop 0
	v_pk_add_f32 v[136:137], v[136:137], v[138:139]
	s_nop 0
	v_pk_add_f32 v[136:137], v[140:141], v[136:137]
	s_nop 0
	v_pk_add_f32 v[154:155], v[154:155], v[136:137]
.LBB0_411:
	s_waitcnt vmcnt(2)
	v_pk_fma_f32 v[142:143], v[102:103], v[200:201], v[150:151]
	v_pk_fma_f32 v[140:141], v[100:101], v[202:203], v[148:149]
	v_pk_fma_f32 v[138:139], v[98:99], v[190:191], v[146:147]
	v_pk_fma_f32 v[136:137], v[96:97], v[188:189], v[144:145]
	v_lshl_add_u64 v[144:145], v[204:205], 2, s[36:37]
	s_and_b64 vcc, exec, s[8:9]
	global_store_dwordx4 v[144:145], v[140:143], off nt
	global_store_dwordx4 v[144:145], v[136:139], off offset:16 nt
	s_cbranch_vccnz .LBB0_413
	v_pk_mul_f32 v[146:147], v[196:197], v[142:143]
	v_pk_mul_f32 v[144:145], v[194:195], v[140:141]
	v_pk_mul_f32 v[148:149], v[198:199], v[138:139]
	v_pk_mul_f32 v[150:151], v[192:193], v[136:137]
	v_cvt_pk_bf16_f32 v144, v144, v145
	v_cvt_pk_bf16_f32 v145, v146, v147
	s_nop 0
	v_cvt_pk_bf16_f32 v146, v150, v151
	v_cvt_pk_bf16_f32 v147, v148, v149
	v_lshl_add_u64 v[148:149], v[204:205], 1, s[34:35]
	global_store_dwordx4 v[148:149], v[144:147], off
	v_mov_b32_e32 v204, v140
	v_pk_mul_f32 v[150:151], v[128:129], v[136:137]
	v_pk_mul_f32 v[146:147], v[132:133], v[140:141]
	v_pk_mul_f32 v[144:145], v[134:135], v[142:143]
	v_mov_b32_e32 v205, v146
	v_mov_b32_e32 v146, v141
	v_pk_mul_f32 v[140:141], v[146:147], v[146:147]
	v_mov_b32_e32 v147, v144
	v_mov_b32_e32 v144, v143
	v_mov_b32_e32 v146, v142
	v_pk_mul_f32 v[142:143], v[144:145], v[144:145]
	v_pk_fma_f32 v[140:141], v[204:205], v[204:205], v[140:141]
	v_pk_fma_f32 v[142:143], v[146:147], v[146:147], v[142:143]
	v_pk_mul_f32 v[148:149], v[130:131], v[138:139]
	v_pk_add_f32 v[140:141], v[140:141], v[142:143]
	v_mov_b32_e32 v143, v150
	v_mov_b32_e32 v150, v137
	v_mov_b32_e32 v142, v136
	v_pk_mul_f32 v[136:137], v[150:151], v[150:151]
	s_nop 0
	v_pk_fma_f32 v[136:137], v[142:143], v[142:143], v[136:137]
	v_mov_b32_e32 v143, v148
	v_mov_b32_e32 v148, v139
	v_mov_b32_e32 v142, v138
	v_pk_mul_f32 v[138:139], v[148:149], v[148:149]
	s_nop 0
	v_pk_fma_f32 v[138:139], v[142:143], v[142:143], v[138:139]
	s_nop 0
	v_pk_add_f32 v[136:137], v[136:137], v[138:139]
	s_nop 0
	v_pk_add_f32 v[136:137], v[140:141], v[136:137]
	s_nop 0
	v_pk_add_f32 v[156:157], v[156:157], v[136:137]
; __device__ __forceinline__ unsigned cvt_pk_bf16(float lo, float hi) { unsigned r; asm volatile("v_cvt_pk_bf16_f32 %0, %1, %2" : "=v"(r) : "v"(lo), "v"(hi)); return r; }
; #define RES_LD(buf, pp) do { _Pragma("unroll") for (int j = 0; j < 2; ++j) { const int i_ = 2 * (pp) + j; const unsigned off_ = (row0 + (i_ >> 2) * HALF + (i_ & 3) * 16) * 1024u + col; \
;                 xq[buf][j][0] = *(const f32x4*)(xin + off_); xq[buf][j][1] = *(const f32x4*)(xin + off_ + 4); } } while (0)
;     static __device__ __forceinline__ void run(const f32x4 (&acc)[2][2][4][2], const Unit& u, int wr, int wc, int fr, int fq, const float* xin, float* xout, const float* gate, float gs, const float* lazy_ssq, const float* lazy_g, ...
;     ...
;             constexpr bool DEEP = !LAZY && !WG2;
;             if (DEEP) RES_LD(0, 0);
; #pragma unroll
;             for (int pp = 0; pp < 4; ++pp) {
;                 if (DEEP) { if (pp < 3) RES_LD((pp + 1) & 1, pp + 1); } else RES_LD(pp & 1, pp);
; #pragma unroll
;                 for (int j = 0; j < 2; ++j) { const int i_ = 2 * pp + j, ai = i_ >> 2, m = i_ & 3; const unsigned off = (row0 + ai * HALF + m * 16) * 1024u + col;
;                     const f32x4 xi0 = xq[pp & 1][j][0], xi1 = xq[pp & 1][j][1];
;                     f32x4 xo0 = gv[0] * acc[ai][bj][m][0], xo1 = gv[1] * acc[ai][bj][m][1];
;                     if (LAZY) { xo0 = xo0 + xi0 * lg[0] * rl[ai][m]; xo1 = xo1 + xi1 * lg[1] * rl[ai][m]; } else { xo0 = xo0 + xi0; xo1 = xo1 + xi1; }
;                     *(f32x4*)(xout + off) = xo0; *(f32x4*)(xout + off + 4) = xo1;
;                     if (aout) { const f32x4 a0 = xo0 * wv[0], a1 = xo1 * wv[1]; u32x4 w; w.x = cvt_pk_bf16(a0[0], a0[1]); w.y = cvt_pk_bf16(a0[2], a0[3]); w.z = cvt_pk_bf16(a1[0], a1[1]); w.w = cvt_pk_bf16(a1[2], a1[3]);
;                         *(u32x4*)(aout + off) = w;
;                         sq[ai][m] += ((xo0[0] * xo0[0] + xo0[1] * xo0[1]) + (xo0[2] * xo0[2] + xo0[3] * xo0[3])) + ((xo1[0] * xo1[0] + xo1[1] * xo1[1]) + (xo1[2] * xo1[2] + xo1[3] * xo1[3]));
;                         if (WG2) { const f32x4 b0 = xo0 * w2[0], b1 = xo1 * w2[1]; sqb[ai][m] += ((b0[0] * b0[0] + b0[1] * b0[1]) + (b0[2] * b0[2] + b0[3] * b0[3])) + ((b1[0] * b1[0] + b1[1] * b1[1]) + (b1[2] * b1[2] + b1[3] * b1[3])); } } }
.LBB0_413:
	v_add_u32_e32 v206, 0x8000, v176
	v_mov_b32_e32 v207, v177
	v_lshlrev_b64 v[148:149], 2, v[206:207]
	v_lshl_add_u64 v[136:137], s[38:39], 0, v[148:149]
	v_add_u32_e32 v204, 0xc000, v176
	v_mov_b32_e32 v205, v177
	global_load_dwordx4 v[144:147], v[136:137], off
	global_load_dwordx4 v[210:213], v[136:137], off offset:16
	v_lshl_add_u64 v[140:141], v[204:205], 2, s[38:39]
	global_load_dwordx4 v[136:139], v[140:141], off offset:16
	s_nop 0
	global_load_dwordx4 v[140:143], v[140:141], off
	s_and_b64 vcc, exec, s[8:9]
	v_lshl_add_u64 v[214:215], s[36:37], 0, v[148:149]
	s_waitcnt vmcnt(3)
	v_pk_fma_f32 v[150:151], v[86:87], v[200:201], v[146:147]
	v_pk_fma_f32 v[148:149], v[84:85], v[202:203], v[144:145]
	s_waitcnt vmcnt(2)
	v_pk_fma_f32 v[146:147], v[82:83], v[190:191], v[212:213]
	v_pk_fma_f32 v[144:145], v[80:81], v[188:189], v[210:211]
	global_store_dwordx4 v[214:215], v[148:151], off nt
	global_store_dwordx4 v[214:215], v[144:147], off offset:16 nt
	s_cbranch_vccnz .LBB0_415
	v_pk_mul_f32 v[210:211], v[194:195], v[148:149]
	v_pk_mul_f32 v[212:213], v[196:197], v[150:151]
	v_cvt_pk_bf16_f32 v210, v210, v211
	v_lshl_add_u64 v[206:207], v[206:207], 1, s[34:35]
	v_cvt_pk_bf16_f32 v211, v212, v213
	v_pk_mul_f32 v[214:215], v[198:199], v[146:147]
	v_pk_mul_f32 v[232:233], v[192:193], v[144:145]
	s_nop 0
	v_cvt_pk_bf16_f32 v212, v232, v233
	v_cvt_pk_bf16_f32 v213, v214, v215
	global_store_dwordx4 v[206:207], v[210:213], off
	v_pk_mul_f32 v[206:207], v[134:135], v[150:151]
	v_mov_b32_e32 v232, v148
	v_pk_mul_f32 v[210:211], v[132:133], v[148:149]
	v_pk_mul_f32 v[214:215], v[128:129], v[144:145]
	v_mov_b32_e32 v233, v210
	v_mov_b32_e32 v210, v149
	v_pk_mul_f32 v[148:149], v[210:211], v[210:211]
	v_mov_b32_e32 v211, v206
	v_mov_b32_e32 v206, v151
	v_mov_b32_e32 v210, v150
	v_pk_mul_f32 v[150:151], v[206:207], v[206:207]
	v_pk_fma_f32 v[148:149], v[232:233], v[232:233], v[148:149]
	v_pk_fma_f32 v[150:151], v[210:211], v[210:211], v[150:151]
	v_pk_mul_f32 v[212:213], v[130:131], v[146:147]
	v_pk_add_f32 v[148:149], v[148:149], v[150:151]
	v_mov_b32_e32 v151, v214
	v_mov_b32_e32 v214, v145
	v_mov_b32_e32 v150, v144
	v_pk_mul_f32 v[144:145], v[214:215], v[214:215]
	s_nop 0
	v_pk_fma_f32 v[144:145], v[150:151], v[150:151], v[144:145]
	v_mov_b32_e32 v151, v212
	v_mov_b32_e32 v212, v147
	v_mov_b32_e32 v150, v146
	v_pk_mul_f32 v[146:147], v[212:213], v[212:213]
	s_nop 0
	v_pk_fma_f32 v[146:147], v[150:151], v[150:151], v[146:147]
	s_nop 0
	v_pk_add_f32 v[144:145], v[144:145], v[146:147]
	s_nop 0
	v_pk_add_f32 v[144:145], v[148:149], v[144:145]
	s_nop 0
	v_pk_add_f32 v[158:159], v[158:159], v[144:145]
.LBB0_415:
	s_waitcnt vmcnt(2)
	v_pk_fma_f32 v[142:143], v[70:71], v[200:201], v[142:143]
	v_pk_fma_f32 v[140:141], v[68:69], v[202:203], v[140:141]
	v_pk_fma_f32 v[138:139], v[66:67], v[190:191], v[138:139]
	v_pk_fma_f32 v[136:137], v[64:65], v[188:189], v[136:137]
	v_lshl_add_u64 v[144:145], v[204:205], 2, s[36:37]
	s_and_b64 vcc, exec, s[8:9]
	global_store_dwordx4 v[144:145], v[140:143], off nt
	global_store_dwordx4 v[144:145], v[136:139], off offset:16 nt
	s_cbranch_vccnz .LBB0_417
	v_pk_mul_f32 v[146:147], v[196:197], v[142:143]
	v_pk_mul_f32 v[144:145], v[194:195], v[140:141]
	v_pk_mul_f32 v[148:149], v[198:199], v[138:139]
	v_pk_mul_f32 v[150:151], v[192:193], v[136:137]
	v_cvt_pk_bf16_f32 v144, v144, v145
	v_cvt_pk_bf16_f32 v145, v146, v147
	s_nop 0
	v_cvt_pk_bf16_f32 v146, v150, v151
	v_cvt_pk_bf16_f32 v147, v148, v149
	v_lshl_add_u64 v[148:149], v[204:205], 1, s[34:35]
	global_store_dwordx4 v[148:149], v[144:147], off
	v_mov_b32_e32 v204, v140
	v_pk_mul_f32 v[150:151], v[128:129], v[136:137]
	v_pk_mul_f32 v[146:147], v[132:133], v[140:141]
	v_pk_mul_f32 v[144:145], v[134:135], v[142:143]
	v_mov_b32_e32 v205, v146
	v_mov_b32_e32 v146, v141
	v_pk_mul_f32 v[140:141], v[146:147], v[146:147]
	v_mov_b32_e32 v147, v144
	v_mov_b32_e32 v144, v143
	v_mov_b32_e32 v146, v142
	v_pk_mul_f32 v[142:143], v[144:145], v[144:145]
	v_pk_fma_f32 v[140:141], v[204:205], v[204:205], v[140:141]
	v_pk_fma_f32 v[142:143], v[146:147], v[146:147], v[142:143]
	v_pk_mul_f32 v[148:149], v[130:131], v[138:139]
	v_pk_add_f32 v[140:141], v[140:141], v[142:143]
	v_mov_b32_e32 v143, v150
	v_mov_b32_e32 v150, v137
	v_mov_b32_e32 v142, v136
	v_pk_mul_f32 v[136:137], v[150:151], v[150:151]
	s_nop 0
	v_pk_fma_f32 v[136:137], v[142:143], v[142:143], v[136:137]
	v_mov_b32_e32 v143, v148
	v_mov_b32_e32 v148, v139
	v_mov_b32_e32 v142, v138
	v_pk_mul_f32 v[138:139], v[148:149], v[148:149]
	s_nop 0
	v_pk_fma_f32 v[138:139], v[142:143], v[142:143], v[138:139]
	s_nop 0
	v_pk_add_f32 v[136:137], v[136:137], v[138:139]
	s_nop 0
	v_pk_add_f32 v[136:137], v[140:141], v[136:137]
	s_nop 0
	v_pk_add_f32 v[174:175], v[174:175], v[136:137]
; __device__ __forceinline__ unsigned cvt_pk_bf16(float lo, float hi) { unsigned r; asm volatile("v_cvt_pk_bf16_f32 %0, %1, %2" : "=v"(r) : "v"(lo), "v"(hi)); return r; }
; #define RES_LD(buf, pp) do { _Pragma("unroll") for (int j = 0; j < 2; ++j) { const int i_ = 2 * (pp) + j; const unsigned off_ = (row0 + (i_ >> 2) * HALF + (i_ & 3) * 16) * 1024u + col; \
;                 xq[buf][j][0] = *(const f32x4*)(xin + off_); xq[buf][j][1] = *(const f32x4*)(xin + off_ + 4); } } while (0)
;     static __device__ __forceinline__ void run(const f32x4 (&acc)[2][2][4][2], const Unit& u, int wr, int wc, int fr, int fq, const float* xin, float* xout, const float* gate, float gs, const float* lazy_ssq, const float* lazy_g, ...
;     ...
;             constexpr bool DEEP = !LAZY && !WG2;
;             if (DEEP) RES_LD(0, 0);
; #pragma unroll
;             for (int pp = 0; pp < 4; ++pp) {
;                 if (DEEP) { if (pp < 3) RES_LD((pp + 1) & 1, pp + 1); } else RES_LD(pp & 1, pp);
; #pragma unroll
;                 for (int j = 0; j < 2; ++j) { const int i_ = 2 * pp + j, ai = i_ >> 2, m = i_ & 3; const unsigned off = (row0 + ai * HALF + m * 16) * 1024u + col;
;                     const f32x4 xi0 = xq[pp & 1][j][0], xi1 = xq[pp & 1][j][1];
;                     f32x4 xo0 = gv[0] * acc[ai][bj][m][0], xo1 = gv[1] * acc[ai][bj][m][1];
;                     if (LAZY) { xo0 = xo0 + xi0 * lg[0] * rl[ai][m]; xo1 = xo1 + xi1 * lg[1] * rl[ai][m]; } else { xo0 = xo0 + xi0; xo1 = xo1 + xi1; }
;                     *(f32x4*)(xout + off) = xo0; *(f32x4*)(xout + off + 4) = xo1;
;                     if (aout) { const f32x4 a0 = xo0 * wv[0], a1 = xo1 * wv[1]; u32x4 w; w.x = cvt_pk_bf16(a0[0], a0[1]); w.y = cvt_pk_bf16(a0[2], a0[3]); w.z = cvt_pk_bf16(a1[0], a1[1]); w.w = cvt_pk_bf16(a1[2], a1[3]);
;                         *(u32x4*)(aout + off) = w;
;                         sq[ai][m] += ((xo0[0] * xo0[0] + xo0[1] * xo0[1]) + (xo0[2] * xo0[2] + xo0[3] * xo0[3])) + ((xo1[0] * xo1[0] + xo1[1] * xo1[1]) + (xo1[2] * xo1[2] + xo1[3] * xo1[3]));
;                         if (WG2) { const f32x4 b0 = xo0 * w2[0], b1 = xo1 * w2[1]; sqb[ai][m] += ((b0[0] * b0[0] + b0[1] * b0[1]) + (b0[2] * b0[2] + b0[3] * b0[3])) + ((b1[0] * b1[0] + b1[1] * b1[1]) + (b1[2] * b1[2] + b1[3] * b1[3])); } } }
.LBB0_417:
	v_add_u32_e32 v204, v173, v208
	v_mov_b32_e32 v205, v177
	v_lshl_add_u64 v[136:137], v[204:205], 2, s[38:39]
	global_load_dwordx4 v[144:147], v[136:137], off offset:16
	global_load_dwordx4 v[148:151], v[136:137], off
	v_add_u32_e32 v136, 0x4000, v204
	v_mov_b32_e32 v137, v177
	v_lshl_add_u64 v[140:141], v[136:137], 2, s[38:39]
	global_load_dwordx4 v[136:139], v[140:141], off offset:16
	s_nop 0
	global_load_dwordx4 v[140:143], v[140:141], off
	v_add_u32_e32 v206, 0x20000, v176
	v_mov_b32_e32 v207, v177
	v_lshl_add_u64 v[208:209], v[206:207], 2, s[36:37]
	s_and_b64 vcc, exec, s[8:9]
	s_waitcnt vmcnt(3)
	v_pk_fma_f32 v[146:147], v[50:51], v[190:191], v[146:147]
	s_waitcnt vmcnt(2)
	v_pk_fma_f32 v[150:151], v[54:55], v[200:201], v[150:151]
	v_pk_fma_f32 v[148:149], v[52:53], v[202:203], v[148:149]
	v_pk_fma_f32 v[144:145], v[48:49], v[188:189], v[144:145]
	global_store_dwordx4 v[208:209], v[148:151], off nt
	global_store_dwordx4 v[208:209], v[144:147], off offset:16 nt
	s_cbranch_vccnz .LBB0_419
	v_pk_mul_f32 v[208:209], v[194:195], v[148:149]
	v_pk_mul_f32 v[210:211], v[196:197], v[150:151]
	v_cvt_pk_bf16_f32 v208, v208, v209
	v_lshl_add_u64 v[206:207], v[206:207], 1, s[34:35]
	v_cvt_pk_bf16_f32 v209, v210, v211
	v_pk_mul_f32 v[212:213], v[198:199], v[146:147]
	v_pk_mul_f32 v[214:215], v[192:193], v[144:145]
	s_nop 0
	v_cvt_pk_bf16_f32 v210, v214, v215
	v_cvt_pk_bf16_f32 v211, v212, v213
	global_store_dwordx4 v[206:207], v[208:211], off
	v_pk_mul_f32 v[206:207], v[134:135], v[150:151]
	v_mov_b32_e32 v214, v148
	v_pk_mul_f32 v[208:209], v[132:133], v[148:149]
	v_pk_mul_f32 v[212:213], v[128:129], v[144:145]
	v_mov_b32_e32 v215, v208
	v_mov_b32_e32 v208, v149
	v_pk_mul_f32 v[148:149], v[208:209], v[208:209]
	v_mov_b32_e32 v209, v206
	v_mov_b32_e32 v206, v151
	v_mov_b32_e32 v208, v150
	v_pk_mul_f32 v[150:151], v[206:207], v[206:207]
	v_pk_fma_f32 v[148:149], v[214:215], v[214:215], v[148:149]
	v_pk_fma_f32 v[150:151], v[208:209], v[208:209], v[150:151]
	v_pk_mul_f32 v[210:211], v[130:131], v[146:147]
	v_pk_add_f32 v[148:149], v[148:149], v[150:151]
	v_mov_b32_e32 v151, v212
	v_mov_b32_e32 v212, v145
	v_mov_b32_e32 v150, v144
	v_pk_mul_f32 v[144:145], v[212:213], v[212:213]
	s_nop 0
	v_pk_fma_f32 v[144:145], v[150:151], v[150:151], v[144:145]
	v_mov_b32_e32 v151, v210
	v_mov_b32_e32 v210, v147
	v_mov_b32_e32 v150, v146
	v_pk_mul_f32 v[146:147], v[210:211], v[210:211]
	s_nop 0
	v_pk_fma_f32 v[146:147], v[150:151], v[150:151], v[146:147]
	s_nop 0
	v_pk_add_f32 v[144:145], v[144:145], v[146:147]
	s_nop 0
	v_pk_add_f32 v[144:145], v[148:149], v[144:145]
	s_nop 0
	v_pk_add_f32 v[180:181], v[180:181], v[144:145]
.LBB0_419:
	s_nop 0
	v_add_u32_e32 v144, 0x24000, v176
	v_mov_b32_e32 v145, v177
	s_waitcnt vmcnt(2)
	v_pk_fma_f32 v[142:143], v[38:39], v[200:201], v[142:143]
	v_pk_fma_f32 v[140:141], v[36:37], v[202:203], v[140:141]
	v_pk_fma_f32 v[138:139], v[34:35], v[190:191], v[138:139]
	v_pk_fma_f32 v[136:137], v[32:33], v[188:189], v[136:137]
	v_lshl_add_u64 v[146:147], v[144:145], 2, s[36:37]
	s_and_b64 vcc, exec, s[8:9]
	global_store_dwordx4 v[146:147], v[140:143], off nt
	global_store_dwordx4 v[146:147], v[136:139], off offset:16 nt
	s_cbranch_vccnz .LBB0_421
	v_pk_mul_f32 v[146:147], v[194:195], v[140:141]
	v_pk_mul_f32 v[148:149], v[196:197], v[142:143]
	v_cvt_pk_bf16_f32 v146, v146, v147
	v_lshl_add_u64 v[144:145], v[144:145], 1, s[34:35]
	v_cvt_pk_bf16_f32 v147, v148, v149
	v_pk_mul_f32 v[150:151], v[198:199], v[138:139]
	v_pk_mul_f32 v[206:207], v[192:193], v[136:137]
	s_nop 0
	v_cvt_pk_bf16_f32 v148, v206, v207
	v_cvt_pk_bf16_f32 v149, v150, v151
	global_store_dwordx4 v[144:145], v[146:149], off
	v_pk_mul_f32 v[144:145], v[134:135], v[142:143]
	v_mov_b32_e32 v206, v140
	v_pk_mul_f32 v[146:147], v[132:133], v[140:141]
	v_pk_mul_f32 v[150:151], v[128:129], v[136:137]
	v_mov_b32_e32 v207, v146
	v_mov_b32_e32 v146, v141
	v_pk_mul_f32 v[140:141], v[146:147], v[146:147]
	v_mov_b32_e32 v147, v144
	v_mov_b32_e32 v144, v143
	v_mov_b32_e32 v146, v142
	v_pk_mul_f32 v[142:143], v[144:145], v[144:145]
	v_pk_fma_f32 v[140:141], v[206:207], v[206:207], v[140:141]
	v_pk_fma_f32 v[142:143], v[146:147], v[146:147], v[142:143]
	v_pk_mul_f32 v[148:149], v[130:131], v[138:139]
	v_pk_add_f32 v[140:141], v[140:141], v[142:143]
	v_mov_b32_e32 v143, v150
	v_mov_b32_e32 v150, v137
	v_mov_b32_e32 v142, v136
	v_pk_mul_f32 v[136:137], v[150:151], v[150:151]
	s_nop 0
	v_pk_fma_f32 v[136:137], v[142:143], v[142:143], v[136:137]
	v_mov_b32_e32 v143, v148
	v_mov_b32_e32 v148, v139
	v_mov_b32_e32 v142, v138
	v_pk_mul_f32 v[138:139], v[148:149], v[148:149]
	s_nop 0
	v_pk_fma_f32 v[138:139], v[142:143], v[142:143], v[138:139]
	s_nop 0
	v_pk_add_f32 v[136:137], v[136:137], v[138:139]
	s_nop 0
	v_pk_add_f32 v[136:137], v[140:141], v[136:137]
	s_nop 0
	v_pk_add_f32 v[182:183], v[182:183], v[136:137]
; __device__ __forceinline__ unsigned cvt_pk_bf16(float lo, float hi) { unsigned r; asm volatile("v_cvt_pk_bf16_f32 %0, %1, %2" : "=v"(r) : "v"(lo), "v"(hi)); return r; }
; #define RES_LD(buf, pp) do { _Pragma("unroll") for (int j = 0; j < 2; ++j) { const int i_ = 2 * (pp) + j; const unsigned off_ = (row0 + (i_ >> 2) * HALF + (i_ & 3) * 16) * 1024u + col; \
;                 xq[buf][j][0] = *(const f32x4*)(xin + off_); xq[buf][j][1] = *(const f32x4*)(xin + off_ + 4); } } while (0)
;     static __device__ __forceinline__ void run(const f32x4 (&acc)[2][2][4][2], const Unit& u, int wr, int wc, int fr, int fq, const float* xin, float* xout, const float* gate, float gs, const float* lazy_ssq, const float* lazy_g, ...
;     ...
;             constexpr bool DEEP = !LAZY && !WG2;
;             if (DEEP) RES_LD(0, 0);
; #pragma unroll
;             for (int pp = 0; pp < 4; ++pp) {
;                 if (DEEP) { if (pp < 3) RES_LD((pp + 1) & 1, pp + 1); } else RES_LD(pp & 1, pp);
; #pragma unroll
;                 for (int j = 0; j < 2; ++j) { const int i_ = 2 * pp + j, ai = i_ >> 2, m = i_ & 3; const unsigned off = (row0 + ai * HALF + m * 16) * 1024u + col;
;                     const f32x4 xi0 = xq[pp & 1][j][0], xi1 = xq[pp & 1][j][1];
;                     f32x4 xo0 = gv[0] * acc[ai][bj][m][0], xo1 = gv[1] * acc[ai][bj][m][1];
;                     if (LAZY) { xo0 = xo0 + xi0 * lg[0] * rl[ai][m]; xo1 = xo1 + xi1 * lg[1] * rl[ai][m]; } else { xo0 = xo0 + xi0; xo1 = xo1 + xi1; }
;                     *(f32x4*)(xout + off) = xo0; *(f32x4*)(xout + off + 4) = xo1;
;                     if (aout) { const f32x4 a0 = xo0 * wv[0], a1 = xo1 * wv[1]; u32x4 w; w.x = cvt_pk_bf16(a0[0], a0[1]); w.y = cvt_pk_bf16(a0[2], a0[3]); w.z = cvt_pk_bf16(a1[0], a1[1]); w.w = cvt_pk_bf16(a1[2], a1[3]);
;                         *(u32x4*)(aout + off) = w;
;                         sq[ai][m] += ((xo0[0] * xo0[0] + xo0[1] * xo0[1]) + (xo0[2] * xo0[2] + xo0[3] * xo0[3])) + ((xo1[0] * xo1[0] + xo1[1] * xo1[1]) + (xo1[2] * xo1[2] + xo1[3] * xo1[3]));
;                         if (WG2) { const f32x4 b0 = xo0 * w2[0], b1 = xo1 * w2[1]; sqb[ai][m] += ((b0[0] * b0[0] + b0[1] * b0[1]) + (b0[2] * b0[2] + b0[3] * b0[3])) + ((b1[0] * b1[0] + b1[1] * b1[1]) + (b1[2] * b1[2] + b1[3] * b1[3])); } } }
.LBB0_421:
	s_nop 0
	v_add_u32_e32 v136, 0x8000, v204
	v_mov_b32_e32 v137, v177
	v_lshl_add_u64 v[136:137], v[136:137], 2, s[38:39]
	global_load_dwordx4 v[144:147], v[136:137], off offset:16
	global_load_dwordx4 v[148:151], v[136:137], off
	v_add_u32_e32 v136, 0xc000, v204
	v_mov_b32_e32 v137, v177
	v_lshl_add_u64 v[140:141], v[136:137], 2, s[38:39]
	global_load_dwordx4 v[136:139], v[140:141], off offset:16
	s_nop 0
	global_load_dwordx4 v[140:143], v[140:141], off
	v_add_u32_e32 v204, 0x28000, v176
	v_mov_b32_e32 v205, v177
	v_lshl_add_u64 v[206:207], v[204:205], 2, s[36:37]
	s_and_b64 vcc, exec, s[8:9]
	s_waitcnt vmcnt(3)
	v_pk_fma_f32 v[146:147], v[18:19], v[190:191], v[146:147]
	s_waitcnt vmcnt(2)
	v_pk_fma_f32 v[150:151], v[22:23], v[200:201], v[150:151]
	v_pk_fma_f32 v[148:149], v[20:21], v[202:203], v[148:149]
	v_pk_fma_f32 v[144:145], v[16:17], v[188:189], v[144:145]
	global_store_dwordx4 v[206:207], v[148:151], off nt
	global_store_dwordx4 v[206:207], v[144:147], off offset:16 nt
	s_cbranch_vccnz .LBB0_423
	v_pk_mul_f32 v[206:207], v[194:195], v[148:149]
	v_pk_mul_f32 v[208:209], v[196:197], v[150:151]
	v_cvt_pk_bf16_f32 v206, v206, v207
	v_lshl_add_u64 v[204:205], v[204:205], 1, s[34:35]
	v_cvt_pk_bf16_f32 v207, v208, v209
	v_pk_mul_f32 v[210:211], v[198:199], v[146:147]
	v_pk_mul_f32 v[212:213], v[192:193], v[144:145]
	s_nop 0
	v_cvt_pk_bf16_f32 v208, v212, v213
	v_cvt_pk_bf16_f32 v209, v210, v211
	global_store_dwordx4 v[204:205], v[206:209], off
	v_pk_mul_f32 v[204:205], v[134:135], v[150:151]
	v_mov_b32_e32 v212, v148
	v_pk_mul_f32 v[206:207], v[132:133], v[148:149]
	v_pk_mul_f32 v[210:211], v[128:129], v[144:145]
	v_mov_b32_e32 v213, v206
	v_mov_b32_e32 v206, v149
	v_pk_mul_f32 v[148:149], v[206:207], v[206:207]
	v_mov_b32_e32 v207, v204
	v_mov_b32_e32 v204, v151
	v_mov_b32_e32 v206, v150
	v_pk_mul_f32 v[150:151], v[204:205], v[204:205]
	v_pk_fma_f32 v[148:149], v[212:213], v[212:213], v[148:149]
	v_pk_fma_f32 v[150:151], v[206:207], v[206:207], v[150:151]
	v_pk_mul_f32 v[208:209], v[130:131], v[146:147]
	v_pk_add_f32 v[148:149], v[148:149], v[150:151]
	v_mov_b32_e32 v151, v210
	v_mov_b32_e32 v210, v145
	v_mov_b32_e32 v150, v144
	v_pk_mul_f32 v[144:145], v[210:211], v[210:211]
	s_nop 0
	v_pk_fma_f32 v[144:145], v[150:151], v[150:151], v[144:145]
	v_mov_b32_e32 v151, v208
	v_mov_b32_e32 v208, v147
	v_mov_b32_e32 v150, v146
	v_pk_mul_f32 v[146:147], v[208:209], v[208:209]
	s_nop 0
	v_pk_fma_f32 v[146:147], v[150:151], v[150:151], v[146:147]
	s_nop 0
	v_pk_add_f32 v[144:145], v[144:145], v[146:147]
	s_nop 0
	v_pk_add_f32 v[144:145], v[148:149], v[144:145]
	s_nop 0
	v_pk_add_f32 v[184:185], v[184:185], v[144:145]
.LBB0_423:
	v_add_u32_e32 v176, 0x2c000, v176
	s_waitcnt vmcnt(2)
	v_pk_fma_f32 v[142:143], v[6:7], v[200:201], v[142:143]
	v_pk_fma_f32 v[140:141], v[4:5], v[202:203], v[140:141]
	v_pk_fma_f32 v[138:139], v[2:3], v[190:191], v[138:139]
	v_pk_fma_f32 v[136:137], v[0:1], v[188:189], v[136:137]
	v_lshl_add_u64 v[144:145], v[176:177], 2, s[36:37]
	s_and_b64 vcc, exec, s[8:9]
	global_store_dwordx4 v[144:145], v[140:143], off nt
	global_store_dwordx4 v[144:145], v[136:139], off offset:16 nt
	s_cbranch_vccnz .LBB0_425
	v_pk_mul_f32 v[146:147], v[196:197], v[142:143]
	v_pk_mul_f32 v[144:145], v[194:195], v[140:141]
	v_pk_mul_f32 v[148:149], v[198:199], v[138:139]
	v_pk_mul_f32 v[150:151], v[192:193], v[136:137]
	v_cvt_pk_bf16_f32 v144, v144, v145
	v_cvt_pk_bf16_f32 v145, v146, v147
	v_pk_mul_f32 v[134:135], v[134:135], v[142:143]
	v_cvt_pk_bf16_f32 v146, v150, v151
	v_cvt_pk_bf16_f32 v147, v148, v149
	v_lshl_add_u64 v[148:149], v[176:177], 1, s[34:35]
	v_pk_mul_f32 v[132:133], v[132:133], v[140:141]
	global_store_dwordx4 v[148:149], v[144:147], off
	v_pk_mul_f32 v[128:129], v[128:129], v[136:137]
	v_pk_mul_f32 v[130:131], v[130:131], v[138:139]
	v_mov_b32_e32 v145, v132
	v_mov_b32_e32 v132, v141
	v_mov_b32_e32 v141, v134
	v_mov_b32_e32 v134, v143
	v_mov_b32_e32 v144, v140
	v_pk_mul_f32 v[132:133], v[132:133], v[132:133]
	v_mov_b32_e32 v140, v142
	v_pk_mul_f32 v[134:135], v[134:135], v[134:135]
	v_pk_fma_f32 v[132:133], v[144:145], v[144:145], v[132:133]
	v_pk_fma_f32 v[134:135], v[140:141], v[140:141], v[134:135]
	s_nop 0
	v_pk_add_f32 v[132:133], v[132:133], v[134:135]
	v_mov_b32_e32 v135, v128
	v_mov_b32_e32 v128, v137
	v_mov_b32_e32 v134, v136
	v_pk_mul_f32 v[128:129], v[128:129], v[128:129]
	s_nop 0
	v_pk_fma_f32 v[128:129], v[134:135], v[134:135], v[128:129]
	v_mov_b32_e32 v135, v130
	v_mov_b32_e32 v130, v139
	v_mov_b32_e32 v134, v138
	v_pk_mul_f32 v[130:131], v[130:131], v[130:131]
	s_nop 0
	v_pk_fma_f32 v[130:131], v[134:135], v[134:135], v[130:131]
	s_nop 0
	v_pk_add_f32 v[128:129], v[128:129], v[130:131]
	s_nop 0
	v_pk_add_f32 v[128:129], v[132:133], v[128:129]
	s_nop 0
	v_pk_add_f32 v[186:187], v[186:187], v[128:129]

;     static __device__ __forceinline__ void run(const f32x4 (&acc)[2][2][4][2], const Unit& u, int wr, int wc, int fr, int fq, const float* xin, float* xout, const float* gate, float gs, const float* lazy_ssq, const float* lazy_g, ...
;     ...
;                 gv[n] = *(const f32x4*)(gate + (b * 9216u + col + 4 * n)) * gs;
;                 lg[n] = (f32x4){1.f, 1.f, 1.f, 1.f}; if (LAZY) lg[n] = *(const f32x4*)(lazy_g + col + 4 * n);
;                 wv[n] = (f32x4){0.f, 0.f, 0.f, 0.f}; w2[n] = (f32x4){1.f, 1.f, 1.f, 1.f};
;                 if (aout) { wv[n] = *(const f32x4*)(wg + col + 4 * n) * (*(const f32x4*)(wsc + (b * 9216u + col + 4 * n)) + 1.0f); if (WG2) { w2[n] = *(const f32x4*)(wg2 + col + 4 * n); wv[n] = wv[n] * w2[n]; } }
;             }
;             f32x4 xq[2][2][2];
;     ...
;             constexpr bool DEEP = !LAZY && !WG2;
;             if (DEEP) RES_LD(0, 0);
; #pragma unroll
;             for (int pp = 0; pp < 4; ++pp) {
;                 if (DEEP) { if (pp < 3) RES_LD((pp + 1) & 1, pp + 1); } else RES_LD(pp & 1, pp);
; #pragma unroll
;                 for (int j = 0; j < 2; ++j) { const int i_ = 2 * pp + j, ai = i_ >> 2, m = i_ & 3; const unsigned off = (row0 + ai * HALF + m * 16) * 1024u + col;
;                     const f32x4 xi0 = xq[pp & 1][j][0], xi1 = xq[pp & 1][j][1];
;                     f32x4 xo0 = gv[0] * acc[ai][bj][m][0], xo1 = gv[1] * acc[ai][bj][m][1];
;                     if (LAZY) { xo0 = xo0 + xi0 * lg[0] * rl[ai][m]; xo1 = xo1 + xi1 * lg[1] * rl[ai][m]; } else { xo0 = xo0 + xi0; xo1 = xo1 + xi1; }
;                     *(f32x4*)(xout + off) = xo0; *(f32x4*)(xout + off + 4) = xo1;
;                     if (aout) { const f32x4 a0 = xo0 * wv[0], a1 = xo1 * wv[1]; u32x4 w; w.x = cvt_pk_bf16(a0[0], a0[1]); w.y = cvt_pk_bf16(a0[2], a0[3]); w.z = cvt_pk_bf16(a1[0], a1[1]); w.w = cvt_pk_bf16(a1[2], a1[3]);
;                         *(u32x4*)(aout + off) = w;
;                         sq[ai][m] += ((xo0[0] * xo0[0] + xo0[1] * xo0[1]) + (xo0[2] * xo0[2] + xo0[3] * xo0[3])) + ((xo1[0] * xo1[0] + xo1[1] * xo1[1]) + (xo1[2] * xo1[2] + xo1[3] * xo1[3]));
;                         if (WG2) { const f32x4 b0 = xo0 * w2[0], b1 = xo1 * w2[1]; sqb[ai][m] += ((b0[0] * b0[0] + b0[1] * b0[1]) + (b0[2] * b0[2] + b0[3] * b0[3])) + ((b1[0] * b1[0] + b1[1] * b1[1]) + (b1[2] * b1[2] + b1[3] * b1[3])); } } }
.LBB0_487:
	s_lshl_b32 s42, s63, 8
	s_lshl_b32 s43, s65, 6
	s_add_i32 s43, s43, s42
	v_or_b32_e32 v172, s43, v230
	v_lshlrev_b32_e32 v207, 10, v172
	v_add_u32_e32 v176, v180, v207
	v_lshlrev_b64 v[204:205], 2, v[176:177]
	s_waitcnt vmcnt(0)
	v_pk_mul_f32 v[196:197], s[36:37], v[128:129] op_sel_hi:[0,1]
	v_lshl_add_u64 v[128:129], s[34:35], 0, v[204:205]
	v_add_u32_e32 v202, 0x4000, v176
	v_mov_b32_e32 v203, v177
	global_load_dwordx4 v[152:155], v[128:129], off offset:16
	global_load_dwordx4 v[156:159], v[128:129], off
	v_lshl_add_u64 v[128:129], v[202:203], 2, s[34:35]
	v_add_u32_e32 v200, 0x8000, v176
	v_mov_b32_e32 v201, v177
	v_add_u32_e32 v198, 0xc000, v176
	v_mov_b32_e32 v199, v177
	v_pk_mul_f32 v[190:191], s[36:37], v[132:133] op_sel_hi:[0,1]
	global_load_dwordx4 v[136:139], v[128:129], off offset:16
	global_load_dwordx4 v[144:147], v[128:129], off
	v_lshl_add_u64 v[128:129], v[200:201], 2, s[34:35]
	v_lshl_add_u64 v[132:133], v[198:199], 2, s[34:35]
	v_pk_mul_f32 v[192:193], s[36:37], v[134:135] op_sel_hi:[0,1]
	v_pk_mul_f32 v[194:195], s[36:37], v[130:131] op_sel_hi:[0,1]
	global_load_dwordx4 v[140:143], v[128:129], off offset:16
	global_load_dwordx4 v[148:151], v[128:129], off
	s_nop 0
	global_load_dwordx4 v[128:131], v[132:133], off offset:16
	s_nop 0
	global_load_dwordx4 v[132:135], v[132:133], off
	v_lshl_add_u64 v[204:205], s[28:29], 0, v[204:205]
	s_and_b64 vcc, exec, s[8:9]
	v_mov_b32_e32 v173, 0
	s_waitcnt vmcnt(0)
	v_pk_fma_f32 v[154:155], v[122:123], v[192:193], v[154:155]
	s_waitcnt vmcnt(0)
	v_pk_fma_f32 v[158:159], v[126:127], v[194:195], v[158:159]
	v_pk_fma_f32 v[156:157], v[124:125], v[196:197], v[156:157]
	v_pk_fma_f32 v[152:153], v[120:121], v[190:191], v[152:153]
	global_store_dwordx4 v[204:205], v[156:159], off nt
	global_store_dwordx4 v[204:205], v[152:155], off offset:16 nt
	v_mov_b32_e32 v204, 0
	s_cbranch_vccnz .LBB0_489
	v_pk_mul_f32 v[210:211], v[184:185], v[158:159]
	v_pk_mul_f32 v[208:209], v[182:183], v[156:157]
	v_pk_mul_f32 v[212:213], v[188:189], v[154:155]
	v_pk_mul_f32 v[214:215], v[186:187], v[152:153]
	v_cvt_pk_bf16_f32 v208, v208, v209
	v_cvt_pk_bf16_f32 v209, v210, v211
	s_nop 0
	v_cvt_pk_bf16_f32 v210, v214, v215
	v_cvt_pk_bf16_f32 v211, v212, v213
	v_lshl_add_u64 v[212:213], v[176:177], 1, s[26:27]
	global_store_dwordx4 v[212:213], v[208:211], off
	s_nop 1
	v_mov_b32_e32 v209, v152
	v_mov_b32_e32 v152, v157
	v_mov_b32_e32 v157, v154
	v_mov_b32_e32 v154, v159
	v_mov_b32_e32 v208, v156
	v_pk_mul_f32 v[152:153], v[152:153], v[152:153]
	v_mov_b32_e32 v156, v158
	v_pk_mul_f32 v[154:155], v[154:155], v[154:155]
	v_pk_fma_f32 v[152:153], v[208:209], v[208:209], v[152:153]
	v_pk_fma_f32 v[154:155], v[156:157], v[156:157], v[154:155]
	s_nop 0
	v_pk_add_f32 v[152:153], v[152:153], v[154:155]
	s_nop 0
	v_add_f32_e32 v173, v152, v153
.LBB0_489:
	s_waitcnt vmcnt(0)
	v_pk_fma_f32 v[146:147], v[110:111], v[194:195], v[146:147]
	v_pk_fma_f32 v[144:145], v[108:109], v[196:197], v[144:145]
	v_pk_fma_f32 v[138:139], v[106:107], v[192:193], v[138:139]
	v_pk_fma_f32 v[136:137], v[104:105], v[190:191], v[136:137]
	v_lshl_add_u64 v[152:153], v[202:203], 2, s[28:29]
	s_and_b64 vcc, exec, s[8:9]
	global_store_dwordx4 v[152:153], v[144:147], off nt
	global_store_dwordx4 v[152:153], v[136:139], off offset:16 nt
	s_cbranch_vccnz .LBB0_491
	v_pk_mul_f32 v[154:155], v[184:185], v[146:147]
	v_pk_mul_f32 v[152:153], v[182:183], v[144:145]
	v_pk_mul_f32 v[156:157], v[188:189], v[138:139]
	v_pk_mul_f32 v[158:159], v[186:187], v[136:137]
	v_cvt_pk_bf16_f32 v152, v152, v153
	v_cvt_pk_bf16_f32 v153, v154, v155
	s_nop 0
	v_cvt_pk_bf16_f32 v154, v158, v159
	v_cvt_pk_bf16_f32 v155, v156, v157
	v_lshl_add_u64 v[156:157], v[202:203], 1, s[26:27]
	global_store_dwordx4 v[156:157], v[152:155], off
	s_nop 1
	v_mov_b32_e32 v153, v136
	v_mov_b32_e32 v136, v145
	v_mov_b32_e32 v145, v138
	v_mov_b32_e32 v138, v147
	v_mov_b32_e32 v152, v144
	v_pk_mul_f32 v[136:137], v[136:137], v[136:137]
	v_mov_b32_e32 v144, v146
	v_pk_mul_f32 v[138:139], v[138:139], v[138:139]
	v_pk_fma_f32 v[136:137], v[152:153], v[152:153], v[136:137]
	v_pk_fma_f32 v[138:139], v[144:145], v[144:145], v[138:139]
	s_nop 0
	v_pk_add_f32 v[136:137], v[136:137], v[138:139]
	s_nop 0
	v_add_f32_e32 v204, v136, v137
.LBB0_491:
	v_add_u32_e32 v208, 0x20000, v207
	v_add_u32_e32 v202, v208, v180
	v_mov_b32_e32 v203, v177
	v_lshl_add_u64 v[136:137], v[202:203], 2, s[34:35]
	global_load_dwordx4 v[152:155], v[136:137], off offset:16
	global_load_dwordx4 v[156:159], v[136:137], off
	v_add_u32_e32 v136, 0x4000, v202
	v_mov_b32_e32 v137, v177
	v_lshl_add_u64 v[144:145], v[136:137], 2, s[34:35]
	global_load_dwordx4 v[136:139], v[144:145], off offset:16
	s_nop 0
	global_load_dwordx4 v[144:147], v[144:145], off
	s_waitcnt vmcnt(0)
	v_pk_fma_f32 v[150:151], v[94:95], v[194:195], v[150:151]
	v_pk_fma_f32 v[148:149], v[92:93], v[196:197], v[148:149]
	v_pk_fma_f32 v[142:143], v[90:91], v[192:193], v[142:143]
	v_pk_fma_f32 v[140:141], v[88:89], v[190:191], v[140:141]
	v_lshl_add_u64 v[210:211], v[200:201], 2, s[28:29]
	v_mov_b32_e32 v203, 0
	s_and_b64 vcc, exec, s[8:9]
	v_mov_b32_e32 v205, 0
	global_store_dwordx4 v[210:211], v[148:151], off nt
	global_store_dwordx4 v[210:211], v[140:143], off offset:16 nt
	s_cbranch_vccnz .LBB0_493
	v_pk_mul_f32 v[212:213], v[184:185], v[150:151]
	v_pk_mul_f32 v[210:211], v[182:183], v[148:149]
	v_lshl_add_u64 v[200:201], v[200:201], 1, s[26:27]
	v_pk_mul_f32 v[214:215], v[188:189], v[142:143]
	v_pk_mul_f32 v[232:233], v[186:187], v[140:141]
	v_cvt_pk_bf16_f32 v210, v210, v211
	v_cvt_pk_bf16_f32 v211, v212, v213
	s_nop 0
	v_cvt_pk_bf16_f32 v212, v232, v233
	v_cvt_pk_bf16_f32 v213, v214, v215
	global_store_dwordx4 v[200:201], v[210:213], off
	v_mov_b32_e32 v201, v140
	v_mov_b32_e32 v140, v149
	v_mov_b32_e32 v149, v142
	v_mov_b32_e32 v142, v151
	v_mov_b32_e32 v200, v148
	v_pk_mul_f32 v[140:141], v[140:141], v[140:141]
	v_mov_b32_e32 v148, v150
	v_pk_mul_f32 v[142:143], v[142:143], v[142:143]
	v_pk_fma_f32 v[140:141], v[200:201], v[200:201], v[140:141]
	v_pk_fma_f32 v[142:143], v[148:149], v[148:149], v[142:143]
	s_nop 0
	v_pk_add_f32 v[140:141], v[140:141], v[142:143]
	s_nop 0
	v_add_f32_e32 v205, v140, v141
; __device__ __forceinline__ unsigned cvt_pk_bf16(float lo, float hi) { unsigned r; asm volatile("v_cvt_pk_bf16_f32 %0, %1, %2" : "=v"(r) : "v"(lo), "v"(hi)); return r; }
; #define RES_LD(buf, pp) do { _Pragma("unroll") for (int j = 0; j < 2; ++j) { const int i_ = 2 * (pp) + j; const unsigned off_ = (row0 + (i_ >> 2) * HALF + (i_ & 3) * 16) * 1024u + col; \
;                 xq[buf][j][0] = *(const f32x4*)(xin + off_); xq[buf][j][1] = *(const f32x4*)(xin + off_ + 4); } } while (0)
;     static __device__ __forceinline__ void run(const f32x4 (&acc)[2][2][4][2], const Unit& u, int wr, int wc, int fr, int fq, const float* xin, float* xout, const float* gate, float gs, const float* lazy_ssq, const float* lazy_g, ...
;     ...
;             constexpr bool DEEP = !LAZY && !WG2;
;             if (DEEP) RES_LD(0, 0);
; #pragma unroll
;             for (int pp = 0; pp < 4; ++pp) {
;                 if (DEEP) { if (pp < 3) RES_LD((pp + 1) & 1, pp + 1); } else RES_LD(pp & 1, pp);
; #pragma unroll
;                 for (int j = 0; j < 2; ++j) { const int i_ = 2 * pp + j, ai = i_ >> 2, m = i_ & 3; const unsigned off = (row0 + ai * HALF + m * 16) * 1024u + col;
;                     const f32x4 xi0 = xq[pp & 1][j][0], xi1 = xq[pp & 1][j][1];
;                     f32x4 xo0 = gv[0] * acc[ai][bj][m][0], xo1 = gv[1] * acc[ai][bj][m][1];
;                     if (LAZY) { xo0 = xo0 + xi0 * lg[0] * rl[ai][m]; xo1 = xo1 + xi1 * lg[1] * rl[ai][m]; } else { xo0 = xo0 + xi0; xo1 = xo1 + xi1; }
;                     *(f32x4*)(xout + off) = xo0; *(f32x4*)(xout + off + 4) = xo1;
;                     if (aout) { const f32x4 a0 = xo0 * wv[0], a1 = xo1 * wv[1]; u32x4 w; w.x = cvt_pk_bf16(a0[0], a0[1]); w.y = cvt_pk_bf16(a0[2], a0[3]); w.z = cvt_pk_bf16(a1[0], a1[1]); w.w = cvt_pk_bf16(a1[2], a1[3]);
;                         *(u32x4*)(aout + off) = w;
;                         sq[ai][m] += ((xo0[0] * xo0[0] + xo0[1] * xo0[1]) + (xo0[2] * xo0[2] + xo0[3] * xo0[3])) + ((xo1[0] * xo1[0] + xo1[1] * xo1[1]) + (xo1[2] * xo1[2] + xo1[3] * xo1[3]));
;                         if (WG2) { const f32x4 b0 = xo0 * w2[0], b1 = xo1 * w2[1]; sqb[ai][m] += ((b0[0] * b0[0] + b0[1] * b0[1]) + (b0[2] * b0[2] + b0[3] * b0[3])) + ((b1[0] * b1[0] + b1[1] * b1[1]) + (b1[2] * b1[2] + b1[3] * b1[3])); } } }
.LBB0_493:
	s_waitcnt vmcnt(0)
	v_pk_fma_f32 v[134:135], v[78:79], v[194:195], v[134:135]
	v_pk_fma_f32 v[132:133], v[76:77], v[196:197], v[132:133]
	v_pk_fma_f32 v[130:131], v[74:75], v[192:193], v[130:131]
	v_pk_fma_f32 v[128:129], v[72:73], v[190:191], v[128:129]
	v_lshl_add_u64 v[140:141], v[198:199], 2, s[28:29]
	s_and_b64 vcc, exec, s[8:9]
	global_store_dwordx4 v[140:141], v[132:135], off nt
	global_store_dwordx4 v[140:141], v[128:131], off offset:16 nt
	s_cbranch_vccnz .LBB0_495
	v_pk_mul_f32 v[142:143], v[184:185], v[134:135]
	v_pk_mul_f32 v[140:141], v[182:183], v[132:133]
	v_pk_mul_f32 v[148:149], v[188:189], v[130:131]
	v_pk_mul_f32 v[150:151], v[186:187], v[128:129]
	v_cvt_pk_bf16_f32 v140, v140, v141
	v_cvt_pk_bf16_f32 v141, v142, v143
	s_nop 0
	v_cvt_pk_bf16_f32 v142, v150, v151
	v_cvt_pk_bf16_f32 v143, v148, v149
	v_lshl_add_u64 v[148:149], v[198:199], 1, s[26:27]
	global_store_dwordx4 v[148:149], v[140:143], off
	s_nop 1
	v_mov_b32_e32 v141, v128
	v_mov_b32_e32 v128, v133
	v_mov_b32_e32 v133, v130
	v_mov_b32_e32 v130, v135
	v_mov_b32_e32 v140, v132
	v_pk_mul_f32 v[128:129], v[128:129], v[128:129]
	v_mov_b32_e32 v132, v134
	v_pk_mul_f32 v[130:131], v[130:131], v[130:131]
	v_pk_fma_f32 v[128:129], v[140:141], v[140:141], v[128:129]
	v_pk_fma_f32 v[130:131], v[132:133], v[132:133], v[130:131]
	s_nop 0
	v_pk_add_f32 v[128:129], v[128:129], v[130:131]
	s_nop 0
	v_add_f32_e32 v203, v128, v129
.LBB0_495:
	s_nop 0
	v_add_u32_e32 v128, 0x8000, v202
	v_mov_b32_e32 v129, v177
	v_lshl_add_u64 v[128:129], v[128:129], 2, s[34:35]
	global_load_dwordx4 v[140:143], v[128:129], off offset:16
	global_load_dwordx4 v[148:151], v[128:129], off
	v_add_u32_e32 v128, 0xc000, v202
	v_mov_b32_e32 v129, v177
	v_lshl_add_u64 v[132:133], v[128:129], 2, s[34:35]
	global_load_dwordx4 v[128:131], v[132:133], off offset:16
	s_nop 0
	global_load_dwordx4 v[132:135], v[132:133], off
	v_add_u32_e32 v198, 0x20000, v176
	v_mov_b32_e32 v199, v177
	s_waitcnt vmcnt(0)
	v_pk_fma_f32 v[158:159], v[62:63], v[194:195], v[158:159]
	v_pk_fma_f32 v[156:157], v[60:61], v[196:197], v[156:157]
	v_lshl_add_u64 v[200:201], v[198:199], 2, s[28:29]
	v_pk_fma_f32 v[154:155], v[58:59], v[192:193], v[154:155]
	v_pk_fma_f32 v[152:153], v[56:57], v[190:191], v[152:153]
	global_store_dwordx4 v[200:201], v[156:159], off nt
	global_store_dwordx4 v[200:201], v[152:155], off offset:16 nt
	v_mov_b32_e32 v200, 0
	s_and_b64 vcc, exec, s[8:9]
	v_mov_b32_e32 v201, 0
	s_cbranch_vccnz .LBB0_497
	v_pk_mul_f32 v[212:213], v[184:185], v[158:159]
	v_pk_mul_f32 v[210:211], v[182:183], v[156:157]
	v_lshl_add_u64 v[198:199], v[198:199], 1, s[26:27]
	v_pk_mul_f32 v[214:215], v[188:189], v[154:155]
	v_pk_mul_f32 v[232:233], v[186:187], v[152:153]
	v_cvt_pk_bf16_f32 v210, v210, v211
	v_cvt_pk_bf16_f32 v211, v212, v213
	s_nop 0
	v_cvt_pk_bf16_f32 v212, v232, v233
	v_cvt_pk_bf16_f32 v213, v214, v215
	global_store_dwordx4 v[198:199], v[210:213], off
	v_mov_b32_e32 v199, v152
	v_mov_b32_e32 v152, v157
	v_mov_b32_e32 v157, v154
	v_mov_b32_e32 v154, v159
	v_mov_b32_e32 v198, v156
	v_pk_mul_f32 v[152:153], v[152:153], v[152:153]
	v_mov_b32_e32 v156, v158
	v_pk_mul_f32 v[154:155], v[154:155], v[154:155]
	v_pk_fma_f32 v[152:153], v[198:199], v[198:199], v[152:153]
	v_pk_fma_f32 v[154:155], v[156:157], v[156:157], v[154:155]
	s_nop 0
	v_pk_add_f32 v[152:153], v[152:153], v[154:155]
	s_nop 0
	v_add_f32_e32 v201, v152, v153
; __device__ __forceinline__ unsigned cvt_pk_bf16(float lo, float hi) { unsigned r; asm volatile("v_cvt_pk_bf16_f32 %0, %1, %2" : "=v"(r) : "v"(lo), "v"(hi)); return r; }
;     static __device__ __forceinline__ void run(const f32x4 (&acc)[2][2][4][2], const Unit& u, int wr, int wc, int fr, int fq, const float* xin, float* xout, const float* gate, float gs, const float* lazy_ssq, const float* lazy_g, ...
;     ...
;                 for (int j = 0; j < 2; ++j) { const int i_ = 2 * pp + j, ai = i_ >> 2, m = i_ & 3; const unsigned off = (row0 + ai * HALF + m * 16) * 1024u + col;
;                     const f32x4 xi0 = xq[pp & 1][j][0], xi1 = xq[pp & 1][j][1];
;                     f32x4 xo0 = gv[0] * acc[ai][bj][m][0], xo1 = gv[1] * acc[ai][bj][m][1];
;                     if (LAZY) { xo0 = xo0 + xi0 * lg[0] * rl[ai][m]; xo1 = xo1 + xi1 * lg[1] * rl[ai][m]; } else { xo0 = xo0 + xi0; xo1 = xo1 + xi1; }
;                     *(f32x4*)(xout + off) = xo0; *(f32x4*)(xout + off + 4) = xo1;
;                     if (aout) { const f32x4 a0 = xo0 * wv[0], a1 = xo1 * wv[1]; u32x4 w; w.x = cvt_pk_bf16(a0[0], a0[1]); w.y = cvt_pk_bf16(a0[2], a0[3]); w.z = cvt_pk_bf16(a1[0], a1[1]); w.w = cvt_pk_bf16(a1[2], a1[3]);
;                         *(u32x4*)(aout + off) = w;
;                         sq[ai][m] += ((xo0[0] * xo0[0] + xo0[1] * xo0[1]) + (xo0[2] * xo0[2] + xo0[3] * xo0[3])) + ((xo1[0] * xo1[0] + xo1[1] * xo1[1]) + (xo1[2] * xo1[2] + xo1[3] * xo1[3]));
;                         if (WG2) { const f32x4 b0 = xo0 * w2[0], b1 = xo1 * w2[1]; sqb[ai][m] += ((b0[0] * b0[0] + b0[1] * b0[1]) + (b0[2] * b0[2] + b0[3] * b0[3])) + ((b1[0] * b1[0] + b1[1] * b1[1]) + (b1[2] * b1[2] + b1[3] * b1[3])); } } }
.LBB0_497:
	v_add_u32_e32 v152, 0x24000, v176
	v_mov_b32_e32 v153, v177
	s_waitcnt vmcnt(0)
	v_pk_fma_f32 v[146:147], v[46:47], v[194:195], v[146:147]
	v_pk_fma_f32 v[144:145], v[44:45], v[196:197], v[144:145]
	v_pk_fma_f32 v[138:139], v[42:43], v[192:193], v[138:139]
	v_pk_fma_f32 v[136:137], v[40:41], v[190:191], v[136:137]
	v_lshl_add_u64 v[154:155], v[152:153], 2, s[28:29]
	s_and_b64 vcc, exec, s[8:9]
	global_store_dwordx4 v[154:155], v[144:147], off nt
	global_store_dwordx4 v[154:155], v[136:139], off offset:16 nt
	s_cbranch_vccnz .LBB0_499
	v_pk_mul_f32 v[156:157], v[184:185], v[146:147]
	v_pk_mul_f32 v[154:155], v[182:183], v[144:145]
	v_lshl_add_u64 v[152:153], v[152:153], 1, s[26:27]
	v_pk_mul_f32 v[158:159], v[188:189], v[138:139]
	v_pk_mul_f32 v[198:199], v[186:187], v[136:137]
	v_cvt_pk_bf16_f32 v154, v154, v155
	v_cvt_pk_bf16_f32 v155, v156, v157
	s_nop 0
	v_cvt_pk_bf16_f32 v156, v198, v199
	v_cvt_pk_bf16_f32 v157, v158, v159
	global_store_dwordx4 v[152:153], v[154:157], off
	v_mov_b32_e32 v153, v136
	v_mov_b32_e32 v136, v145
	v_mov_b32_e32 v145, v138
	v_mov_b32_e32 v138, v147
	v_mov_b32_e32 v152, v144
	v_pk_mul_f32 v[136:137], v[136:137], v[136:137]
	v_mov_b32_e32 v144, v146
	v_pk_mul_f32 v[138:139], v[138:139], v[138:139]
	v_pk_fma_f32 v[136:137], v[152:153], v[152:153], v[136:137]
	v_pk_fma_f32 v[138:139], v[144:145], v[144:145], v[138:139]
	s_nop 0
	v_pk_add_f32 v[136:137], v[136:137], v[138:139]
	s_nop 0
	v_add_f32_e32 v200, v136, v137
.LBB0_499:
	v_add_u32_e32 v144, 0x28000, v176
	v_mov_b32_e32 v145, v177
	s_waitcnt vmcnt(0)
	v_pk_fma_f32 v[138:139], v[30:31], v[194:195], v[150:151]
	v_pk_fma_f32 v[136:137], v[28:29], v[196:197], v[148:149]
	v_pk_fma_f32 v[142:143], v[26:27], v[192:193], v[142:143]
	v_pk_fma_f32 v[140:141], v[24:25], v[190:191], v[140:141]
	v_lshl_add_u64 v[146:147], v[144:145], 2, s[28:29]
	v_mov_b32_e32 v202, 0
	s_and_b64 vcc, exec, s[8:9]
	v_mov_b32_e32 v206, 0
	global_store_dwordx4 v[146:147], v[136:139], off nt
	global_store_dwordx4 v[146:147], v[140:143], off offset:16 nt
	s_cbranch_vccnz .LBB0_501
	v_pk_mul_f32 v[148:149], v[184:185], v[138:139]
	v_pk_mul_f32 v[146:147], v[182:183], v[136:137]
	v_lshl_add_u64 v[144:145], v[144:145], 1, s[26:27]
	v_pk_mul_f32 v[150:151], v[188:189], v[142:143]
	v_pk_mul_f32 v[152:153], v[186:187], v[140:141]
	v_cvt_pk_bf16_f32 v146, v146, v147
	v_cvt_pk_bf16_f32 v147, v148, v149
	s_nop 0
	v_cvt_pk_bf16_f32 v148, v152, v153
	v_cvt_pk_bf16_f32 v149, v150, v151
	global_store_dwordx4 v[144:145], v[146:149], off
	v_mov_b32_e32 v145, v140
	v_mov_b32_e32 v140, v137
	v_mov_b32_e32 v144, v136
	v_pk_mul_f32 v[136:137], v[140:141], v[140:141]
	v_mov_b32_e32 v141, v142
	v_mov_b32_e32 v142, v139
	v_mov_b32_e32 v140, v138
	v_pk_mul_f32 v[138:139], v[142:143], v[142:143]
	v_pk_fma_f32 v[136:137], v[144:145], v[144:145], v[136:137]
	v_pk_fma_f32 v[138:139], v[140:141], v[140:141], v[138:139]
	s_nop 0
	v_pk_add_f32 v[136:137], v[136:137], v[138:139]
	s_nop 0
	v_add_f32_e32 v206, v136, v137
.LBB0_501:
	v_add_u32_e32 v176, 0x2c000, v176
	s_waitcnt vmcnt(0)
	v_pk_fma_f32 v[134:135], v[14:15], v[194:195], v[134:135]
	v_pk_fma_f32 v[132:133], v[12:13], v[196:197], v[132:133]
	v_pk_fma_f32 v[130:131], v[10:11], v[192:193], v[130:131]
	v_pk_fma_f32 v[128:129], v[8:9], v[190:191], v[128:129]
	v_lshl_add_u64 v[136:137], v[176:177], 2, s[28:29]
	s_and_b64 vcc, exec, s[8:9]
	global_store_dwordx4 v[136:137], v[132:135], off nt
	global_store_dwordx4 v[136:137], v[128:131], off offset:16 nt
	s_cbranch_vccnz .LBB0_503
	v_pk_mul_f32 v[138:139], v[184:185], v[134:135]
	v_pk_mul_f32 v[136:137], v[182:183], v[132:133]
	v_pk_mul_f32 v[140:141], v[188:189], v[130:131]
	v_pk_mul_f32 v[142:143], v[186:187], v[128:129]
	v_cvt_pk_bf16_f32 v136, v136, v137
	v_cvt_pk_bf16_f32 v137, v138, v139
	s_nop 0
	v_cvt_pk_bf16_f32 v138, v142, v143
	v_cvt_pk_bf16_f32 v139, v140, v141
	v_lshl_add_u64 v[140:141], v[176:177], 1, s[26:27]
	global_store_dwordx4 v[140:141], v[136:139], off
	s_nop 1
	v_mov_b32_e32 v137, v128
	v_mov_b32_e32 v128, v133
	v_mov_b32_e32 v133, v130
	v_mov_b32_e32 v130, v135
	v_mov_b32_e32 v136, v132
	v_pk_mul_f32 v[128:129], v[128:129], v[128:129]
	v_mov_b32_e32 v132, v134
	v_pk_mul_f32 v[130:131], v[130:131], v[130:131]
	v_pk_fma_f32 v[128:129], v[136:137], v[136:137], v[128:129]
	v_pk_fma_f32 v[130:131], v[132:133], v[132:133], v[130:131]
	s_nop 0
	v_pk_add_f32 v[128:129], v[128:129], v[130:131]
	s_nop 0
	v_add_f32_e32 v202, v128, v129

;     static __device__ __forceinline__ void run(const f32x4 (&acc)[2][2][4][2], const Unit& u, int wr, int wc, int fr, int fq, const float* xin, float* xout, const float* gate, float gs, const float* lazy_ssq, const float* lazy_g, ...
;     ...
;                 gv[n] = *(const f32x4*)(gate + (b * 9216u + col + 4 * n)) * gs;
;                 lg[n] = (f32x4){1.f, 1.f, 1.f, 1.f}; if (LAZY) lg[n] = *(const f32x4*)(lazy_g + col + 4 * n);
;                 wv[n] = (f32x4){0.f, 0.f, 0.f, 0.f}; w2[n] = (f32x4){1.f, 1.f, 1.f, 1.f};
;                 if (aout) { wv[n] = *(const f32x4*)(wg + col + 4 * n) * (*(const f32x4*)(wsc + (b * 9216u + col + 4 * n)) + 1.0f); if (WG2) { w2[n] = *(const f32x4*)(wg2 + col + 4 * n); wv[n] = wv[n] * w2[n]; } }
;             }
;             f32x4 xq[2][2][2];
;     ...
;             constexpr bool DEEP = !LAZY && !WG2;
;             if (DEEP) RES_LD(0, 0);
; #pragma unroll
;             for (int pp = 0; pp < 4; ++pp) {
;                 if (DEEP) { if (pp < 3) RES_LD((pp + 1) & 1, pp + 1); } else RES_LD(pp & 1, pp);
; #pragma unroll
;                 for (int j = 0; j < 2; ++j) { const int i_ = 2 * pp + j, ai = i_ >> 2, m = i_ & 3; const unsigned off = (row0 + ai * HALF + m * 16) * 1024u + col;
;                     const f32x4 xi0 = xq[pp & 1][j][0], xi1 = xq[pp & 1][j][1];
;                     f32x4 xo0 = gv[0] * acc[ai][bj][m][0], xo1 = gv[1] * acc[ai][bj][m][1];
;                     if (LAZY) { xo0 = xo0 + xi0 * lg[0] * rl[ai][m]; xo1 = xo1 + xi1 * lg[1] * rl[ai][m]; } else { xo0 = xo0 + xi0; xo1 = xo1 + xi1; }
;                     *(f32x4*)(xout + off) = xo0; *(f32x4*)(xout + off + 4) = xo1;
;                     if (aout) { const f32x4 a0 = xo0 * wv[0], a1 = xo1 * wv[1]; u32x4 w; w.x = cvt_pk_bf16(a0[0], a0[1]); w.y = cvt_pk_bf16(a0[2], a0[3]); w.z = cvt_pk_bf16(a1[0], a1[1]); w.w = cvt_pk_bf16(a1[2], a1[3]);
;                         *(u32x4*)(aout + off) = w;
;                         sq[ai][m] += ((xo0[0] * xo0[0] + xo0[1] * xo0[1]) + (xo0[2] * xo0[2] + xo0[3] * xo0[3])) + ((xo1[0] * xo1[0] + xo1[1] * xo1[1]) + (xo1[2] * xo1[2] + xo1[3] * xo1[3]));
;                         if (WG2) { const f32x4 b0 = xo0 * w2[0], b1 = xo1 * w2[1]; sqb[ai][m] += ((b0[0] * b0[0] + b0[1] * b0[1]) + (b0[2] * b0[2] + b0[3] * b0[3])) + ((b1[0] * b1[0] + b1[1] * b1[1]) + (b1[2] * b1[2] + b1[3] * b1[3])); } } }
.LBB0_507:
	v_add_u32_e32 v176, v209, v207
	v_lshlrev_b64 v[214:215], 2, v[176:177]
	v_lshl_add_u64 v[128:129], s[34:35], 0, v[214:215]
	v_add_u32_e32 v198, 0x4000, v176
	v_mov_b32_e32 v199, v177
	global_load_dwordx4 v[210:213], v[128:129], off offset:16
	global_load_dwordx4 v[232:235], v[128:129], off
	v_lshl_add_u64 v[128:129], v[198:199], 2, s[34:35]
	v_add_u32_e32 v196, 0x8000, v176
	v_mov_b32_e32 v197, v177
	v_add_u32_e32 v194, 0xc000, v176
	v_mov_b32_e32 v195, v177
	global_load_dwordx4 v[132:135], v[128:129], off offset:16
	global_load_dwordx4 v[152:155], v[128:129], off
	v_lshl_add_u64 v[128:129], v[196:197], 2, s[34:35]
	v_lshl_add_u64 v[136:137], v[194:195], 2, s[34:35]
	global_load_dwordx4 v[144:147], v[128:129], off offset:16
	global_load_dwordx4 v[148:151], v[128:129], off
	s_nop 0
	global_load_dwordx4 v[128:131], v[136:137], off offset:16
	s_nop 0
	global_load_dwordx4 v[136:139], v[136:137], off
	s_mov_b32 s37, s36
	s_mov_b32 s38, s36
	s_mov_b32 s39, s36
	s_waitcnt vmcnt(8)
	v_pk_mul_f32 v[188:189], s[38:39], v[158:159]
	v_pk_mul_f32 v[174:175], s[36:37], v[156:157]
	v_pk_mul_f32 v[190:191], s[38:39], v[142:143]
	v_pk_mul_f32 v[192:193], s[36:37], v[140:141]
	s_and_b64 vcc, exec, s[8:9]
	v_lshl_add_u64 v[214:215], s[28:29], 0, v[214:215]
	s_waitcnt vmcnt(0)
	v_pk_fma_f32 v[142:143], v[114:115], v[188:189], v[212:213]
	s_waitcnt vmcnt(0)
	v_pk_fma_f32 v[158:159], v[118:119], v[190:191], v[234:235]
	v_pk_fma_f32 v[156:157], v[116:117], v[192:193], v[232:233]
	v_pk_fma_f32 v[140:141], v[112:113], v[174:175], v[210:211]
	global_store_dwordx4 v[214:215], v[156:159], off nt
	global_store_dwordx4 v[214:215], v[140:143], off offset:16 nt
	s_cbranch_vccnz .LBB0_509
	v_pk_mul_f32 v[212:213], v[184:185], v[158:159]
	v_pk_mul_f32 v[210:211], v[182:183], v[156:157]
	v_pk_mul_f32 v[214:215], v[186:187], v[142:143]
	v_pk_mul_f32 v[232:233], v[180:181], v[140:141]
	v_cvt_pk_bf16_f32 v210, v210, v211
	v_cvt_pk_bf16_f32 v211, v212, v213
	s_nop 0
	v_cvt_pk_bf16_f32 v212, v232, v233
	v_cvt_pk_bf16_f32 v213, v214, v215
	v_lshl_add_u64 v[214:215], v[176:177], 1, s[26:27]
	global_store_dwordx4 v[214:215], v[210:213], off
	s_nop 1
	v_mov_b32_e32 v211, v140
	v_mov_b32_e32 v140, v157
	v_mov_b32_e32 v157, v142
	v_mov_b32_e32 v142, v159
	v_mov_b32_e32 v210, v156
	v_pk_mul_f32 v[140:141], v[140:141], v[140:141]
	v_mov_b32_e32 v156, v158
	v_pk_mul_f32 v[142:143], v[142:143], v[142:143]
	v_pk_fma_f32 v[140:141], v[210:211], v[210:211], v[140:141]
	v_pk_fma_f32 v[142:143], v[156:157], v[156:157], v[142:143]
	s_nop 0
	v_pk_add_f32 v[140:141], v[140:141], v[142:143]
	s_nop 0
	v_add_f32_e32 v140, v140, v141
	v_add_f32_e32 v173, v173, v140
.LBB0_509:
	s_waitcnt vmcnt(0)
	v_pk_fma_f32 v[142:143], v[102:103], v[190:191], v[154:155]
	v_pk_fma_f32 v[140:141], v[100:101], v[192:193], v[152:153]
	v_pk_fma_f32 v[134:135], v[98:99], v[188:189], v[134:135]
	v_pk_fma_f32 v[132:133], v[96:97], v[174:175], v[132:133]
	v_lshl_add_u64 v[152:153], v[198:199], 2, s[28:29]
	s_and_b64 vcc, exec, s[8:9]
	global_store_dwordx4 v[152:153], v[140:143], off nt
	global_store_dwordx4 v[152:153], v[132:135], off offset:16 nt
	s_cbranch_vccnz .LBB0_511
	v_pk_mul_f32 v[154:155], v[184:185], v[142:143]
	v_pk_mul_f32 v[152:153], v[182:183], v[140:141]
	v_pk_mul_f32 v[156:157], v[186:187], v[134:135]
	v_pk_mul_f32 v[158:159], v[180:181], v[132:133]
	v_cvt_pk_bf16_f32 v152, v152, v153
	v_cvt_pk_bf16_f32 v153, v154, v155
	s_nop 0
	v_cvt_pk_bf16_f32 v154, v158, v159
	v_cvt_pk_bf16_f32 v155, v156, v157
	v_lshl_add_u64 v[156:157], v[198:199], 1, s[26:27]
	global_store_dwordx4 v[156:157], v[152:155], off
	s_nop 1
	v_mov_b32_e32 v153, v132
	v_mov_b32_e32 v132, v141
	v_mov_b32_e32 v141, v134
	v_mov_b32_e32 v134, v143
	v_mov_b32_e32 v152, v140
	v_pk_mul_f32 v[132:133], v[132:133], v[132:133]
	v_mov_b32_e32 v140, v142
	v_pk_mul_f32 v[134:135], v[134:135], v[134:135]
	v_pk_fma_f32 v[132:133], v[152:153], v[152:153], v[132:133]
	v_pk_fma_f32 v[134:135], v[140:141], v[140:141], v[134:135]
	s_nop 0
	v_pk_add_f32 v[132:133], v[132:133], v[134:135]
	s_nop 0
	v_add_f32_e32 v132, v132, v133
	v_add_f32_e32 v204, v204, v132
.LBB0_511:
	v_add_u32_e32 v198, v208, v209
	v_mov_b32_e32 v199, v177
	v_lshl_add_u64 v[132:133], v[198:199], 2, s[34:35]
	global_load_dwordx4 v[152:155], v[132:133], off offset:16
	global_load_dwordx4 v[156:159], v[132:133], off
	v_add_u32_e32 v132, 0x4000, v198
	v_mov_b32_e32 v133, v177
	v_lshl_add_u64 v[140:141], v[132:133], 2, s[34:35]
	global_load_dwordx4 v[132:135], v[140:141], off offset:16
	s_nop 0
	global_load_dwordx4 v[140:143], v[140:141], off
	s_waitcnt vmcnt(0)
	v_pk_fma_f32 v[150:151], v[86:87], v[190:191], v[150:151]
	v_pk_fma_f32 v[148:149], v[84:85], v[192:193], v[148:149]
	v_pk_fma_f32 v[146:147], v[82:83], v[188:189], v[146:147]
	v_pk_fma_f32 v[144:145], v[80:81], v[174:175], v[144:145]
	v_lshl_add_u64 v[208:209], v[196:197], 2, s[28:29]
	s_and_b64 vcc, exec, s[8:9]
	global_store_dwordx4 v[208:209], v[148:151], off nt
	global_store_dwordx4 v[208:209], v[144:147], off offset:16 nt
	s_cbranch_vccnz .LBB0_513
	v_pk_mul_f32 v[210:211], v[184:185], v[150:151]
	v_pk_mul_f32 v[208:209], v[182:183], v[148:149]
	v_lshl_add_u64 v[196:197], v[196:197], 1, s[26:27]
	v_pk_mul_f32 v[212:213], v[186:187], v[146:147]
	v_pk_mul_f32 v[214:215], v[180:181], v[144:145]
	v_cvt_pk_bf16_f32 v208, v208, v209
	v_cvt_pk_bf16_f32 v209, v210, v211
	s_nop 0
	v_cvt_pk_bf16_f32 v210, v214, v215
	v_cvt_pk_bf16_f32 v211, v212, v213
	global_store_dwordx4 v[196:197], v[208:211], off
	v_mov_b32_e32 v197, v144
	v_mov_b32_e32 v144, v149
	v_mov_b32_e32 v149, v146
	v_mov_b32_e32 v146, v151
	v_mov_b32_e32 v196, v148
	v_pk_mul_f32 v[144:145], v[144:145], v[144:145]
	v_mov_b32_e32 v148, v150
	v_pk_mul_f32 v[146:147], v[146:147], v[146:147]
	v_pk_fma_f32 v[144:145], v[196:197], v[196:197], v[144:145]
	v_pk_fma_f32 v[146:147], v[148:149], v[148:149], v[146:147]
	s_nop 0
	v_pk_add_f32 v[144:145], v[144:145], v[146:147]
	s_nop 0
	v_add_f32_e32 v144, v144, v145
	v_add_f32_e32 v205, v205, v144
;     static __device__ __forceinline__ void run(const f32x4 (&acc)[2][2][4][2], const Unit& u, int wr, int wc, int fr, int fq, const float* xin, float* xout, const float* gate, float gs, const float* lazy_ssq, const float* lazy_g, ...
;     ...
;                 gv[n] = *(const f32x4*)(gate + (b * 9216u + col + 4 * n)) * gs;
;                 lg[n] = (f32x4){1.f, 1.f, 1.f, 1.f}; if (LAZY) lg[n] = *(const f32x4*)(lazy_g + col + 4 * n);
;                 wv[n] = (f32x4){0.f, 0.f, 0.f, 0.f}; w2[n] = (f32x4){1.f, 1.f, 1.f, 1.f};
;                 if (aout) { wv[n] = *(const f32x4*)(wg + col + 4 * n) * (*(const f32x4*)(wsc + (b * 9216u + col + 4 * n)) + 1.0f); if (WG2) { w2[n] = *(const f32x4*)(wg2 + col + 4 * n); wv[n] = wv[n] * w2[n]; } }
;             }
;             f32x4 xq[2][2][2];
;     ...
;             constexpr bool DEEP = !LAZY && !WG2;
;             if (DEEP) RES_LD(0, 0);
; #pragma unroll
;             for (int pp = 0; pp < 4; ++pp) {
;                 if (DEEP) { if (pp < 3) RES_LD((pp + 1) & 1, pp + 1); } else RES_LD(pp & 1, pp);
; #pragma unroll
;                 for (int j = 0; j < 2; ++j) { const int i_ = 2 * pp + j, ai = i_ >> 2, m = i_ & 3; const unsigned off = (row0 + ai * HALF + m * 16) * 1024u + col;
;                     const f32x4 xi0 = xq[pp & 1][j][0], xi1 = xq[pp & 1][j][1];
;                     f32x4 xo0 = gv[0] * acc[ai][bj][m][0], xo1 = gv[1] * acc[ai][bj][m][1];
;                     if (LAZY) { xo0 = xo0 + xi0 * lg[0] * rl[ai][m]; xo1 = xo1 + xi1 * lg[1] * rl[ai][m]; } else { xo0 = xo0 + xi0; xo1 = xo1 + xi1; }
;                     *(f32x4*)(xout + off) = xo0; *(f32x4*)(xout + off + 4) = xo1;
;                     if (aout) { const f32x4 a0 = xo0 * wv[0], a1 = xo1 * wv[1]; u32x4 w; w.x = cvt_pk_bf16(a0[0], a0[1]); w.y = cvt_pk_bf16(a0[2], a0[3]); w.z = cvt_pk_bf16(a1[0], a1[1]); w.w = cvt_pk_bf16(a1[2], a1[3]);
;                         *(u32x4*)(aout + off) = w;
;                         sq[ai][m] += ((xo0[0] * xo0[0] + xo0[1] * xo0[1]) + (xo0[2] * xo0[2] + xo0[3] * xo0[3])) + ((xo1[0] * xo1[0] + xo1[1] * xo1[1]) + (xo1[2] * xo1[2] + xo1[3] * xo1[3]));
;                         if (WG2) { const f32x4 b0 = xo0 * w2[0], b1 = xo1 * w2[1]; sqb[ai][m] += ((b0[0] * b0[0] + b0[1] * b0[1]) + (b0[2] * b0[2] + b0[3] * b0[3])) + ((b1[0] * b1[0] + b1[1] * b1[1]) + (b1[2] * b1[2] + b1[3] * b1[3])); } } }
.LBB0_513:
	s_waitcnt vmcnt(0)
	v_pk_fma_f32 v[138:139], v[70:71], v[190:191], v[138:139]
	v_pk_fma_f32 v[136:137], v[68:69], v[192:193], v[136:137]
	v_pk_fma_f32 v[130:131], v[66:67], v[188:189], v[130:131]
	v_pk_fma_f32 v[128:129], v[64:65], v[174:175], v[128:129]
	v_lshl_add_u64 v[144:145], v[194:195], 2, s[28:29]
	s_and_b64 vcc, exec, s[8:9]
	global_store_dwordx4 v[144:145], v[136:139], off nt
	global_store_dwordx4 v[144:145], v[128:131], off offset:16 nt
	s_cbranch_vccnz .LBB0_515
	v_pk_mul_f32 v[146:147], v[184:185], v[138:139]
	v_pk_mul_f32 v[144:145], v[182:183], v[136:137]
	v_pk_mul_f32 v[148:149], v[186:187], v[130:131]
	v_pk_mul_f32 v[150:151], v[180:181], v[128:129]
	v_cvt_pk_bf16_f32 v144, v144, v145
	v_cvt_pk_bf16_f32 v145, v146, v147
	s_nop 0
	v_cvt_pk_bf16_f32 v146, v150, v151
	v_cvt_pk_bf16_f32 v147, v148, v149
	v_lshl_add_u64 v[148:149], v[194:195], 1, s[26:27]
	global_store_dwordx4 v[148:149], v[144:147], off
	s_nop 1
	v_mov_b32_e32 v145, v128
	v_mov_b32_e32 v128, v137
	v_mov_b32_e32 v137, v130
	v_mov_b32_e32 v130, v139
	v_mov_b32_e32 v144, v136
	v_pk_mul_f32 v[128:129], v[128:129], v[128:129]
	v_mov_b32_e32 v136, v138
	v_pk_mul_f32 v[130:131], v[130:131], v[130:131]
	v_pk_fma_f32 v[128:129], v[144:145], v[144:145], v[128:129]
	v_pk_fma_f32 v[130:131], v[136:137], v[136:137], v[130:131]
	s_nop 0
	v_pk_add_f32 v[128:129], v[128:129], v[130:131]
	s_nop 0
	v_add_f32_e32 v128, v128, v129
	v_add_f32_e32 v203, v203, v128
.LBB0_515:
	s_nop 0
	v_add_u32_e32 v128, 0x8000, v198
	v_mov_b32_e32 v129, v177
	v_lshl_add_u64 v[128:129], v[128:129], 2, s[34:35]
	global_load_dwordx4 v[144:147], v[128:129], off offset:16
	global_load_dwordx4 v[148:151], v[128:129], off
	v_add_u32_e32 v128, 0xc000, v198
	v_mov_b32_e32 v129, v177
	v_lshl_add_u64 v[136:137], v[128:129], 2, s[34:35]
	global_load_dwordx4 v[128:131], v[136:137], off offset:16
	s_nop 0
	global_load_dwordx4 v[136:139], v[136:137], off
	v_add_u32_e32 v194, 0x20000, v176
	v_mov_b32_e32 v195, v177
	s_waitcnt vmcnt(0)
	v_pk_fma_f32 v[158:159], v[54:55], v[190:191], v[158:159]
	v_pk_fma_f32 v[156:157], v[52:53], v[192:193], v[156:157]
	v_pk_fma_f32 v[154:155], v[50:51], v[188:189], v[154:155]
	v_pk_fma_f32 v[152:153], v[48:49], v[174:175], v[152:153]
	v_lshl_add_u64 v[196:197], v[194:195], 2, s[28:29]
	s_and_b64 vcc, exec, s[8:9]
	global_store_dwordx4 v[196:197], v[156:159], off nt
	global_store_dwordx4 v[196:197], v[152:155], off offset:16 nt
	s_cbranch_vccnz .LBB0_517
	v_pk_mul_f32 v[198:199], v[184:185], v[158:159]
	v_pk_mul_f32 v[196:197], v[182:183], v[156:157]
	v_lshl_add_u64 v[194:195], v[194:195], 1, s[26:27]
	v_pk_mul_f32 v[208:209], v[186:187], v[154:155]
	v_pk_mul_f32 v[210:211], v[180:181], v[152:153]
	v_cvt_pk_bf16_f32 v196, v196, v197
	v_cvt_pk_bf16_f32 v197, v198, v199
	s_nop 0
	v_cvt_pk_bf16_f32 v198, v210, v211
	v_cvt_pk_bf16_f32 v199, v208, v209
	global_store_dwordx4 v[194:195], v[196:199], off
	v_mov_b32_e32 v195, v152
	v_mov_b32_e32 v152, v157
	v_mov_b32_e32 v157, v154
	v_mov_b32_e32 v154, v159
	v_mov_b32_e32 v194, v156
	v_pk_mul_f32 v[152:153], v[152:153], v[152:153]
	v_mov_b32_e32 v156, v158
	v_pk_mul_f32 v[154:155], v[154:155], v[154:155]
	v_pk_fma_f32 v[152:153], v[194:195], v[194:195], v[152:153]
	v_pk_fma_f32 v[154:155], v[156:157], v[156:157], v[154:155]
	s_nop 0
	v_pk_add_f32 v[152:153], v[152:153], v[154:155]
	s_nop 0
	v_add_f32_e32 v152, v152, v153
	v_add_f32_e32 v201, v201, v152
;     static __device__ __forceinline__ void run(const f32x4 (&acc)[2][2][4][2], const Unit& u, int wr, int wc, int fr, int fq, const float* xin, float* xout, const float* gate, float gs, const float* lazy_ssq, const float* lazy_g, ...
;     ...
;                 gv[n] = *(const f32x4*)(gate + (b * 9216u + col + 4 * n)) * gs;
;                 lg[n] = (f32x4){1.f, 1.f, 1.f, 1.f}; if (LAZY) lg[n] = *(const f32x4*)(lazy_g + col + 4 * n);
;                 wv[n] = (f32x4){0.f, 0.f, 0.f, 0.f}; w2[n] = (f32x4){1.f, 1.f, 1.f, 1.f};
;                 if (aout) { wv[n] = *(const f32x4*)(wg + col + 4 * n) * (*(const f32x4*)(wsc + (b * 9216u + col + 4 * n)) + 1.0f); if (WG2) { w2[n] = *(const f32x4*)(wg2 + col + 4 * n); wv[n] = wv[n] * w2[n]; } }
;             }
;             f32x4 xq[2][2][2];
;     ...
;             constexpr bool DEEP = !LAZY && !WG2;
;             if (DEEP) RES_LD(0, 0);
; #pragma unroll
;             for (int pp = 0; pp < 4; ++pp) {
;                 if (DEEP) { if (pp < 3) RES_LD((pp + 1) & 1, pp + 1); } else RES_LD(pp & 1, pp);
; #pragma unroll
;                 for (int j = 0; j < 2; ++j) { const int i_ = 2 * pp + j, ai = i_ >> 2, m = i_ & 3; const unsigned off = (row0 + ai * HALF + m * 16) * 1024u + col;
;                     const f32x4 xi0 = xq[pp & 1][j][0], xi1 = xq[pp & 1][j][1];
;                     f32x4 xo0 = gv[0] * acc[ai][bj][m][0], xo1 = gv[1] * acc[ai][bj][m][1];
;                     if (LAZY) { xo0 = xo0 + xi0 * lg[0] * rl[ai][m]; xo1 = xo1 + xi1 * lg[1] * rl[ai][m]; } else { xo0 = xo0 + xi0; xo1 = xo1 + xi1; }
;                     *(f32x4*)(xout + off) = xo0; *(f32x4*)(xout + off + 4) = xo1;
;                     if (aout) { const f32x4 a0 = xo0 * wv[0], a1 = xo1 * wv[1]; u32x4 w; w.x = cvt_pk_bf16(a0[0], a0[1]); w.y = cvt_pk_bf16(a0[2], a0[3]); w.z = cvt_pk_bf16(a1[0], a1[1]); w.w = cvt_pk_bf16(a1[2], a1[3]);
;                         *(u32x4*)(aout + off) = w;
;                         sq[ai][m] += ((xo0[0] * xo0[0] + xo0[1] * xo0[1]) + (xo0[2] * xo0[2] + xo0[3] * xo0[3])) + ((xo1[0] * xo1[0] + xo1[1] * xo1[1]) + (xo1[2] * xo1[2] + xo1[3] * xo1[3]));
;                         if (WG2) { const f32x4 b0 = xo0 * w2[0], b1 = xo1 * w2[1]; sqb[ai][m] += ((b0[0] * b0[0] + b0[1] * b0[1]) + (b0[2] * b0[2] + b0[3] * b0[3])) + ((b1[0] * b1[0] + b1[1] * b1[1]) + (b1[2] * b1[2] + b1[3] * b1[3])); } } }
.LBB0_517:
	s_nop 0
	v_add_u32_e32 v152, 0x24000, v176
	v_mov_b32_e32 v153, v177
	s_waitcnt vmcnt(0)
	v_pk_fma_f32 v[142:143], v[38:39], v[190:191], v[142:143]
	v_pk_fma_f32 v[140:141], v[36:37], v[192:193], v[140:141]
	v_pk_fma_f32 v[134:135], v[34:35], v[188:189], v[134:135]
	v_pk_fma_f32 v[132:133], v[32:33], v[174:175], v[132:133]
	v_lshl_add_u64 v[154:155], v[152:153], 2, s[28:29]
	s_and_b64 vcc, exec, s[8:9]
	global_store_dwordx4 v[154:155], v[140:143], off nt
	global_store_dwordx4 v[154:155], v[132:135], off offset:16 nt
	s_cbranch_vccnz .LBB0_519
	v_pk_mul_f32 v[156:157], v[184:185], v[142:143]
	v_pk_mul_f32 v[154:155], v[182:183], v[140:141]
	v_lshl_add_u64 v[152:153], v[152:153], 1, s[26:27]
	v_pk_mul_f32 v[158:159], v[186:187], v[134:135]
	v_pk_mul_f32 v[194:195], v[180:181], v[132:133]
	v_cvt_pk_bf16_f32 v154, v154, v155
	v_cvt_pk_bf16_f32 v155, v156, v157
	s_nop 0
	v_cvt_pk_bf16_f32 v156, v194, v195
	v_cvt_pk_bf16_f32 v157, v158, v159
	global_store_dwordx4 v[152:153], v[154:157], off
	v_mov_b32_e32 v153, v132
	v_mov_b32_e32 v132, v141
	v_mov_b32_e32 v141, v134
	v_mov_b32_e32 v134, v143
	v_mov_b32_e32 v152, v140
	v_pk_mul_f32 v[132:133], v[132:133], v[132:133]
	v_mov_b32_e32 v140, v142
	v_pk_mul_f32 v[134:135], v[134:135], v[134:135]
	v_pk_fma_f32 v[132:133], v[152:153], v[152:153], v[132:133]
	v_pk_fma_f32 v[134:135], v[140:141], v[140:141], v[134:135]
	s_nop 0
	v_pk_add_f32 v[132:133], v[132:133], v[134:135]
	s_nop 0
	v_add_f32_e32 v132, v132, v133
	v_add_f32_e32 v200, v200, v132
.LBB0_519:
	v_add_u32_e32 v152, 0x28000, v176
	v_mov_b32_e32 v153, v177
	s_waitcnt vmcnt(0)
	v_pk_fma_f32 v[134:135], v[22:23], v[190:191], v[150:151]
	v_pk_fma_f32 v[132:133], v[20:21], v[192:193], v[148:149]
	v_pk_fma_f32 v[142:143], v[18:19], v[188:189], v[146:147]
	v_pk_fma_f32 v[140:141], v[16:17], v[174:175], v[144:145]
	v_lshl_add_u64 v[144:145], v[152:153], 2, s[28:29]
	s_and_b64 vcc, exec, s[8:9]
	global_store_dwordx4 v[144:145], v[132:135], off nt
	global_store_dwordx4 v[144:145], v[140:143], off offset:16 nt
	s_cbranch_vccnz .LBB0_521
	v_pk_mul_f32 v[146:147], v[184:185], v[134:135]
	v_pk_mul_f32 v[144:145], v[182:183], v[132:133]
	v_pk_mul_f32 v[148:149], v[186:187], v[142:143]
	v_pk_mul_f32 v[150:151], v[180:181], v[140:141]
	v_cvt_pk_bf16_f32 v144, v144, v145
	v_cvt_pk_bf16_f32 v145, v146, v147
	s_nop 0
	v_cvt_pk_bf16_f32 v146, v150, v151
	v_cvt_pk_bf16_f32 v147, v148, v149
	v_lshl_add_u64 v[148:149], v[152:153], 1, s[26:27]
	global_store_dwordx4 v[148:149], v[144:147], off
	s_nop 1
	v_mov_b32_e32 v145, v140
	v_mov_b32_e32 v140, v133
	v_mov_b32_e32 v144, v132
	v_pk_mul_f32 v[132:133], v[140:141], v[140:141]
	v_mov_b32_e32 v141, v142
	v_mov_b32_e32 v142, v135
	v_mov_b32_e32 v140, v134
	v_pk_mul_f32 v[134:135], v[142:143], v[142:143]
	v_pk_fma_f32 v[132:133], v[144:145], v[144:145], v[132:133]
	v_pk_fma_f32 v[134:135], v[140:141], v[140:141], v[134:135]
	s_nop 0
	v_pk_add_f32 v[132:133], v[132:133], v[134:135]
	s_nop 0
	v_add_f32_e32 v132, v132, v133
	v_add_f32_e32 v206, v206, v132
.LBB0_521:
	v_add_u32_e32 v176, 0x2c000, v176
	s_waitcnt vmcnt(0)
	v_pk_fma_f32 v[134:135], v[6:7], v[190:191], v[138:139]
	v_pk_fma_f32 v[132:133], v[4:5], v[192:193], v[136:137]
	v_pk_fma_f32 v[130:131], v[2:3], v[188:189], v[130:131]
	v_pk_fma_f32 v[128:129], v[0:1], v[174:175], v[128:129]
	v_lshl_add_u64 v[136:137], v[176:177], 2, s[28:29]
	s_and_b64 vcc, exec, s[8:9]
	global_store_dwordx4 v[136:137], v[132:135], off nt
	global_store_dwordx4 v[136:137], v[128:131], off offset:16 nt
	s_cbranch_vccnz .LBB0_523
	v_pk_mul_f32 v[138:139], v[184:185], v[134:135]
	v_pk_mul_f32 v[136:137], v[182:183], v[132:133]
	v_pk_mul_f32 v[140:141], v[186:187], v[130:131]
	v_pk_mul_f32 v[142:143], v[180:181], v[128:129]
	v_cvt_pk_bf16_f32 v136, v136, v137
	v_cvt_pk_bf16_f32 v137, v138, v139
	s_nop 0
	v_cvt_pk_bf16_f32 v138, v142, v143
	v_cvt_pk_bf16_f32 v139, v140, v141
	v_lshl_add_u64 v[140:141], v[176:177], 1, s[26:27]
	global_store_dwordx4 v[140:141], v[136:139], off
	s_nop 1
	v_mov_b32_e32 v137, v128
	v_mov_b32_e32 v128, v133
	v_mov_b32_e32 v133, v130
	v_mov_b32_e32 v130, v135
	v_mov_b32_e32 v136, v132
	v_pk_mul_f32 v[128:129], v[128:129], v[128:129]
	v_mov_b32_e32 v132, v134
	v_pk_mul_f32 v[130:131], v[130:131], v[130:131]
	v_pk_fma_f32 v[128:129], v[136:137], v[136:137], v[128:129]
	v_pk_fma_f32 v[130:131], v[132:133], v[132:133], v[130:131]
	s_nop 0
	v_pk_add_f32 v[128:129], v[128:129], v[130:131]
	s_nop 0
	v_add_f32_e32 v128, v128, v129
	v_add_f32_e32 v202, v202, v128
